# v5 + deleted the 36 provably redundant s_waitcnt lgkmcnt(0) that follow s_barrier/s_setprio in the GEMM K-loop MFMA phases
# speedup vs baseline: 1.0094x; 1.0094x over previous
; #define PG8_STAGE(bufoff, gbase, voff) do { _Pragma("unroll") for (int _i = 0; _i < 2; ++_i) \
;         __builtin_amdgcn_global_load_lds((const unsigned*)((const char*)(gbase) + (voff)[_i]), (LAS unsigned*)(lds + (bufoff) + ldsw + _i * 8192), 16, 0, 0); } while (0)
; #define PG8_LDA(dst, b, h) do { _Pragma("unroll") for (int m = 0; m < 4; ++m) _Pragma("unroll") for (int k = 0; k < 2; ++k) dst[m][k] = *(const LAS bf16x8*)(lds + PG8_SA(b, h) + aoff + m * 2048 + k * 1024); } while (0)
; #define PG8_LDB(dst, b, h) do { _Pragma("unroll") for (int n = 0; n < 2; ++n) _Pragma("unroll") for (int k = 0; k < 2; ++k) dst[n][k] = *(const LAS bf16x8*)(lds + PG8_SB(b, h) + boff + n * 2048 + k * 1024); } while (0)
; #define PG8_WAIT_V(n) asm volatile("s_waitcnt vmcnt(" #n ")" ::: "memory")
; template <class Epi, class Sched, bool SP2 = PG8_SP2>
; __device__ __forceinline__ void gemm_phase(LAS unsigned char* lds, const Gemm g, const Sched& S, const Epi& E) {
;     ...
;         for (int t = 0; t < nt; t += 2) {
;             const bool last = (t == nt - 2);
;             const char* a1 = cA + (size_t)(t + 1) * kstep;
;             const char* a2 = last ? nA : cA + (size_t)(t + 2) * kstep; const char* b2 = last ? nB : cB + (size_t)(t + 2) * kstep;
;             const char* a3 = a2 + kstep; const char* b3 = b2 + kstep;
;             if constexpr (SP2) {
;             PG8_LDB(B0, 0, 0); PG8_LDB(B1, 0, 1); PG8_SCHED; PG8_LDA(At, 0, 0); PG8_STAGE(PG8_SA(1, 1), a1 + hstepA, voffA);
;             PG8_WAIT_V(8); PG8_WAIT_L(0); PG8_BAR; PG8_MMA(0, 0, At, B0); PG8_MMA(0, 1, At, B1); PG8_BAR; PG8_SCHED;
;             PG8_LDA(At, 0, 1); PG8_STAGE(PG8_SB(0, 0), b2, voffB); PG8_STAGE(PG8_SB(0, 1), b2 + hstepB, voffB); PG8_STAGE(PG8_SA(0, 0), a2, voffA);
;             PG8_WAIT_V(8); PG8_WAIT_L(0); PG8_BAR; PG8_MMA(1, 0, At, B0); PG8_MMA(1, 1, At, B1); PG8_BAR; PG8_SCHED;
;             PG8_LDB(B0, 1, 0); PG8_LDB(B1, 1, 1); PG8_SCHED; PG8_LDA(At, 1, 0); PG8_STAGE(PG8_SA(0, 1), a2 + hstepA, voffA);
;             PG8_WAIT_V(8); PG8_WAIT_L(0); PG8_BAR; PG8_MMA(0, 0, At, B0); PG8_MMA(0, 1, At, B1); PG8_BAR; PG8_SCHED;
;             PG8_LDA(At, 1, 1); PG8_STAGE(PG8_SB(1, 0), b3, voffB); PG8_STAGE(PG8_SB(1, 1), b3 + hstepB, voffB); PG8_STAGE(PG8_SA(1, 0), a3, voffA);
;             PG8_WAIT_V(8); PG8_WAIT_L(0); PG8_BAR; PG8_MMA(1, 0, At, B0); PG8_MMA(1, 1, At, B1); PG8_BAR; PG8_SCHED;
.LBB0_153:
	ds_read_b128 v[144:147], v152
	ds_read_b128 v[156:159], v152 offset:1024
	ds_read_b128 v[160:163], v152 offset:2048
	ds_read_b128 v[164:167], v152 offset:3072
	ds_read_b128 v[168:171], v153
	ds_read_b128 v[172:175], v153 offset:1024
	ds_read_b128 v[176:179], v153 offset:2048
	ds_read_b128 v[180:183], v153 offset:3072
	s_add_u32 s3, s0, 0xfff80080
	s_addc_u32 s44, s1, -1
	s_cmp_eq_u32 s67, 28
	s_cselect_b32 s47, s2, s44
	s_cselect_b32 s46, s9, s3
	s_cselect_b32 s45, s35, s66
	s_cselect_b32 s44, s37, s43
	s_add_i32 m0, s53, 0xc000
	ds_read_b128 v[184:187], v154
	ds_read_b128 v[188:191], v154 offset:1024
	ds_read_b128 v[192:195], v154 offset:2048
	ds_read_b128 v[196:199], v154 offset:3072
	ds_read_b128 v[200:203], v154 offset:4096
	ds_read_b128 v[204:207], v154 offset:5120
	ds_read_b128 v[208:211], v154 offset:6144
	ds_read_b128 v[212:215], v154 offset:7168
	global_load_lds_dwordx4 v136, s[0:1]
	s_add_i32 m0, s53, 0xe000
	s_nop 0
	global_load_lds_dwordx4 v138, s[0:1]
	s_waitcnt vmcnt(8)
	s_waitcnt lgkmcnt(0)
	s_barrier
	s_setprio 1
	v_mfma_f32_16x16x32_bf16 v[124:127], v[144:147], v[184:187], v[124:127]
	v_mfma_f32_16x16x32_bf16 v[120:123], v[160:163], v[184:187], v[120:123]
	v_mfma_f32_16x16x32_bf16 v[108:111], v[144:147], v[192:195], v[108:111]
	v_mfma_f32_16x16x32_bf16 v[104:107], v[160:163], v[192:195], v[104:107]
	v_mfma_f32_16x16x32_bf16 v[92:95], v[144:147], v[200:203], v[92:95]
	v_mfma_f32_16x16x32_bf16 v[88:91], v[160:163], v[200:203], v[88:91]
	v_mfma_f32_16x16x32_bf16 v[76:79], v[144:147], v[208:211], v[76:79]
	v_mfma_f32_16x16x32_bf16 v[72:75], v[160:163], v[208:211], v[72:75]
	v_mfma_f32_16x16x32_bf16 v[124:127], v[156:159], v[188:191], v[124:127]
	v_mfma_f32_16x16x32_bf16 v[120:123], v[164:167], v[188:191], v[120:123]
	v_mfma_f32_16x16x32_bf16 v[108:111], v[156:159], v[196:199], v[108:111]
	v_mfma_f32_16x16x32_bf16 v[104:107], v[164:167], v[196:199], v[104:107]
	v_mfma_f32_16x16x32_bf16 v[92:95], v[156:159], v[204:207], v[92:95]
	v_mfma_f32_16x16x32_bf16 v[88:91], v[164:167], v[204:207], v[88:91]
	v_mfma_f32_16x16x32_bf16 v[76:79], v[156:159], v[212:215], v[76:79]
	v_mfma_f32_16x16x32_bf16 v[72:75], v[164:167], v[212:215], v[72:75]
	s_setprio 0
	s_setprio 1
	v_mfma_f32_16x16x32_bf16 v[116:119], v[168:171], v[184:187], v[116:119]
	v_mfma_f32_16x16x32_bf16 v[112:115], v[176:179], v[184:187], v[112:115]
	v_mfma_f32_16x16x32_bf16 v[100:103], v[168:171], v[192:195], v[100:103]
	v_mfma_f32_16x16x32_bf16 v[96:99], v[176:179], v[192:195], v[96:99]
	v_mfma_f32_16x16x32_bf16 v[84:87], v[168:171], v[200:203], v[84:87]
	v_mfma_f32_16x16x32_bf16 v[80:83], v[176:179], v[200:203], v[80:83]
	v_mfma_f32_16x16x32_bf16 v[68:71], v[168:171], v[208:211], v[68:71]
	v_mfma_f32_16x16x32_bf16 v[64:67], v[176:179], v[208:211], v[64:67]
	v_mfma_f32_16x16x32_bf16 v[116:119], v[172:175], v[188:191], v[116:119]
	v_mfma_f32_16x16x32_bf16 v[112:115], v[180:183], v[188:191], v[112:115]
	v_mfma_f32_16x16x32_bf16 v[100:103], v[172:175], v[196:199], v[100:103]
	v_mfma_f32_16x16x32_bf16 v[96:99], v[180:183], v[196:199], v[96:99]
	v_mfma_f32_16x16x32_bf16 v[84:87], v[172:175], v[204:207], v[84:87]
	v_mfma_f32_16x16x32_bf16 v[80:83], v[180:183], v[204:207], v[80:83]
	v_mfma_f32_16x16x32_bf16 v[68:71], v[172:175], v[212:215], v[68:71]
	v_mfma_f32_16x16x32_bf16 v[64:67], v[180:183], v[212:215], v[64:67]
	s_setprio 0
	s_barrier
	s_add_i32 s3, s62, s52
	s_add_u32 s98, s44, s22
	s_addc_u32 s99, s45, s23
	s_mov_b32 m0, s3
	ds_read_b128 v[184:187], v154 offset:16384
	ds_read_b128 v[188:191], v154 offset:17408
	ds_read_b128 v[192:195], v154 offset:18432
	ds_read_b128 v[196:199], v154 offset:19456
	ds_read_b128 v[200:203], v154 offset:20480
	ds_read_b128 v[204:207], v154 offset:21504
	ds_read_b128 v[208:211], v154 offset:22528
	ds_read_b128 v[212:215], v154 offset:23552
	global_load_lds_dwordx4 v130, s[44:45]
	s_add_i32 m0, s3, 0x2000
	s_add_u32 s68, s44, 0x80000
	s_addc_u32 s69, s45, 0
	s_add_i32 s3, s63, s52
	global_load_lds_dwordx4 v134, s[44:45]
	s_mov_b32 m0, s3
	s_nop 0
	global_load_lds_dwordx4 v130, s[68:69]
	s_add_i32 m0, s3, 0x2000
	s_nop 0
	global_load_lds_dwordx4 v134, s[68:69]
	s_add_u32 s100, s46, s22
	s_addc_u32 s101, s47, s23
	s_mov_b32 m0, s53
	s_nop 0
	global_load_lds_dwordx4 v128, s[46:47]
	s_mov_b32 m0, s54
	s_nop 0
	global_load_lds_dwordx4 v132, s[46:47]
	s_waitcnt vmcnt(8)
	s_waitcnt lgkmcnt(0)
	s_barrier
	s_setprio 1
	v_mfma_f32_16x16x32_bf16 v[60:63], v[144:147], v[184:187], v[60:63]
	v_mfma_f32_16x16x32_bf16 v[56:59], v[160:163], v[184:187], v[56:59]
	v_mfma_f32_16x16x32_bf16 v[44:47], v[144:147], v[192:195], v[44:47]
	v_mfma_f32_16x16x32_bf16 v[40:43], v[160:163], v[192:195], v[40:43]
	v_mfma_f32_16x16x32_bf16 v[28:31], v[144:147], v[200:203], v[28:31]
	v_mfma_f32_16x16x32_bf16 v[24:27], v[160:163], v[200:203], v[24:27]
	v_mfma_f32_16x16x32_bf16 v[12:15], v[144:147], v[208:211], v[12:15]
	v_mfma_f32_16x16x32_bf16 v[8:11], v[160:163], v[208:211], v[8:11]
	v_mfma_f32_16x16x32_bf16 v[60:63], v[156:159], v[188:191], v[60:63]
	v_mfma_f32_16x16x32_bf16 v[56:59], v[164:167], v[188:191], v[56:59]
	v_mfma_f32_16x16x32_bf16 v[44:47], v[156:159], v[196:199], v[44:47]
	v_mfma_f32_16x16x32_bf16 v[40:43], v[164:167], v[196:199], v[40:43]
	v_mfma_f32_16x16x32_bf16 v[28:31], v[156:159], v[204:207], v[28:31]
	v_mfma_f32_16x16x32_bf16 v[24:27], v[164:167], v[204:207], v[24:27]
	v_mfma_f32_16x16x32_bf16 v[12:15], v[156:159], v[212:215], v[12:15]
	v_mfma_f32_16x16x32_bf16 v[8:11], v[164:167], v[212:215], v[8:11]
	s_setprio 0
	s_setprio 1
	v_mfma_f32_16x16x32_bf16 v[52:55], v[168:171], v[184:187], v[52:55]
	v_mfma_f32_16x16x32_bf16 v[48:51], v[176:179], v[184:187], v[48:51]
	v_mfma_f32_16x16x32_bf16 v[36:39], v[168:171], v[192:195], v[36:39]
	v_mfma_f32_16x16x32_bf16 v[32:35], v[176:179], v[192:195], v[32:35]
	v_mfma_f32_16x16x32_bf16 v[20:23], v[168:171], v[200:203], v[20:23]
	v_mfma_f32_16x16x32_bf16 v[16:19], v[176:179], v[200:203], v[16:19]
	v_mfma_f32_16x16x32_bf16 v[4:7], v[168:171], v[208:211], v[4:7]
	v_mfma_f32_16x16x32_bf16 v[0:3], v[176:179], v[208:211], v[0:3]
	v_mfma_f32_16x16x32_bf16 v[52:55], v[172:175], v[188:191], v[52:55]
	v_mfma_f32_16x16x32_bf16 v[48:51], v[180:183], v[188:191], v[48:51]
	v_mfma_f32_16x16x32_bf16 v[36:39], v[172:175], v[196:199], v[36:39]
	v_mfma_f32_16x16x32_bf16 v[32:35], v[180:183], v[196:199], v[32:35]
	v_mfma_f32_16x16x32_bf16 v[20:23], v[172:175], v[204:207], v[20:23]
	v_mfma_f32_16x16x32_bf16 v[16:19], v[180:183], v[204:207], v[16:19]
	v_mfma_f32_16x16x32_bf16 v[4:7], v[172:175], v[212:215], v[4:7]
	v_mfma_f32_16x16x32_bf16 v[0:3], v[180:183], v[212:215], v[0:3]
	s_setprio 0
	s_barrier
; #define PG8_STAGE(bufoff, gbase, voff) do { _Pragma("unroll") for (int _i = 0; _i < 2; ++_i) \
;         __builtin_amdgcn_global_load_lds((const unsigned*)((const char*)(gbase) + (voff)[_i]), (LAS unsigned*)(lds + (bufoff) + ldsw + _i * 8192), 16, 0, 0); } while (0)
; #define PG8_LDA(dst, b, h) do { _Pragma("unroll") for (int m = 0; m < 4; ++m) _Pragma("unroll") for (int k = 0; k < 2; ++k) dst[m][k] = *(const LAS bf16x8*)(lds + PG8_SA(b, h) + aoff + m * 2048 + k * 1024); } while (0)
; #define PG8_LDB(dst, b, h) do { _Pragma("unroll") for (int n = 0; n < 2; ++n) _Pragma("unroll") for (int k = 0; k < 2; ++k) dst[n][k] = *(const LAS bf16x8*)(lds + PG8_SB(b, h) + boff + n * 2048 + k * 1024); } while (0)
; #define PG8_WAIT_V(n) asm volatile("s_waitcnt vmcnt(" #n ")" ::: "memory")
; template <class Epi, class Sched, bool SP2 = PG8_SP2>
; __device__ __forceinline__ void gemm_phase(LAS unsigned char* lds, const Gemm g, const Sched& S, const Epi& E) {
;     ...
;         for (int t = 0; t < nt; t += 2) {
;             const bool last = (t == nt - 2);
;             const char* a1 = cA + (size_t)(t + 1) * kstep;
;             const char* a2 = last ? nA : cA + (size_t)(t + 2) * kstep; const char* b2 = last ? nB : cB + (size_t)(t + 2) * kstep;
;             const char* a3 = a2 + kstep; const char* b3 = b2 + kstep;
;             if constexpr (SP2) {
;             PG8_LDB(B0, 0, 0); PG8_LDB(B1, 0, 1); PG8_SCHED; PG8_LDA(At, 0, 0); PG8_STAGE(PG8_SA(1, 1), a1 + hstepA, voffA);
;             PG8_WAIT_V(8); PG8_WAIT_L(0); PG8_BAR; PG8_MMA(0, 0, At, B0); PG8_MMA(0, 1, At, B1); PG8_BAR; PG8_SCHED;
;             PG8_LDA(At, 0, 1); PG8_STAGE(PG8_SB(0, 0), b2, voffB); PG8_STAGE(PG8_SB(0, 1), b2 + hstepB, voffB); PG8_STAGE(PG8_SA(0, 0), a2, voffA);
;             PG8_WAIT_V(8); PG8_WAIT_L(0); PG8_BAR; PG8_MMA(1, 0, At, B0); PG8_MMA(1, 1, At, B1); PG8_BAR; PG8_SCHED;
;             PG8_LDB(B0, 1, 0); PG8_LDB(B1, 1, 1); PG8_SCHED; PG8_LDA(At, 1, 0); PG8_STAGE(PG8_SA(0, 1), a2 + hstepA, voffA);
;             PG8_WAIT_V(8); PG8_WAIT_L(0); PG8_BAR; PG8_MMA(0, 0, At, B0); PG8_MMA(0, 1, At, B1); PG8_BAR; PG8_SCHED;
;             PG8_LDA(At, 1, 1); PG8_STAGE(PG8_SB(1, 0), b3, voffB); PG8_STAGE(PG8_SB(1, 1), b3 + hstepB, voffB); PG8_STAGE(PG8_SA(1, 0), a3, voffA);
;             PG8_WAIT_V(8); PG8_WAIT_L(0); PG8_BAR; PG8_MMA(1, 0, At, B0); PG8_MMA(1, 1, At, B1); PG8_BAR; PG8_SCHED;
	s_add_i32 s3, 0, 0x18000
	s_add_i32 s68, 0, 0x1c000
	v_add_u32_e32 v164, s3, v150
	v_add_u32_e32 v180, s68, v150
	ds_read_b128 v[144:147], v164
	ds_read_b128 v[156:159], v164 offset:1024
	ds_read_b128 v[160:163], v164 offset:2048
	ds_read_b128 v[164:167], v164 offset:3072
	ds_read_b128 v[168:171], v180
	ds_read_b128 v[172:175], v180 offset:1024
	ds_read_b128 v[176:179], v180 offset:2048
	ds_read_b128 v[180:183], v180 offset:3072
	s_add_u32 s46, s46, 0x80000
	s_addc_u32 s47, s47, 0
	s_mov_b32 m0, s55
	ds_read_b128 v[184:187], v154 offset:32768
	ds_read_b128 v[188:191], v154 offset:33792
	ds_read_b128 v[192:195], v154 offset:34816
	ds_read_b128 v[196:199], v154 offset:35840
	ds_read_b128 v[200:203], v154 offset:36864
	ds_read_b128 v[204:207], v154 offset:37888
	ds_read_b128 v[208:211], v154 offset:38912
	ds_read_b128 v[212:215], v154 offset:39936
	global_load_lds_dwordx4 v128, s[46:47]
	s_mov_b32 m0, s56
	s_nop 0
	global_load_lds_dwordx4 v132, s[46:47]
	s_waitcnt vmcnt(8)
	s_waitcnt lgkmcnt(0)
	s_barrier
	s_setprio 1
	v_mfma_f32_16x16x32_bf16 v[124:127], v[144:147], v[184:187], v[124:127]
	v_mfma_f32_16x16x32_bf16 v[120:123], v[160:163], v[184:187], v[120:123]
	v_mfma_f32_16x16x32_bf16 v[108:111], v[144:147], v[192:195], v[108:111]
	v_mfma_f32_16x16x32_bf16 v[104:107], v[160:163], v[192:195], v[104:107]
	v_mfma_f32_16x16x32_bf16 v[92:95], v[144:147], v[200:203], v[92:95]
	v_mfma_f32_16x16x32_bf16 v[88:91], v[160:163], v[200:203], v[88:91]
	v_mfma_f32_16x16x32_bf16 v[76:79], v[144:147], v[208:211], v[76:79]
	v_mfma_f32_16x16x32_bf16 v[72:75], v[160:163], v[208:211], v[72:75]
	v_mfma_f32_16x16x32_bf16 v[124:127], v[156:159], v[188:191], v[124:127]
	v_mfma_f32_16x16x32_bf16 v[120:123], v[164:167], v[188:191], v[120:123]
	v_mfma_f32_16x16x32_bf16 v[108:111], v[156:159], v[196:199], v[108:111]
	v_mfma_f32_16x16x32_bf16 v[104:107], v[164:167], v[196:199], v[104:107]
	v_mfma_f32_16x16x32_bf16 v[92:95], v[156:159], v[204:207], v[92:95]
	v_mfma_f32_16x16x32_bf16 v[88:91], v[164:167], v[204:207], v[88:91]
	v_mfma_f32_16x16x32_bf16 v[76:79], v[156:159], v[212:215], v[76:79]
	v_mfma_f32_16x16x32_bf16 v[72:75], v[164:167], v[212:215], v[72:75]
	s_setprio 0
	s_setprio 1
	v_mfma_f32_16x16x32_bf16 v[116:119], v[168:171], v[184:187], v[116:119]
	v_mfma_f32_16x16x32_bf16 v[112:115], v[176:179], v[184:187], v[112:115]
	v_mfma_f32_16x16x32_bf16 v[100:103], v[168:171], v[192:195], v[100:103]
	v_mfma_f32_16x16x32_bf16 v[96:99], v[176:179], v[192:195], v[96:99]
	v_mfma_f32_16x16x32_bf16 v[84:87], v[168:171], v[200:203], v[84:87]
	v_mfma_f32_16x16x32_bf16 v[80:83], v[176:179], v[200:203], v[80:83]
	v_mfma_f32_16x16x32_bf16 v[68:71], v[168:171], v[208:211], v[68:71]
	v_mfma_f32_16x16x32_bf16 v[64:67], v[176:179], v[208:211], v[64:67]
	v_mfma_f32_16x16x32_bf16 v[116:119], v[172:175], v[188:191], v[116:119]
	v_mfma_f32_16x16x32_bf16 v[112:115], v[180:183], v[188:191], v[112:115]
	v_mfma_f32_16x16x32_bf16 v[100:103], v[172:175], v[196:199], v[100:103]
	v_mfma_f32_16x16x32_bf16 v[96:99], v[180:183], v[196:199], v[96:99]
	v_mfma_f32_16x16x32_bf16 v[84:87], v[172:175], v[204:207], v[84:87]
	v_mfma_f32_16x16x32_bf16 v[80:83], v[180:183], v[204:207], v[80:83]
	v_mfma_f32_16x16x32_bf16 v[68:71], v[172:175], v[212:215], v[68:71]
	v_mfma_f32_16x16x32_bf16 v[64:67], v[180:183], v[212:215], v[64:67]
	s_setprio 0
	s_barrier
	s_add_i32 s3, s3, s52
	s_mov_b32 m0, s3
	ds_read_b128 v[184:187], v154 offset:49152
	ds_read_b128 v[188:191], v154 offset:50176
	ds_read_b128 v[192:195], v154 offset:51200
	ds_read_b128 v[196:199], v154 offset:52224
	ds_read_b128 v[200:203], v154 offset:53248
	ds_read_b128 v[204:207], v154 offset:54272
	ds_read_b128 v[208:211], v154 offset:55296
	ds_read_b128 v[212:215], v154 offset:56320
	global_load_lds_dwordx4 v130, s[98:99]
	s_add_i32 m0, s3, 0x2000
	s_add_u32 s44, s44, 0x80080
	s_addc_u32 s45, s45, 0
	s_add_i32 s3, s68, s52
	global_load_lds_dwordx4 v134, s[98:99]
	s_mov_b32 m0, s3
	s_nop 0
	global_load_lds_dwordx4 v130, s[44:45]
	s_add_i32 m0, s3, 0x2000
	s_nop 0
	global_load_lds_dwordx4 v134, s[44:45]
	s_mov_b32 m0, s58
	s_nop 0
	global_load_lds_dwordx4 v128, s[100:101]
	s_mov_b32 m0, s59
	s_nop 0
	global_load_lds_dwordx4 v132, s[100:101]
	s_waitcnt vmcnt(8)
	s_waitcnt lgkmcnt(0)
	s_barrier
	s_setprio 1
	v_mfma_f32_16x16x32_bf16 v[60:63], v[144:147], v[184:187], v[60:63]
	v_mfma_f32_16x16x32_bf16 v[56:59], v[160:163], v[184:187], v[56:59]
	v_mfma_f32_16x16x32_bf16 v[44:47], v[144:147], v[192:195], v[44:47]
	v_mfma_f32_16x16x32_bf16 v[40:43], v[160:163], v[192:195], v[40:43]
	v_mfma_f32_16x16x32_bf16 v[28:31], v[144:147], v[200:203], v[28:31]
	v_mfma_f32_16x16x32_bf16 v[24:27], v[160:163], v[200:203], v[24:27]
	v_mfma_f32_16x16x32_bf16 v[12:15], v[144:147], v[208:211], v[12:15]
	v_mfma_f32_16x16x32_bf16 v[8:11], v[160:163], v[208:211], v[8:11]
	v_mfma_f32_16x16x32_bf16 v[60:63], v[156:159], v[188:191], v[60:63]
	v_mfma_f32_16x16x32_bf16 v[56:59], v[164:167], v[188:191], v[56:59]
	v_mfma_f32_16x16x32_bf16 v[44:47], v[156:159], v[196:199], v[44:47]
	v_mfma_f32_16x16x32_bf16 v[40:43], v[164:167], v[196:199], v[40:43]
	v_mfma_f32_16x16x32_bf16 v[28:31], v[156:159], v[204:207], v[28:31]
	v_mfma_f32_16x16x32_bf16 v[24:27], v[164:167], v[204:207], v[24:27]
	v_mfma_f32_16x16x32_bf16 v[12:15], v[156:159], v[212:215], v[12:15]
	v_mfma_f32_16x16x32_bf16 v[8:11], v[164:167], v[212:215], v[8:11]
	s_setprio 0
	s_setprio 1
	v_mfma_f32_16x16x32_bf16 v[52:55], v[168:171], v[184:187], v[52:55]
	v_mfma_f32_16x16x32_bf16 v[48:51], v[176:179], v[184:187], v[48:51]
	v_mfma_f32_16x16x32_bf16 v[36:39], v[168:171], v[192:195], v[36:39]
	v_mfma_f32_16x16x32_bf16 v[32:35], v[176:179], v[192:195], v[32:35]
	v_mfma_f32_16x16x32_bf16 v[20:23], v[168:171], v[200:203], v[20:23]
	v_mfma_f32_16x16x32_bf16 v[16:19], v[176:179], v[200:203], v[16:19]
	v_mfma_f32_16x16x32_bf16 v[4:7], v[168:171], v[208:211], v[4:7]
	v_mfma_f32_16x16x32_bf16 v[0:3], v[176:179], v[208:211], v[0:3]
	v_mfma_f32_16x16x32_bf16 v[52:55], v[172:175], v[188:191], v[52:55]
	v_mfma_f32_16x16x32_bf16 v[48:51], v[180:183], v[188:191], v[48:51]
	v_mfma_f32_16x16x32_bf16 v[36:39], v[172:175], v[196:199], v[36:39]
	v_mfma_f32_16x16x32_bf16 v[32:35], v[180:183], v[196:199], v[32:35]
	v_mfma_f32_16x16x32_bf16 v[20:23], v[172:175], v[204:207], v[20:23]
	v_mfma_f32_16x16x32_bf16 v[16:19], v[180:183], v[204:207], v[16:19]
	v_mfma_f32_16x16x32_bf16 v[4:7], v[172:175], v[212:215], v[4:7]
	v_mfma_f32_16x16x32_bf16 v[0:3], v[180:183], v[212:215], v[0:3]
	s_setprio 0
	s_barrier
	s_add_i32 s67, s67, 2
	s_add_u32 s0, s0, 0x100
	s_addc_u32 s1, s1, 0
	s_add_u32 s43, s43, 0x100
	s_addc_u32 s66, s66, 0
	s_cmp_gt_u32 s67, 29
	s_cbranch_scc0 .LBB0_153
	s_and_b64 vcc, exec, s[24:25]
	s_cbranch_vccz .LBB0_156
	s_barrier

; #define PG8_STAGE(bufoff, gbase, voff) do { _Pragma("unroll") for (int _i = 0; _i < 2; ++_i) \
;         __builtin_amdgcn_global_load_lds((const unsigned*)((const char*)(gbase) + (voff)[_i]), (LAS unsigned*)(lds + (bufoff) + ldsw + _i * 8192), 16, 0, 0); } while (0)
; #define PG8_LDA(dst, b, h) do { _Pragma("unroll") for (int m = 0; m < 4; ++m) _Pragma("unroll") for (int k = 0; k < 2; ++k) dst[m][k] = *(const LAS bf16x8*)(lds + PG8_SA(b, h) + aoff + m * 2048 + k * 1024); } while (0)
; #define PG8_LDB(dst, b, h) do { _Pragma("unroll") for (int n = 0; n < 2; ++n) _Pragma("unroll") for (int k = 0; k < 2; ++k) dst[n][k] = *(const LAS bf16x8*)(lds + PG8_SB(b, h) + boff + n * 2048 + k * 1024); } while (0)
; #define PG8_WAIT_V(n) asm volatile("s_waitcnt vmcnt(" #n ")" ::: "memory")
; template <class Epi, class Sched, bool SP2 = PG8_SP2>
; __device__ __forceinline__ void gemm_phase(LAS unsigned char* lds, const Gemm g, const Sched& S, const Epi& E) {
;     ...
;         for (int t = 0; t < nt; t += 2) {
;             const bool last = (t == nt - 2);
;             const char* a1 = cA + (size_t)(t + 1) * kstep;
;             const char* a2 = last ? nA : cA + (size_t)(t + 2) * kstep; const char* b2 = last ? nB : cB + (size_t)(t + 2) * kstep;
;             const char* a3 = a2 + kstep; const char* b3 = b2 + kstep;
;             if constexpr (SP2) {
;             PG8_LDB(B0, 0, 0); PG8_LDB(B1, 0, 1); PG8_SCHED; PG8_LDA(At, 0, 0); PG8_STAGE(PG8_SA(1, 1), a1 + hstepA, voffA);
;             PG8_WAIT_V(8); PG8_WAIT_L(0); PG8_BAR; PG8_MMA(0, 0, At, B0); PG8_MMA(0, 1, At, B1); PG8_BAR; PG8_SCHED;
;             PG8_LDA(At, 0, 1); PG8_STAGE(PG8_SB(0, 0), b2, voffB); PG8_STAGE(PG8_SB(0, 1), b2 + hstepB, voffB); PG8_STAGE(PG8_SA(0, 0), a2, voffA);
;             PG8_WAIT_V(8); PG8_WAIT_L(0); PG8_BAR; PG8_MMA(1, 0, At, B0); PG8_MMA(1, 1, At, B1); PG8_BAR; PG8_SCHED;
;             PG8_LDB(B0, 1, 0); PG8_LDB(B1, 1, 1); PG8_SCHED; PG8_LDA(At, 1, 0); PG8_STAGE(PG8_SA(0, 1), a2 + hstepA, voffA);
;             PG8_WAIT_V(8); PG8_WAIT_L(0); PG8_BAR; PG8_MMA(0, 0, At, B0); PG8_MMA(0, 1, At, B1); PG8_BAR; PG8_SCHED;
;             PG8_LDA(At, 1, 1); PG8_STAGE(PG8_SB(1, 0), b3, voffB); PG8_STAGE(PG8_SB(1, 1), b3 + hstepB, voffB); PG8_STAGE(PG8_SA(1, 0), a3, voffA);
;             PG8_WAIT_V(8); PG8_WAIT_L(0); PG8_BAR; PG8_MMA(1, 0, At, B0); PG8_MMA(1, 1, At, B1); PG8_BAR; PG8_SCHED;
.LBB0_262:
	ds_read_b128 v[150:153], v142
	ds_read_b128 v[154:157], v142 offset:1024
	ds_read_b128 v[158:161], v142 offset:2048
	ds_read_b128 v[162:165], v142 offset:3072
	ds_read_b128 v[166:169], v143
	ds_read_b128 v[170:173], v143 offset:1024
	ds_read_b128 v[174:177], v143 offset:2048
	ds_read_b128 v[178:181], v143 offset:3072
	s_add_u32 s3, s0, 0xfa380080
	s_addc_u32 s10, s1, -1
	s_cmp_lg_u32 s2, 28
	s_cselect_b32 s3, s3, 0
	s_cselect_b32 s11, s10, 0
	s_add_u32 s12, s6, s3
	s_addc_u32 s13, s7, s11
	s_add_u32 s10, s4, s3
	s_addc_u32 s11, s5, s11
	s_mov_b32 m0, s24
	v_lshl_add_u64 v[214:215], v[136:137], 0, s[0:1]
	ds_read_b128 v[182:185], v144
	ds_read_b128 v[186:189], v144 offset:1024
	ds_read_b128 v[190:193], v144 offset:2048
	ds_read_b128 v[194:197], v144 offset:3072
	ds_read_b128 v[198:201], v144 offset:4096
	ds_read_b128 v[202:205], v144 offset:5120
	ds_read_b128 v[206:209], v144 offset:6144
	ds_read_b128 v[210:213], v144 offset:7168
	global_load_lds_dwordx4 v[214:215], off
	v_lshl_add_u64 v[214:215], v[138:139], 0, s[0:1]
	s_mov_b32 m0, s25
	s_nop 0
	global_load_lds_dwordx4 v[214:215], off
	s_waitcnt vmcnt(8)
	s_waitcnt lgkmcnt(0)
	s_barrier
	s_setprio 1
	v_mfma_f32_16x16x32_bf16 v[124:127], v[150:153], v[182:185], v[124:127]
	v_mfma_f32_16x16x32_bf16 v[120:123], v[158:161], v[182:185], v[120:123]
	v_mfma_f32_16x16x32_bf16 v[116:119], v[150:153], v[190:193], v[116:119]
	v_mfma_f32_16x16x32_bf16 v[108:111], v[158:161], v[190:193], v[108:111]
	v_mfma_f32_16x16x32_bf16 v[100:103], v[150:153], v[198:201], v[100:103]
	v_mfma_f32_16x16x32_bf16 v[92:95], v[158:161], v[198:201], v[92:95]
	v_mfma_f32_16x16x32_bf16 v[84:87], v[150:153], v[206:209], v[84:87]
	v_mfma_f32_16x16x32_bf16 v[76:79], v[158:161], v[206:209], v[76:79]
	v_mfma_f32_16x16x32_bf16 v[124:127], v[154:157], v[186:189], v[124:127]
	v_mfma_f32_16x16x32_bf16 v[120:123], v[162:165], v[186:189], v[120:123]
	v_mfma_f32_16x16x32_bf16 v[116:119], v[154:157], v[194:197], v[116:119]
	v_mfma_f32_16x16x32_bf16 v[108:111], v[162:165], v[194:197], v[108:111]
	v_mfma_f32_16x16x32_bf16 v[100:103], v[154:157], v[202:205], v[100:103]
	v_mfma_f32_16x16x32_bf16 v[92:95], v[162:165], v[202:205], v[92:95]
	v_mfma_f32_16x16x32_bf16 v[84:87], v[154:157], v[210:213], v[84:87]
	v_mfma_f32_16x16x32_bf16 v[76:79], v[162:165], v[210:213], v[76:79]
	s_setprio 0
	s_setprio 1
	v_mfma_f32_16x16x32_bf16 v[112:115], v[166:169], v[182:185], v[112:115]
	v_mfma_f32_16x16x32_bf16 v[104:107], v[174:177], v[182:185], v[104:107]
	v_mfma_f32_16x16x32_bf16 v[96:99], v[166:169], v[190:193], v[96:99]
	v_mfma_f32_16x16x32_bf16 v[88:91], v[174:177], v[190:193], v[88:91]
	v_mfma_f32_16x16x32_bf16 v[80:83], v[166:169], v[198:201], v[80:83]
	v_mfma_f32_16x16x32_bf16 v[72:75], v[174:177], v[198:201], v[72:75]
	v_mfma_f32_16x16x32_bf16 v[68:71], v[166:169], v[206:209], v[68:71]
	v_mfma_f32_16x16x32_bf16 v[64:67], v[174:177], v[206:209], v[64:67]
	v_mfma_f32_16x16x32_bf16 v[112:115], v[170:173], v[186:189], v[112:115]
	v_mfma_f32_16x16x32_bf16 v[104:107], v[178:181], v[186:189], v[104:107]
	v_mfma_f32_16x16x32_bf16 v[96:99], v[170:173], v[194:197], v[96:99]
	v_mfma_f32_16x16x32_bf16 v[88:91], v[178:181], v[194:197], v[88:91]
	v_mfma_f32_16x16x32_bf16 v[80:83], v[170:173], v[202:205], v[80:83]
	v_mfma_f32_16x16x32_bf16 v[72:75], v[178:181], v[202:205], v[72:75]
	v_mfma_f32_16x16x32_bf16 v[68:71], v[170:173], v[210:213], v[68:71]
	v_mfma_f32_16x16x32_bf16 v[64:67], v[178:181], v[210:213], v[64:67]
	s_setprio 0
	s_barrier
	s_mov_b32 m0, s26
	v_lshl_add_u64 v[214:215], s[10:11], 0, v[130:131]
	s_add_u32 s40, s10, 0x80000
	ds_read_b128 v[182:185], v144 offset:16384
	ds_read_b128 v[186:189], v144 offset:17408
	ds_read_b128 v[190:193], v144 offset:18432
	ds_read_b128 v[194:197], v144 offset:19456
	ds_read_b128 v[198:201], v144 offset:20480
	ds_read_b128 v[202:205], v144 offset:21504
	ds_read_b128 v[206:209], v144 offset:22528
	ds_read_b128 v[210:213], v144 offset:23552
	global_load_lds_dwordx4 v[214:215], off
	v_lshl_add_u64 v[216:217], s[10:11], 0, v[134:135]
	s_mov_b32 m0, s27
	s_addc_u32 s41, s11, 0
	global_load_lds_dwordx4 v[216:217], off
	v_lshl_add_u64 v[218:219], s[40:41], 0, v[130:131]
	s_mov_b32 m0, s28
	v_lshl_add_u64 v[220:221], s[12:13], 0, v[132:133]
	global_load_lds_dwordx4 v[218:219], off
	v_lshl_add_u64 v[218:219], s[40:41], 0, v[134:135]
	s_mov_b32 m0, s29
	s_nop 0
	global_load_lds_dwordx4 v[218:219], off
	v_lshl_add_u64 v[218:219], s[12:13], 0, v[128:129]
	s_mov_b32 m0, s17
	s_nop 0
	global_load_lds_dwordx4 v[218:219], off
	s_mov_b32 m0, s18
	s_nop 0
	global_load_lds_dwordx4 v[220:221], off
	s_waitcnt vmcnt(8)
	s_waitcnt lgkmcnt(0)
	s_barrier
; #define PG8_STAGE(bufoff, gbase, voff) do { _Pragma("unroll") for (int _i = 0; _i < 2; ++_i) \
;         __builtin_amdgcn_global_load_lds((const unsigned*)((const char*)(gbase) + (voff)[_i]), (LAS unsigned*)(lds + (bufoff) + ldsw + _i * 8192), 16, 0, 0); } while (0)
; #define PG8_LDA(dst, b, h) do { _Pragma("unroll") for (int m = 0; m < 4; ++m) _Pragma("unroll") for (int k = 0; k < 2; ++k) dst[m][k] = *(const LAS bf16x8*)(lds + PG8_SA(b, h) + aoff + m * 2048 + k * 1024); } while (0)
; #define PG8_LDB(dst, b, h) do { _Pragma("unroll") for (int n = 0; n < 2; ++n) _Pragma("unroll") for (int k = 0; k < 2; ++k) dst[n][k] = *(const LAS bf16x8*)(lds + PG8_SB(b, h) + boff + n * 2048 + k * 1024); } while (0)
; #define PG8_MMA(ai, bj, At, Bt) do { __builtin_amdgcn_s_setprio(1); _Pragma("unroll") for (int m = 0; m < 4; ++m) _Pragma("unroll") for (int n = 0; n < 2; ++n) _Pragma("unroll") for (int k = 0; k < 2; ++k) \
;         acc[ai][bj][m][n] = __builtin_amdgcn_mfma_f32_16x16x32_bf16(Bt[n][k], At[m][k], acc[ai][bj][m][n], 0, 0, 0); __builtin_amdgcn_s_setprio(0); } while (0)
; #define PG8_WAIT_V(n) asm volatile("s_waitcnt vmcnt(" #n ")" ::: "memory")
; #define PG8_WAIT_L(n) asm volatile("s_waitcnt lgkmcnt(" #n ")" ::: "memory")
; #define PG8_BAR __builtin_amdgcn_s_barrier()
; #define PG8_SCHED __builtin_amdgcn_sched_barrier(0)
; template <class Epi, class Sched, bool SP2 = PG8_SP2>
; __device__ __forceinline__ void gemm_phase(LAS unsigned char* lds, const Gemm g, const Sched& S, const Epi& E) {
;     ...
;             PG8_WAIT_V(8); PG8_WAIT_L(0); PG8_BAR; PG8_MMA(0, 0, At, B0); PG8_MMA(0, 1, At, B1); PG8_BAR; PG8_SCHED;
;             PG8_LDA(At, 0, 1); PG8_STAGE(PG8_SB(0, 0), b2, voffB); PG8_STAGE(PG8_SB(0, 1), b2 + hstepB, voffB); PG8_STAGE(PG8_SA(0, 0), a2, voffA);
;             PG8_WAIT_V(8); PG8_WAIT_L(0); PG8_BAR; PG8_MMA(1, 0, At, B0); PG8_MMA(1, 1, At, B1); PG8_BAR; PG8_SCHED;
;             PG8_LDB(B0, 1, 0); PG8_LDB(B1, 1, 1); PG8_SCHED; PG8_LDA(At, 1, 0); PG8_STAGE(PG8_SA(0, 1), a2 + hstepA, voffA);
;             PG8_WAIT_V(8); PG8_WAIT_L(0); PG8_BAR; PG8_MMA(0, 0, At, B0); PG8_MMA(0, 1, At, B1); PG8_BAR; PG8_SCHED;
	s_setprio 1
	v_mfma_f32_16x16x32_bf16 v[60:63], v[150:153], v[182:185], v[60:63]
	v_mfma_f32_16x16x32_bf16 v[56:59], v[158:161], v[182:185], v[56:59]
	v_mfma_f32_16x16x32_bf16 v[52:55], v[150:153], v[190:193], v[52:55]
	v_mfma_f32_16x16x32_bf16 v[44:47], v[158:161], v[190:193], v[44:47]
	v_mfma_f32_16x16x32_bf16 v[36:39], v[150:153], v[198:201], v[36:39]
	v_mfma_f32_16x16x32_bf16 v[28:31], v[158:161], v[198:201], v[28:31]
	v_mfma_f32_16x16x32_bf16 v[20:23], v[150:153], v[206:209], v[20:23]
	v_mfma_f32_16x16x32_bf16 v[12:15], v[158:161], v[206:209], v[12:15]
	v_mfma_f32_16x16x32_bf16 v[60:63], v[154:157], v[186:189], v[60:63]
	v_mfma_f32_16x16x32_bf16 v[56:59], v[162:165], v[186:189], v[56:59]
	v_mfma_f32_16x16x32_bf16 v[52:55], v[154:157], v[194:197], v[52:55]
	v_mfma_f32_16x16x32_bf16 v[44:47], v[162:165], v[194:197], v[44:47]
	v_mfma_f32_16x16x32_bf16 v[36:39], v[154:157], v[202:205], v[36:39]
	v_mfma_f32_16x16x32_bf16 v[28:31], v[162:165], v[202:205], v[28:31]
	v_mfma_f32_16x16x32_bf16 v[20:23], v[154:157], v[210:213], v[20:23]
	v_mfma_f32_16x16x32_bf16 v[12:15], v[162:165], v[210:213], v[12:15]
	s_setprio 0
	s_setprio 1
	v_mfma_f32_16x16x32_bf16 v[48:51], v[166:169], v[182:185], v[48:51]
	v_mfma_f32_16x16x32_bf16 v[40:43], v[174:177], v[182:185], v[40:43]
	v_mfma_f32_16x16x32_bf16 v[32:35], v[166:169], v[190:193], v[32:35]
	v_mfma_f32_16x16x32_bf16 v[24:27], v[174:177], v[190:193], v[24:27]
	v_mfma_f32_16x16x32_bf16 v[16:19], v[166:169], v[198:201], v[16:19]
	v_mfma_f32_16x16x32_bf16 v[8:11], v[174:177], v[198:201], v[8:11]
	v_mfma_f32_16x16x32_bf16 v[4:7], v[166:169], v[206:209], v[4:7]
	v_mfma_f32_16x16x32_bf16 v[0:3], v[174:177], v[206:209], v[0:3]
	v_mfma_f32_16x16x32_bf16 v[48:51], v[170:173], v[186:189], v[48:51]
	v_mfma_f32_16x16x32_bf16 v[40:43], v[178:181], v[186:189], v[40:43]
	v_mfma_f32_16x16x32_bf16 v[32:35], v[170:173], v[194:197], v[32:35]
	v_mfma_f32_16x16x32_bf16 v[24:27], v[178:181], v[194:197], v[24:27]
	v_mfma_f32_16x16x32_bf16 v[16:19], v[170:173], v[202:205], v[16:19]
	v_mfma_f32_16x16x32_bf16 v[8:11], v[178:181], v[202:205], v[8:11]
	v_mfma_f32_16x16x32_bf16 v[4:7], v[170:173], v[210:213], v[4:7]
	v_mfma_f32_16x16x32_bf16 v[0:3], v[178:181], v[210:213], v[0:3]
	s_setprio 0
	s_barrier
	ds_read_b128 v[150:153], v145
	ds_read_b128 v[154:157], v145 offset:1024
	ds_read_b128 v[158:161], v145 offset:2048
	ds_read_b128 v[162:165], v145 offset:3072
	ds_read_b128 v[166:169], v146
	ds_read_b128 v[170:173], v146 offset:1024
	ds_read_b128 v[174:177], v146 offset:2048
	ds_read_b128 v[178:181], v146 offset:3072
	s_add_u32 s12, s12, 0x80000
	s_addc_u32 s13, s13, 0
	s_mov_b32 m0, s19
	v_lshl_add_u64 v[224:225], s[12:13], 0, v[128:129]
	ds_read_b128 v[182:185], v144 offset:32768
	ds_read_b128 v[186:189], v144 offset:33792
	ds_read_b128 v[190:193], v144 offset:34816
	ds_read_b128 v[194:197], v144 offset:35840
	ds_read_b128 v[198:201], v144 offset:36864
	ds_read_b128 v[202:205], v144 offset:37888
	ds_read_b128 v[206:209], v144 offset:38912
	ds_read_b128 v[210:213], v144 offset:39936
	global_load_lds_dwordx4 v[224:225], off
	v_lshl_add_u64 v[224:225], s[12:13], 0, v[132:133]
	s_mov_b32 m0, s20
	s_nop 0
	global_load_lds_dwordx4 v[224:225], off
	s_waitcnt vmcnt(8)
	s_waitcnt lgkmcnt(0)
	s_barrier
	s_setprio 1
	v_mfma_f32_16x16x32_bf16 v[124:127], v[150:153], v[182:185], v[124:127]
	v_mfma_f32_16x16x32_bf16 v[120:123], v[158:161], v[182:185], v[120:123]
	v_mfma_f32_16x16x32_bf16 v[116:119], v[150:153], v[190:193], v[116:119]
	v_mfma_f32_16x16x32_bf16 v[108:111], v[158:161], v[190:193], v[108:111]
	v_mfma_f32_16x16x32_bf16 v[100:103], v[150:153], v[198:201], v[100:103]
	v_mfma_f32_16x16x32_bf16 v[92:95], v[158:161], v[198:201], v[92:95]
	v_mfma_f32_16x16x32_bf16 v[84:87], v[150:153], v[206:209], v[84:87]
	v_mfma_f32_16x16x32_bf16 v[76:79], v[158:161], v[206:209], v[76:79]
	v_mfma_f32_16x16x32_bf16 v[124:127], v[154:157], v[186:189], v[124:127]
	v_mfma_f32_16x16x32_bf16 v[120:123], v[162:165], v[186:189], v[120:123]
	v_mfma_f32_16x16x32_bf16 v[116:119], v[154:157], v[194:197], v[116:119]
	v_mfma_f32_16x16x32_bf16 v[108:111], v[162:165], v[194:197], v[108:111]
	v_mfma_f32_16x16x32_bf16 v[100:103], v[154:157], v[202:205], v[100:103]
	v_mfma_f32_16x16x32_bf16 v[92:95], v[162:165], v[202:205], v[92:95]
	v_mfma_f32_16x16x32_bf16 v[84:87], v[154:157], v[210:213], v[84:87]
	v_mfma_f32_16x16x32_bf16 v[76:79], v[162:165], v[210:213], v[76:79]
	s_setprio 0
	s_setprio 1
	v_mfma_f32_16x16x32_bf16 v[112:115], v[166:169], v[182:185], v[112:115]
	v_mfma_f32_16x16x32_bf16 v[104:107], v[174:177], v[182:185], v[104:107]
	v_mfma_f32_16x16x32_bf16 v[96:99], v[166:169], v[190:193], v[96:99]
	v_mfma_f32_16x16x32_bf16 v[88:91], v[174:177], v[190:193], v[88:91]
	v_mfma_f32_16x16x32_bf16 v[80:83], v[166:169], v[198:201], v[80:83]
	v_mfma_f32_16x16x32_bf16 v[72:75], v[174:177], v[198:201], v[72:75]
	v_mfma_f32_16x16x32_bf16 v[68:71], v[166:169], v[206:209], v[68:71]
	v_mfma_f32_16x16x32_bf16 v[64:67], v[174:177], v[206:209], v[64:67]
	v_mfma_f32_16x16x32_bf16 v[112:115], v[170:173], v[186:189], v[112:115]
	v_mfma_f32_16x16x32_bf16 v[104:107], v[178:181], v[186:189], v[104:107]
	v_mfma_f32_16x16x32_bf16 v[96:99], v[170:173], v[194:197], v[96:99]
	v_mfma_f32_16x16x32_bf16 v[88:91], v[178:181], v[194:197], v[88:91]
	v_mfma_f32_16x16x32_bf16 v[80:83], v[170:173], v[202:205], v[80:83]
	v_mfma_f32_16x16x32_bf16 v[72:75], v[178:181], v[202:205], v[72:75]
	v_mfma_f32_16x16x32_bf16 v[68:71], v[170:173], v[210:213], v[68:71]
	v_mfma_f32_16x16x32_bf16 v[64:67], v[178:181], v[210:213], v[64:67]
	s_setprio 0
	s_barrier
; #define PG8_STAGE(bufoff, gbase, voff) do { _Pragma("unroll") for (int _i = 0; _i < 2; ++_i) \
;         __builtin_amdgcn_global_load_lds((const unsigned*)((const char*)(gbase) + (voff)[_i]), (LAS unsigned*)(lds + (bufoff) + ldsw + _i * 8192), 16, 0, 0); } while (0)
; #define PG8_LDA(dst, b, h) do { _Pragma("unroll") for (int m = 0; m < 4; ++m) _Pragma("unroll") for (int k = 0; k < 2; ++k) dst[m][k] = *(const LAS bf16x8*)(lds + PG8_SA(b, h) + aoff + m * 2048 + k * 1024); } while (0)
; #define PG8_MMA(ai, bj, At, Bt) do { __builtin_amdgcn_s_setprio(1); _Pragma("unroll") for (int m = 0; m < 4; ++m) _Pragma("unroll") for (int n = 0; n < 2; ++n) _Pragma("unroll") for (int k = 0; k < 2; ++k) \
;         acc[ai][bj][m][n] = __builtin_amdgcn_mfma_f32_16x16x32_bf16(Bt[n][k], At[m][k], acc[ai][bj][m][n], 0, 0, 0); __builtin_amdgcn_s_setprio(0); } while (0)
; #define PG8_WAIT_V(n) asm volatile("s_waitcnt vmcnt(" #n ")" ::: "memory")
; #define PG8_WAIT_L(n) asm volatile("s_waitcnt lgkmcnt(" #n ")" ::: "memory")
; #define PG8_BAR __builtin_amdgcn_s_barrier()
; #define PG8_SCHED __builtin_amdgcn_sched_barrier(0)
; template <class Epi, class Sched, bool SP2 = PG8_SP2>
; __device__ __forceinline__ void gemm_phase(LAS unsigned char* lds, const Gemm g, const Sched& S, const Epi& E) {
;     ...
;             PG8_WAIT_V(8); PG8_WAIT_L(0); PG8_BAR; PG8_MMA(0, 0, At, B0); PG8_MMA(0, 1, At, B1); PG8_BAR; PG8_SCHED;
;             PG8_LDA(At, 1, 1); PG8_STAGE(PG8_SB(1, 0), b3, voffB); PG8_STAGE(PG8_SB(1, 1), b3 + hstepB, voffB); PG8_STAGE(PG8_SA(1, 0), a3, voffA);
;             PG8_WAIT_V(8); PG8_WAIT_L(0); PG8_BAR; PG8_MMA(1, 0, At, B0); PG8_MMA(1, 1, At, B1); PG8_BAR; PG8_SCHED;
	s_mov_b32 m0, s33
	v_lshl_add_u64 v[214:215], v[214:215], 0, s[8:9]
	s_add_u32 s10, s10, 0x80080
	ds_read_b128 v[182:185], v144 offset:49152
	ds_read_b128 v[186:189], v144 offset:50176
	ds_read_b128 v[190:193], v144 offset:51200
	ds_read_b128 v[194:197], v144 offset:52224
	ds_read_b128 v[198:201], v144 offset:53248
	ds_read_b128 v[202:205], v144 offset:54272
	ds_read_b128 v[206:209], v144 offset:55296
	ds_read_b128 v[210:213], v144 offset:56320
	global_load_lds_dwordx4 v[214:215], off
	v_lshl_add_u64 v[214:215], v[216:217], 0, s[8:9]
	s_mov_b32 m0, s36
	s_addc_u32 s11, s11, 0
	global_load_lds_dwordx4 v[214:215], off
	v_lshl_add_u64 v[214:215], s[10:11], 0, v[130:131]
	s_mov_b32 m0, s37
	s_nop 0
	global_load_lds_dwordx4 v[214:215], off
	v_lshl_add_u64 v[214:215], s[10:11], 0, v[134:135]
	s_mov_b32 m0, s38
	s_nop 0
	global_load_lds_dwordx4 v[214:215], off
	v_lshl_add_u64 v[214:215], v[218:219], 0, s[8:9]
	s_mov_b32 m0, s22
	s_nop 0
	global_load_lds_dwordx4 v[214:215], off
	v_lshl_add_u64 v[214:215], v[220:221], 0, s[8:9]
	s_mov_b32 m0, s23
	s_nop 0
	global_load_lds_dwordx4 v[214:215], off
	s_waitcnt vmcnt(8)
	s_waitcnt lgkmcnt(0)
	s_barrier
	s_setprio 1
	v_mfma_f32_16x16x32_bf16 v[60:63], v[150:153], v[182:185], v[60:63]
	v_mfma_f32_16x16x32_bf16 v[56:59], v[158:161], v[182:185], v[56:59]
	v_mfma_f32_16x16x32_bf16 v[52:55], v[150:153], v[190:193], v[52:55]
	v_mfma_f32_16x16x32_bf16 v[44:47], v[158:161], v[190:193], v[44:47]
	v_mfma_f32_16x16x32_bf16 v[36:39], v[150:153], v[198:201], v[36:39]
	v_mfma_f32_16x16x32_bf16 v[28:31], v[158:161], v[198:201], v[28:31]
	v_mfma_f32_16x16x32_bf16 v[20:23], v[150:153], v[206:209], v[20:23]
	v_mfma_f32_16x16x32_bf16 v[12:15], v[158:161], v[206:209], v[12:15]
	v_mfma_f32_16x16x32_bf16 v[60:63], v[154:157], v[186:189], v[60:63]
	v_mfma_f32_16x16x32_bf16 v[56:59], v[162:165], v[186:189], v[56:59]
	v_mfma_f32_16x16x32_bf16 v[52:55], v[154:157], v[194:197], v[52:55]
	v_mfma_f32_16x16x32_bf16 v[44:47], v[162:165], v[194:197], v[44:47]
	v_mfma_f32_16x16x32_bf16 v[36:39], v[154:157], v[202:205], v[36:39]
	v_mfma_f32_16x16x32_bf16 v[28:31], v[162:165], v[202:205], v[28:31]
	v_mfma_f32_16x16x32_bf16 v[20:23], v[154:157], v[210:213], v[20:23]
	v_mfma_f32_16x16x32_bf16 v[12:15], v[162:165], v[210:213], v[12:15]
	s_setprio 0
	s_setprio 1
	v_mfma_f32_16x16x32_bf16 v[48:51], v[166:169], v[182:185], v[48:51]
	v_mfma_f32_16x16x32_bf16 v[40:43], v[174:177], v[182:185], v[40:43]
	v_mfma_f32_16x16x32_bf16 v[32:35], v[166:169], v[190:193], v[32:35]
	v_mfma_f32_16x16x32_bf16 v[24:27], v[174:177], v[190:193], v[24:27]
	v_mfma_f32_16x16x32_bf16 v[16:19], v[166:169], v[198:201], v[16:19]
	v_mfma_f32_16x16x32_bf16 v[8:11], v[174:177], v[198:201], v[8:11]
	v_mfma_f32_16x16x32_bf16 v[4:7], v[166:169], v[206:209], v[4:7]
	v_mfma_f32_16x16x32_bf16 v[0:3], v[174:177], v[206:209], v[0:3]
	v_mfma_f32_16x16x32_bf16 v[48:51], v[170:173], v[186:189], v[48:51]
	v_mfma_f32_16x16x32_bf16 v[40:43], v[178:181], v[186:189], v[40:43]
	v_mfma_f32_16x16x32_bf16 v[32:35], v[170:173], v[194:197], v[32:35]
	v_mfma_f32_16x16x32_bf16 v[24:27], v[178:181], v[194:197], v[24:27]
	v_mfma_f32_16x16x32_bf16 v[16:19], v[170:173], v[202:205], v[16:19]
	v_mfma_f32_16x16x32_bf16 v[8:11], v[178:181], v[202:205], v[8:11]
	v_mfma_f32_16x16x32_bf16 v[4:7], v[170:173], v[210:213], v[4:7]
	v_mfma_f32_16x16x32_bf16 v[0:3], v[178:181], v[210:213], v[0:3]
	s_setprio 0
	s_barrier
	s_add_i32 s2, s2, 2
	s_add_u32 s0, s0, 0x100
	s_addc_u32 s1, s1, 0
	s_cmp_gt_u32 s2, 29
	s_cbranch_scc0 .LBB0_262
	s_cmpk_lt_u32 s14, 0x100
	s_cbranch_scc0 .LBB0_265
	s_barrier

; #define PG8_STAGE(bufoff, gbase, voff) do { _Pragma("unroll") for (int _i = 0; _i < 2; ++_i) \
;         __builtin_amdgcn_global_load_lds((const unsigned*)((const char*)(gbase) + (voff)[_i]), (LAS unsigned*)(lds + (bufoff) + ldsw + _i * 8192), 16, 0, 0); } while (0)
; #define PG8_LDA(dst, b, h) do { _Pragma("unroll") for (int m = 0; m < 4; ++m) _Pragma("unroll") for (int k = 0; k < 2; ++k) dst[m][k] = *(const LAS bf16x8*)(lds + PG8_SA(b, h) + aoff + m * 2048 + k * 1024); } while (0)
; #define PG8_LDB(dst, b, h) do { _Pragma("unroll") for (int n = 0; n < 2; ++n) _Pragma("unroll") for (int k = 0; k < 2; ++k) dst[n][k] = *(const LAS bf16x8*)(lds + PG8_SB(b, h) + boff + n * 2048 + k * 1024); } while (0)
; #define PG8_MMA(ai, bj, At, Bt) do { __builtin_amdgcn_s_setprio(1); _Pragma("unroll") for (int m = 0; m < 4; ++m) _Pragma("unroll") for (int n = 0; n < 2; ++n) _Pragma("unroll") for (int k = 0; k < 2; ++k) \
;         acc[ai][bj][m][n] = __builtin_amdgcn_mfma_f32_16x16x32_bf16(Bt[n][k], At[m][k], acc[ai][bj][m][n], 0, 0, 0); __builtin_amdgcn_s_setprio(0); } while (0)
; #define PG8_WAIT_V(n) asm volatile("s_waitcnt vmcnt(" #n ")" ::: "memory")
; #define PG8_WAIT_L(n) asm volatile("s_waitcnt lgkmcnt(" #n ")" ::: "memory")
; #define PG8_BAR __builtin_amdgcn_s_barrier()
; template <class Epi, class Sched, bool SP2 = PG8_SP2>
; __device__ __forceinline__ void gemm_phase(LAS unsigned char* lds, const Gemm g, const Sched& S, const Epi& E) {
;     ...
;         for (int t = 0; t < nt; t += 2) {
;             const bool last = (t == nt - 2);
;             const char* a1 = cA + (size_t)(t + 1) * kstep;
;             const char* a2 = last ? nA : cA + (size_t)(t + 2) * kstep; const char* b2 = last ? nB : cB + (size_t)(t + 2) * kstep;
;             const char* a3 = a2 + kstep; const char* b3 = b2 + kstep;
;             if constexpr (SP2) {
;             PG8_LDB(B0, 0, 0); PG8_LDB(B1, 0, 1); PG8_SCHED; PG8_LDA(At, 0, 0); PG8_STAGE(PG8_SA(1, 1), a1 + hstepA, voffA);
;             PG8_WAIT_V(8); PG8_WAIT_L(0); PG8_BAR; PG8_MMA(0, 0, At, B0); PG8_MMA(0, 1, At, B1); PG8_BAR; PG8_SCHED;
;             PG8_LDA(At, 0, 1); PG8_STAGE(PG8_SB(0, 0), b2, voffB); PG8_STAGE(PG8_SB(0, 1), b2 + hstepB, voffB); PG8_STAGE(PG8_SA(0, 0), a2, voffA);
;             PG8_WAIT_V(8); PG8_WAIT_L(0); PG8_BAR; PG8_MMA(1, 0, At, B0); PG8_MMA(1, 1, At, B1); PG8_BAR; PG8_SCHED;
.LBB0_333:
	ds_read_b128 v[144:147], v168
	ds_read_b128 v[148:151], v168 offset:1024
	ds_read_b128 v[172:175], v168 offset:2048
	ds_read_b128 v[176:179], v168 offset:3072
	ds_read_b128 v[180:183], v169
	ds_read_b128 v[184:187], v169 offset:1024
	ds_read_b128 v[188:191], v169 offset:2048
	ds_read_b128 v[192:195], v169 offset:3072
	s_add_u32 s3, s0, 0xfff80080
	s_addc_u32 s30, s1, -1
	s_cmp_eq_u32 s56, 4
	s_cselect_b32 s35, s2, s30
	s_cselect_b32 s34, s23, s3
	s_cselect_b32 s31, s21, s55
	s_cselect_b32 s30, s53, s54
	s_add_i32 m0, s29, 0xc000
	ds_read_b128 v[196:199], v170
	ds_read_b128 v[200:203], v170 offset:1024
	ds_read_b128 v[204:207], v170 offset:2048
	ds_read_b128 v[208:211], v170 offset:3072
	ds_read_b128 v[212:215], v170 offset:4096
	ds_read_b128 v[216:219], v170 offset:5120
	ds_read_b128 v[224:227], v170 offset:6144
	ds_read_b128 v[228:231], v170 offset:7168
	global_load_lds_dwordx4 v136, s[0:1]
	s_add_i32 m0, s29, 0xe000
	s_nop 0
	global_load_lds_dwordx4 v138, s[0:1]
	s_waitcnt vmcnt(8)
	s_waitcnt lgkmcnt(0)
	s_barrier
	s_setprio 1
	v_mfma_f32_16x16x32_bf16 v[124:127], v[144:147], v[196:199], v[124:127]
	v_mfma_f32_16x16x32_bf16 v[120:123], v[172:175], v[196:199], v[120:123]
	v_mfma_f32_16x16x32_bf16 v[108:111], v[144:147], v[204:207], v[108:111]
	v_mfma_f32_16x16x32_bf16 v[104:107], v[172:175], v[204:207], v[104:107]
	v_mfma_f32_16x16x32_bf16 v[92:95], v[144:147], v[212:215], v[92:95]
	v_mfma_f32_16x16x32_bf16 v[88:91], v[172:175], v[212:215], v[88:91]
	v_mfma_f32_16x16x32_bf16 v[84:87], v[144:147], v[224:227], v[84:87]
	v_mfma_f32_16x16x32_bf16 v[76:79], v[172:175], v[224:227], v[76:79]
	v_mfma_f32_16x16x32_bf16 v[124:127], v[148:151], v[200:203], v[124:127]
	v_mfma_f32_16x16x32_bf16 v[120:123], v[176:179], v[200:203], v[120:123]
	v_mfma_f32_16x16x32_bf16 v[108:111], v[148:151], v[208:211], v[108:111]
	v_mfma_f32_16x16x32_bf16 v[104:107], v[176:179], v[208:211], v[104:107]
	v_mfma_f32_16x16x32_bf16 v[92:95], v[148:151], v[216:219], v[92:95]
	v_mfma_f32_16x16x32_bf16 v[88:91], v[176:179], v[216:219], v[88:91]
	v_mfma_f32_16x16x32_bf16 v[84:87], v[148:151], v[228:231], v[84:87]
	v_mfma_f32_16x16x32_bf16 v[76:79], v[176:179], v[228:231], v[76:79]
	s_setprio 0
	s_setprio 1
	v_mfma_f32_16x16x32_bf16 v[116:119], v[180:183], v[196:199], v[116:119]
	v_mfma_f32_16x16x32_bf16 v[112:115], v[188:191], v[196:199], v[112:115]
	v_mfma_f32_16x16x32_bf16 v[100:103], v[180:183], v[204:207], v[100:103]
	v_mfma_f32_16x16x32_bf16 v[96:99], v[188:191], v[204:207], v[96:99]
	v_mfma_f32_16x16x32_bf16 v[80:83], v[180:183], v[212:215], v[80:83]
	v_mfma_f32_16x16x32_bf16 v[72:75], v[188:191], v[212:215], v[72:75]
	v_mfma_f32_16x16x32_bf16 v[68:71], v[180:183], v[224:227], v[68:71]
	v_mfma_f32_16x16x32_bf16 v[64:67], v[188:191], v[224:227], v[64:67]
	v_mfma_f32_16x16x32_bf16 v[116:119], v[184:187], v[200:203], v[116:119]
	v_mfma_f32_16x16x32_bf16 v[112:115], v[192:195], v[200:203], v[112:115]
	v_mfma_f32_16x16x32_bf16 v[100:103], v[184:187], v[208:211], v[100:103]
	v_mfma_f32_16x16x32_bf16 v[96:99], v[192:195], v[208:211], v[96:99]
	v_mfma_f32_16x16x32_bf16 v[80:83], v[184:187], v[216:219], v[80:83]
	v_mfma_f32_16x16x32_bf16 v[72:75], v[192:195], v[216:219], v[72:75]
	v_mfma_f32_16x16x32_bf16 v[68:71], v[184:187], v[228:231], v[68:71]
	v_mfma_f32_16x16x32_bf16 v[64:67], v[192:195], v[228:231], v[64:67]
	s_setprio 0
	s_barrier
	s_add_i32 s3, s49, s39
	s_add_u32 s98, s30, s16
	s_addc_u32 s99, s31, s17
	s_mov_b32 m0, s3
	ds_read_b128 v[196:199], v170 offset:16384
	ds_read_b128 v[200:203], v170 offset:17408
	ds_read_b128 v[204:207], v170 offset:18432
	ds_read_b128 v[208:211], v170 offset:19456
	ds_read_b128 v[212:215], v170 offset:20480
	ds_read_b128 v[216:219], v170 offset:21504
	ds_read_b128 v[224:227], v170 offset:22528
	ds_read_b128 v[228:231], v170 offset:23552
	global_load_lds_dwordx4 v134, s[30:31]
	s_add_i32 m0, s3, 0x2000
	s_add_u32 s58, s30, 0x20000
	s_addc_u32 s59, s31, 0
	s_add_i32 s3, s50, s39
	global_load_lds_dwordx4 v132, s[30:31]
	s_mov_b32 m0, s3
	s_nop 0
	global_load_lds_dwordx4 v134, s[58:59]
	s_add_i32 m0, s3, 0x2000
	s_nop 0
	global_load_lds_dwordx4 v132, s[58:59]
	s_add_u32 s100, s34, s16
	s_addc_u32 s101, s35, s17
	s_mov_b32 m0, s29
	s_nop 0
	global_load_lds_dwordx4 v128, s[34:35]
	s_mov_b32 m0, s41
	s_nop 0
	global_load_lds_dwordx4 v130, s[34:35]
	s_waitcnt vmcnt(8)
	s_waitcnt lgkmcnt(0)
	s_barrier
	s_setprio 1
	v_mfma_f32_16x16x32_bf16 v[60:63], v[144:147], v[196:199], v[60:63]
	v_mfma_f32_16x16x32_bf16 v[56:59], v[172:175], v[196:199], v[56:59]
	v_mfma_f32_16x16x32_bf16 v[44:47], v[144:147], v[204:207], v[44:47]
	v_mfma_f32_16x16x32_bf16 v[40:43], v[172:175], v[204:207], v[40:43]
	v_mfma_f32_16x16x32_bf16 v[28:31], v[144:147], v[212:215], v[28:31]
	v_mfma_f32_16x16x32_bf16 v[24:27], v[172:175], v[212:215], v[24:27]
	v_mfma_f32_16x16x32_bf16 v[12:15], v[144:147], v[224:227], v[12:15]
	v_mfma_f32_16x16x32_bf16 v[8:11], v[172:175], v[224:227], v[8:11]
	v_mfma_f32_16x16x32_bf16 v[60:63], v[148:151], v[200:203], v[60:63]
	v_mfma_f32_16x16x32_bf16 v[56:59], v[176:179], v[200:203], v[56:59]
	v_mfma_f32_16x16x32_bf16 v[44:47], v[148:151], v[208:211], v[44:47]
	v_mfma_f32_16x16x32_bf16 v[40:43], v[176:179], v[208:211], v[40:43]
	v_mfma_f32_16x16x32_bf16 v[28:31], v[148:151], v[216:219], v[28:31]
	v_mfma_f32_16x16x32_bf16 v[24:27], v[176:179], v[216:219], v[24:27]
	v_mfma_f32_16x16x32_bf16 v[12:15], v[148:151], v[228:231], v[12:15]
	v_mfma_f32_16x16x32_bf16 v[8:11], v[176:179], v[228:231], v[8:11]
	s_setprio 0
	s_setprio 1
	v_mfma_f32_16x16x32_bf16 v[52:55], v[180:183], v[196:199], v[52:55]
	v_mfma_f32_16x16x32_bf16 v[48:51], v[188:191], v[196:199], v[48:51]
	v_mfma_f32_16x16x32_bf16 v[36:39], v[180:183], v[204:207], v[36:39]
	v_mfma_f32_16x16x32_bf16 v[32:35], v[188:191], v[204:207], v[32:35]
	v_mfma_f32_16x16x32_bf16 v[20:23], v[180:183], v[212:215], v[20:23]
	v_mfma_f32_16x16x32_bf16 v[16:19], v[188:191], v[212:215], v[16:19]
	v_mfma_f32_16x16x32_bf16 v[4:7], v[180:183], v[224:227], v[4:7]
	v_mfma_f32_16x16x32_bf16 v[0:3], v[188:191], v[224:227], v[0:3]
	v_mfma_f32_16x16x32_bf16 v[52:55], v[184:187], v[200:203], v[52:55]
	v_mfma_f32_16x16x32_bf16 v[48:51], v[192:195], v[200:203], v[48:51]
	v_mfma_f32_16x16x32_bf16 v[36:39], v[184:187], v[208:211], v[36:39]
	v_mfma_f32_16x16x32_bf16 v[32:35], v[192:195], v[208:211], v[32:35]
	v_mfma_f32_16x16x32_bf16 v[20:23], v[184:187], v[216:219], v[20:23]
	v_mfma_f32_16x16x32_bf16 v[16:19], v[192:195], v[216:219], v[16:19]
	v_mfma_f32_16x16x32_bf16 v[4:7], v[184:187], v[228:231], v[4:7]
	v_mfma_f32_16x16x32_bf16 v[0:3], v[192:195], v[228:231], v[0:3]
	s_setprio 0
	s_barrier
; #define PG8_STAGE(bufoff, gbase, voff) do { _Pragma("unroll") for (int _i = 0; _i < 2; ++_i) \
;         __builtin_amdgcn_global_load_lds((const unsigned*)((const char*)(gbase) + (voff)[_i]), (LAS unsigned*)(lds + (bufoff) + ldsw + _i * 8192), 16, 0, 0); } while (0)
; #define PG8_WAIT_V(n) asm volatile("s_waitcnt vmcnt(" #n ")" ::: "memory")
; template <class Epi, class Sched, bool SP2 = PG8_SP2>
; __device__ __forceinline__ void gemm_phase(LAS unsigned char* lds, const Gemm g, const Sched& S, const Epi& E) {
;     ...
;             PG8_LDB(B0, 1, 0); PG8_LDB(B1, 1, 1); PG8_SCHED; PG8_LDA(At, 1, 0); PG8_STAGE(PG8_SA(0, 1), a2 + hstepA, voffA);
;             PG8_WAIT_V(8); PG8_WAIT_L(0); PG8_BAR; PG8_MMA(0, 0, At, B0); PG8_MMA(0, 1, At, B1); PG8_BAR; PG8_SCHED;
;             PG8_LDA(At, 1, 1); PG8_STAGE(PG8_SB(1, 0), b3, voffB); PG8_STAGE(PG8_SB(1, 1), b3 + hstepB, voffB); PG8_STAGE(PG8_SA(1, 0), a3, voffA);
;             PG8_WAIT_V(8); PG8_WAIT_L(0); PG8_BAR; PG8_MMA(1, 0, At, B0); PG8_MMA(1, 1, At, B1); PG8_BAR; PG8_SCHED;
;             } else {
;             PG8_LDB(B0, 0, 0); PG8_SCHED; PG8_LDA(At, 0, 0); PG8_STAGE(PG8_SA(1, 1), a1 + hstepA, voffA);
;             PG8_WAIT_L(8); PG8_BAR; PG8_WAIT_L(0); PG8_MMA(0, 0, At, B0); PG8_BAR; PG8_SCHED;
;             PG8_LDB(B1, 0, 1); PG8_STAGE(PG8_SB(0, 0), b2, voffB);
;             PG8_BAR; PG8_WAIT_L(0); PG8_MMA(0, 1, At, B1); PG8_BAR;
;             PG8_LDA(At, 0, 1); PG8_STAGE(PG8_SA(0, 0), a2, voffA);
;             PG8_BAR; PG8_WAIT_L(0); PG8_MMA(1, 0, At, B0); PG8_BAR; PG8_SCHED;
;             PG8_STAGE(PG8_SB(0, 1), b2 + hstepB, voffB);
;             PG8_WAIT_V(6); PG8_BAR; PG8_MMA(1, 1, At, B1); PG8_BAR;
;             PG8_LDB(B0, 1, 0); PG8_SCHED; PG8_LDA(At, 1, 0); PG8_STAGE(PG8_SA(0, 1), a2 + hstepA, voffA);
;             PG8_WAIT_L(8); PG8_BAR; PG8_WAIT_L(0); PG8_MMA(0, 0, At, B0); PG8_BAR; PG8_SCHED;
;             PG8_LDB(B1, 1, 1); PG8_STAGE(PG8_SB(1, 0), b3, voffB);
;             PG8_BAR; PG8_WAIT_L(0); PG8_MMA(0, 1, At, B1); PG8_BAR;
;             PG8_LDA(At, 1, 1); PG8_STAGE(PG8_SA(1, 0), a3, voffA);
;             PG8_BAR; PG8_WAIT_L(0); PG8_MMA(1, 0, At, B0); PG8_BAR; PG8_SCHED;
;             PG8_STAGE(PG8_SB(1, 1), b3 + hstepB, voffB);
;             PG8_WAIT_V(6); PG8_BAR; PG8_MMA(1, 1, At, B1); PG8_BAR;
;             }
;         }
;         if (wr == 0) PG8_BAR;
	s_add_i32 s3, 0, 0x18000
	s_add_i32 s57, 0, 0x1c000
	v_add_u32_e32 v176, s3, v166
	v_add_u32_e32 v192, s57, v166
	ds_read_b128 v[144:147], v176
	ds_read_b128 v[148:151], v176 offset:1024
	ds_read_b128 v[172:175], v176 offset:2048
	ds_read_b128 v[176:179], v176 offset:3072
	ds_read_b128 v[180:183], v192
	ds_read_b128 v[184:187], v192 offset:1024
	ds_read_b128 v[188:191], v192 offset:2048
	ds_read_b128 v[192:195], v192 offset:3072
	s_add_u32 s34, s34, 0x80000
	s_addc_u32 s35, s35, 0
	s_mov_b32 m0, s42
	ds_read_b128 v[196:199], v170 offset:32768
	ds_read_b128 v[200:203], v170 offset:33792
	ds_read_b128 v[204:207], v170 offset:34816
	ds_read_b128 v[208:211], v170 offset:35840
	ds_read_b128 v[212:215], v170 offset:36864
	ds_read_b128 v[216:219], v170 offset:37888
	ds_read_b128 v[224:227], v170 offset:38912
	ds_read_b128 v[228:231], v170 offset:39936
	global_load_lds_dwordx4 v128, s[34:35]
	s_mov_b32 m0, s43
	s_nop 0
	global_load_lds_dwordx4 v130, s[34:35]
	s_waitcnt vmcnt(8)
	s_waitcnt lgkmcnt(0)
	s_barrier
	s_setprio 1
	v_mfma_f32_16x16x32_bf16 v[124:127], v[144:147], v[196:199], v[124:127]
	v_mfma_f32_16x16x32_bf16 v[120:123], v[172:175], v[196:199], v[120:123]
	v_mfma_f32_16x16x32_bf16 v[108:111], v[144:147], v[204:207], v[108:111]
	v_mfma_f32_16x16x32_bf16 v[104:107], v[172:175], v[204:207], v[104:107]
	v_mfma_f32_16x16x32_bf16 v[92:95], v[144:147], v[212:215], v[92:95]
	v_mfma_f32_16x16x32_bf16 v[88:91], v[172:175], v[212:215], v[88:91]
	v_mfma_f32_16x16x32_bf16 v[84:87], v[144:147], v[224:227], v[84:87]
	v_mfma_f32_16x16x32_bf16 v[76:79], v[172:175], v[224:227], v[76:79]
	v_mfma_f32_16x16x32_bf16 v[124:127], v[148:151], v[200:203], v[124:127]
	v_mfma_f32_16x16x32_bf16 v[120:123], v[176:179], v[200:203], v[120:123]
	v_mfma_f32_16x16x32_bf16 v[108:111], v[148:151], v[208:211], v[108:111]
	v_mfma_f32_16x16x32_bf16 v[104:107], v[176:179], v[208:211], v[104:107]
	v_mfma_f32_16x16x32_bf16 v[92:95], v[148:151], v[216:219], v[92:95]
	v_mfma_f32_16x16x32_bf16 v[88:91], v[176:179], v[216:219], v[88:91]
	v_mfma_f32_16x16x32_bf16 v[84:87], v[148:151], v[228:231], v[84:87]
	v_mfma_f32_16x16x32_bf16 v[76:79], v[176:179], v[228:231], v[76:79]
	s_setprio 0
	s_setprio 1
	v_mfma_f32_16x16x32_bf16 v[116:119], v[180:183], v[196:199], v[116:119]
	v_mfma_f32_16x16x32_bf16 v[112:115], v[188:191], v[196:199], v[112:115]
	v_mfma_f32_16x16x32_bf16 v[100:103], v[180:183], v[204:207], v[100:103]
	v_mfma_f32_16x16x32_bf16 v[96:99], v[188:191], v[204:207], v[96:99]
	v_mfma_f32_16x16x32_bf16 v[80:83], v[180:183], v[212:215], v[80:83]
	v_mfma_f32_16x16x32_bf16 v[72:75], v[188:191], v[212:215], v[72:75]
	v_mfma_f32_16x16x32_bf16 v[68:71], v[180:183], v[224:227], v[68:71]
	v_mfma_f32_16x16x32_bf16 v[64:67], v[188:191], v[224:227], v[64:67]
	v_mfma_f32_16x16x32_bf16 v[116:119], v[184:187], v[200:203], v[116:119]
	v_mfma_f32_16x16x32_bf16 v[112:115], v[192:195], v[200:203], v[112:115]
	v_mfma_f32_16x16x32_bf16 v[100:103], v[184:187], v[208:211], v[100:103]
	v_mfma_f32_16x16x32_bf16 v[96:99], v[192:195], v[208:211], v[96:99]
	v_mfma_f32_16x16x32_bf16 v[80:83], v[184:187], v[216:219], v[80:83]
	v_mfma_f32_16x16x32_bf16 v[72:75], v[192:195], v[216:219], v[72:75]
	v_mfma_f32_16x16x32_bf16 v[68:71], v[184:187], v[228:231], v[68:71]
	v_mfma_f32_16x16x32_bf16 v[64:67], v[192:195], v[228:231], v[64:67]
	s_setprio 0
	s_barrier
	s_add_i32 s3, s3, s39
	s_mov_b32 m0, s3
	ds_read_b128 v[196:199], v170 offset:49152
	ds_read_b128 v[200:203], v170 offset:50176
	ds_read_b128 v[204:207], v170 offset:51200
	ds_read_b128 v[208:211], v170 offset:52224
	ds_read_b128 v[212:215], v170 offset:53248
	ds_read_b128 v[216:219], v170 offset:54272
	ds_read_b128 v[224:227], v170 offset:55296
	ds_read_b128 v[228:231], v170 offset:56320
	global_load_lds_dwordx4 v134, s[98:99]
	s_add_i32 m0, s3, 0x2000
	s_add_u32 s30, s30, 0x20080
	s_addc_u32 s31, s31, 0
	s_add_i32 s3, s57, s39
	global_load_lds_dwordx4 v132, s[98:99]
	s_mov_b32 m0, s3
	s_nop 0
	global_load_lds_dwordx4 v134, s[30:31]
	s_add_i32 m0, s3, 0x2000
	s_nop 0
	global_load_lds_dwordx4 v132, s[30:31]
	s_mov_b32 m0, s45
	s_nop 0
	global_load_lds_dwordx4 v128, s[100:101]
	s_mov_b32 m0, s46
	s_nop 0
	global_load_lds_dwordx4 v130, s[100:101]
	s_waitcnt vmcnt(8)
	s_waitcnt lgkmcnt(0)
	s_barrier
	s_setprio 1
	v_mfma_f32_16x16x32_bf16 v[60:63], v[144:147], v[196:199], v[60:63]
	v_mfma_f32_16x16x32_bf16 v[56:59], v[172:175], v[196:199], v[56:59]
	v_mfma_f32_16x16x32_bf16 v[44:47], v[144:147], v[204:207], v[44:47]
	v_mfma_f32_16x16x32_bf16 v[40:43], v[172:175], v[204:207], v[40:43]
	v_mfma_f32_16x16x32_bf16 v[28:31], v[144:147], v[212:215], v[28:31]
	v_mfma_f32_16x16x32_bf16 v[24:27], v[172:175], v[212:215], v[24:27]
	v_mfma_f32_16x16x32_bf16 v[12:15], v[144:147], v[224:227], v[12:15]
	v_mfma_f32_16x16x32_bf16 v[8:11], v[172:175], v[224:227], v[8:11]
	v_mfma_f32_16x16x32_bf16 v[60:63], v[148:151], v[200:203], v[60:63]
	v_mfma_f32_16x16x32_bf16 v[56:59], v[176:179], v[200:203], v[56:59]
	v_mfma_f32_16x16x32_bf16 v[44:47], v[148:151], v[208:211], v[44:47]
	v_mfma_f32_16x16x32_bf16 v[40:43], v[176:179], v[208:211], v[40:43]
	v_mfma_f32_16x16x32_bf16 v[28:31], v[148:151], v[216:219], v[28:31]
	v_mfma_f32_16x16x32_bf16 v[24:27], v[176:179], v[216:219], v[24:27]
	v_mfma_f32_16x16x32_bf16 v[12:15], v[148:151], v[228:231], v[12:15]
	v_mfma_f32_16x16x32_bf16 v[8:11], v[176:179], v[228:231], v[8:11]
	s_setprio 0
	s_setprio 1
	v_mfma_f32_16x16x32_bf16 v[52:55], v[180:183], v[196:199], v[52:55]
	v_mfma_f32_16x16x32_bf16 v[48:51], v[188:191], v[196:199], v[48:51]
	v_mfma_f32_16x16x32_bf16 v[36:39], v[180:183], v[204:207], v[36:39]
	v_mfma_f32_16x16x32_bf16 v[32:35], v[188:191], v[204:207], v[32:35]
	v_mfma_f32_16x16x32_bf16 v[20:23], v[180:183], v[212:215], v[20:23]
	v_mfma_f32_16x16x32_bf16 v[16:19], v[188:191], v[212:215], v[16:19]
	v_mfma_f32_16x16x32_bf16 v[4:7], v[180:183], v[224:227], v[4:7]
	v_mfma_f32_16x16x32_bf16 v[0:3], v[188:191], v[224:227], v[0:3]
	v_mfma_f32_16x16x32_bf16 v[52:55], v[184:187], v[200:203], v[52:55]
	v_mfma_f32_16x16x32_bf16 v[48:51], v[192:195], v[200:203], v[48:51]
	v_mfma_f32_16x16x32_bf16 v[36:39], v[184:187], v[208:211], v[36:39]
	v_mfma_f32_16x16x32_bf16 v[32:35], v[192:195], v[208:211], v[32:35]
	v_mfma_f32_16x16x32_bf16 v[20:23], v[184:187], v[216:219], v[20:23]
	v_mfma_f32_16x16x32_bf16 v[16:19], v[192:195], v[216:219], v[16:19]
	v_mfma_f32_16x16x32_bf16 v[4:7], v[184:187], v[228:231], v[4:7]
	v_mfma_f32_16x16x32_bf16 v[0:3], v[192:195], v[228:231], v[0:3]
	s_setprio 0
	s_barrier
	s_add_i32 s56, s56, 2
	s_add_u32 s0, s0, 0x100
	s_addc_u32 s1, s1, 0
	s_add_u32 s54, s54, 0x100
	s_addc_u32 s55, s55, 0
	s_cmp_gt_u32 s56, 5
	s_cbranch_scc0 .LBB0_333
	s_and_b64 vcc, exec, s[18:19]
	s_cbranch_vccz .LBB0_336
	s_barrier

; #define PG8_STAGE(bufoff, gbase, voff) do { _Pragma("unroll") for (int _i = 0; _i < 2; ++_i) \
;         __builtin_amdgcn_global_load_lds((const unsigned*)((const char*)(gbase) + (voff)[_i]), (LAS unsigned*)(lds + (bufoff) + ldsw + _i * 8192), 16, 0, 0); } while (0)
; #define PG8_LDA(dst, b, h) do { _Pragma("unroll") for (int m = 0; m < 4; ++m) _Pragma("unroll") for (int k = 0; k < 2; ++k) dst[m][k] = *(const LAS bf16x8*)(lds + PG8_SA(b, h) + aoff + m * 2048 + k * 1024); } while (0)
; #define PG8_LDB(dst, b, h) do { _Pragma("unroll") for (int n = 0; n < 2; ++n) _Pragma("unroll") for (int k = 0; k < 2; ++k) dst[n][k] = *(const LAS bf16x8*)(lds + PG8_SB(b, h) + boff + n * 2048 + k * 1024); } while (0)
; #define PG8_MMA(ai, bj, At, Bt) do { __builtin_amdgcn_s_setprio(1); _Pragma("unroll") for (int m = 0; m < 4; ++m) _Pragma("unroll") for (int n = 0; n < 2; ++n) _Pragma("unroll") for (int k = 0; k < 2; ++k) \
;         acc[ai][bj][m][n] = __builtin_amdgcn_mfma_f32_16x16x32_bf16(Bt[n][k], At[m][k], acc[ai][bj][m][n], 0, 0, 0); __builtin_amdgcn_s_setprio(0); } while (0)
; #define PG8_WAIT_V(n) asm volatile("s_waitcnt vmcnt(" #n ")" ::: "memory")
; #define PG8_WAIT_L(n) asm volatile("s_waitcnt lgkmcnt(" #n ")" ::: "memory")
; #define PG8_BAR __builtin_amdgcn_s_barrier()
; template <class Epi, class Sched, bool SP2 = PG8_SP2>
; __device__ __forceinline__ void gemm_phase(LAS unsigned char* lds, const Gemm g, const Sched& S, const Epi& E) {
;     ...
;         for (int t = 0; t < nt; t += 2) {
;             const bool last = (t == nt - 2);
;             const char* a1 = cA + (size_t)(t + 1) * kstep;
;             const char* a2 = last ? nA : cA + (size_t)(t + 2) * kstep; const char* b2 = last ? nB : cB + (size_t)(t + 2) * kstep;
;             const char* a3 = a2 + kstep; const char* b3 = b2 + kstep;
;             if constexpr (SP2) {
;             PG8_LDB(B0, 0, 0); PG8_LDB(B1, 0, 1); PG8_SCHED; PG8_LDA(At, 0, 0); PG8_STAGE(PG8_SA(1, 1), a1 + hstepA, voffA);
;             PG8_WAIT_V(8); PG8_WAIT_L(0); PG8_BAR; PG8_MMA(0, 0, At, B0); PG8_MMA(0, 1, At, B1); PG8_BAR; PG8_SCHED;
;             PG8_LDA(At, 0, 1); PG8_STAGE(PG8_SB(0, 0), b2, voffB); PG8_STAGE(PG8_SB(0, 1), b2 + hstepB, voffB); PG8_STAGE(PG8_SA(0, 0), a2, voffA);
;             PG8_WAIT_V(8); PG8_WAIT_L(0); PG8_BAR; PG8_MMA(1, 0, At, B0); PG8_MMA(1, 1, At, B1); PG8_BAR; PG8_SCHED;
.LBB0_359:
	s_add_u32 s52, s42, s3
	s_addc_u32 s53, s43, 0
	s_add_u32 s48, s52, 0x100
	s_addc_u32 s49, s53, 0
	s_and_b64 s[46:47], s[44:45], exec
	s_cselect_b32 s49, s2, s49
	s_cselect_b32 s48, s31, s48
	s_add_u32 s3, s40, s3
	s_addc_u32 s46, s41, 0
	s_add_u32 s3, s3, 0x100
	s_addc_u32 s46, s46, 0
	s_and_b64 s[44:45], s[44:45], exec
	s_cselect_b32 s51, s29, s46
	s_cselect_b32 s50, s77, s3
	s_add_u32 s54, s52, 0x80080
	ds_read_b128 v[140:143], v149
	ds_read_b128 v[164:167], v149 offset:1024
	ds_read_b128 v[168:171], v149 offset:2048
	ds_read_b128 v[172:175], v149 offset:3072
	ds_read_b128 v[176:179], v150
	ds_read_b128 v[180:183], v150 offset:1024
	ds_read_b128 v[184:187], v150 offset:2048
	ds_read_b128 v[188:191], v150 offset:3072
	s_addc_u32 s55, s53, 0
	s_add_i32 s82, s68, s60
	s_add_i32 m0, s61, 0xc000
	s_add_i32 s85, s61, 0xe000
	s_add_i32 s79, s82, 0x2000
	s_add_u32 s52, s50, 0x10000
	s_addc_u32 s53, s51, 0
	s_add_i32 s81, s69, s60
	s_add_i32 s80, s81, 0x2000
	s_add_i32 s78, 0, 0x18000
	s_add_i32 s73, 0, 0x1c000
	s_add_u32 s46, s48, 0x80000
	s_addc_u32 s47, s49, 0
	s_add_i32 s72, s78, s60
	s_add_i32 s3, s72, 0x2000
	s_add_u32 s44, s50, 0x10080
	s_addc_u32 s45, s51, 0
	s_add_i32 s84, s73, s60
	s_add_i32 s83, s84, 0x2000
	ds_read_b128 v[192:195], v151
	ds_read_b128 v[196:199], v151 offset:1024
	ds_read_b128 v[200:203], v151 offset:2048
	ds_read_b128 v[204:207], v151 offset:3072
	ds_read_b128 v[208:211], v151 offset:4096
	ds_read_b128 v[212:215], v151 offset:5120
	ds_read_b128 v[216:219], v151 offset:6144
	ds_read_b128 v[224:227], v151 offset:7168
	global_load_lds_dwordx4 v128, s[54:55]
	s_mov_b32 m0, s85
	s_nop 0
	global_load_lds_dwordx4 v130, s[54:55]
	s_waitcnt vmcnt(8)
	s_waitcnt lgkmcnt(0)
	s_barrier
	s_setprio 1
	v_mfma_f32_16x16x32_bf16 v[124:127], v[140:143], v[192:195], v[124:127]
	v_mfma_f32_16x16x32_bf16 v[120:123], v[168:171], v[192:195], v[120:123]
	v_mfma_f32_16x16x32_bf16 v[108:111], v[140:143], v[200:203], v[108:111]
	v_mfma_f32_16x16x32_bf16 v[104:107], v[168:171], v[200:203], v[104:107]
	v_mfma_f32_16x16x32_bf16 v[92:95], v[140:143], v[208:211], v[92:95]
	v_mfma_f32_16x16x32_bf16 v[88:91], v[168:171], v[208:211], v[88:91]
	v_mfma_f32_16x16x32_bf16 v[84:87], v[140:143], v[216:219], v[84:87]
	v_mfma_f32_16x16x32_bf16 v[72:75], v[168:171], v[216:219], v[72:75]
	v_mfma_f32_16x16x32_bf16 v[124:127], v[164:167], v[196:199], v[124:127]
	v_mfma_f32_16x16x32_bf16 v[120:123], v[172:175], v[196:199], v[120:123]
	v_mfma_f32_16x16x32_bf16 v[108:111], v[164:167], v[204:207], v[108:111]
	v_mfma_f32_16x16x32_bf16 v[104:107], v[172:175], v[204:207], v[104:107]
	v_mfma_f32_16x16x32_bf16 v[92:95], v[164:167], v[212:215], v[92:95]
	v_mfma_f32_16x16x32_bf16 v[88:91], v[172:175], v[212:215], v[88:91]
	v_mfma_f32_16x16x32_bf16 v[84:87], v[164:167], v[224:227], v[84:87]
	v_mfma_f32_16x16x32_bf16 v[72:75], v[172:175], v[224:227], v[72:75]
	s_setprio 0
	s_setprio 1
	v_mfma_f32_16x16x32_bf16 v[116:119], v[176:179], v[192:195], v[116:119]
	v_mfma_f32_16x16x32_bf16 v[112:115], v[184:187], v[192:195], v[112:115]
	v_mfma_f32_16x16x32_bf16 v[100:103], v[176:179], v[200:203], v[100:103]
	v_mfma_f32_16x16x32_bf16 v[96:99], v[184:187], v[200:203], v[96:99]
	v_mfma_f32_16x16x32_bf16 v[80:83], v[176:179], v[208:211], v[80:83]
	v_mfma_f32_16x16x32_bf16 v[76:79], v[184:187], v[208:211], v[76:79]
	v_mfma_f32_16x16x32_bf16 v[68:71], v[176:179], v[216:219], v[68:71]
	v_mfma_f32_16x16x32_bf16 v[64:67], v[184:187], v[216:219], v[64:67]
	v_mfma_f32_16x16x32_bf16 v[116:119], v[180:183], v[196:199], v[116:119]
	v_mfma_f32_16x16x32_bf16 v[112:115], v[188:191], v[196:199], v[112:115]
	v_mfma_f32_16x16x32_bf16 v[100:103], v[180:183], v[204:207], v[100:103]
	v_mfma_f32_16x16x32_bf16 v[96:99], v[188:191], v[204:207], v[96:99]
	v_mfma_f32_16x16x32_bf16 v[80:83], v[180:183], v[212:215], v[80:83]
	v_mfma_f32_16x16x32_bf16 v[76:79], v[188:191], v[212:215], v[76:79]
	v_mfma_f32_16x16x32_bf16 v[68:71], v[180:183], v[224:227], v[68:71]
	v_mfma_f32_16x16x32_bf16 v[64:67], v[188:191], v[224:227], v[64:67]
	s_setprio 0
	s_barrier
	s_mov_b32 m0, s82
	s_add_u32 s98, s50, s18
	s_addc_u32 s99, s51, s19
	ds_read_b128 v[192:195], v151 offset:16384
	ds_read_b128 v[196:199], v151 offset:17408
	ds_read_b128 v[200:203], v151 offset:18432
	ds_read_b128 v[204:207], v151 offset:19456
	ds_read_b128 v[208:211], v151 offset:20480
	ds_read_b128 v[212:215], v151 offset:21504
	ds_read_b128 v[216:219], v151 offset:22528
	ds_read_b128 v[224:227], v151 offset:23552
	global_load_lds_dwordx4 v132, s[50:51]
	s_mov_b32 m0, s79
	s_nop 0
	global_load_lds_dwordx4 v134, s[50:51]
	s_mov_b32 m0, s81
	s_nop 0
	global_load_lds_dwordx4 v132, s[52:53]
	s_mov_b32 m0, s80
	s_nop 0
	global_load_lds_dwordx4 v134, s[52:53]
	s_add_u32 s100, s48, s18
	s_addc_u32 s101, s49, s19
	s_mov_b32 m0, s61
	s_nop 0
	global_load_lds_dwordx4 v128, s[48:49]
	s_mov_b32 m0, s62
	s_nop 0
	global_load_lds_dwordx4 v130, s[48:49]
	s_waitcnt vmcnt(8)
	s_waitcnt lgkmcnt(0)
	s_barrier
; #define PG8_STAGE(bufoff, gbase, voff) do { _Pragma("unroll") for (int _i = 0; _i < 2; ++_i) \
;         __builtin_amdgcn_global_load_lds((const unsigned*)((const char*)(gbase) + (voff)[_i]), (LAS unsigned*)(lds + (bufoff) + ldsw + _i * 8192), 16, 0, 0); } while (0)
; #define PG8_LDA(dst, b, h) do { _Pragma("unroll") for (int m = 0; m < 4; ++m) _Pragma("unroll") for (int k = 0; k < 2; ++k) dst[m][k] = *(const LAS bf16x8*)(lds + PG8_SA(b, h) + aoff + m * 2048 + k * 1024); } while (0)
; #define PG8_LDB(dst, b, h) do { _Pragma("unroll") for (int n = 0; n < 2; ++n) _Pragma("unroll") for (int k = 0; k < 2; ++k) dst[n][k] = *(const LAS bf16x8*)(lds + PG8_SB(b, h) + boff + n * 2048 + k * 1024); } while (0)
; #define PG8_MMA(ai, bj, At, Bt) do { __builtin_amdgcn_s_setprio(1); _Pragma("unroll") for (int m = 0; m < 4; ++m) _Pragma("unroll") for (int n = 0; n < 2; ++n) _Pragma("unroll") for (int k = 0; k < 2; ++k) \
;         acc[ai][bj][m][n] = __builtin_amdgcn_mfma_f32_16x16x32_bf16(Bt[n][k], At[m][k], acc[ai][bj][m][n], 0, 0, 0); __builtin_amdgcn_s_setprio(0); } while (0)
; #define PG8_WAIT_V(n) asm volatile("s_waitcnt vmcnt(" #n ")" ::: "memory")
; #define PG8_WAIT_L(n) asm volatile("s_waitcnt lgkmcnt(" #n ")" ::: "memory")
; #define PG8_BAR __builtin_amdgcn_s_barrier()
; #define PG8_SCHED __builtin_amdgcn_sched_barrier(0)
; template <class Epi, class Sched, bool SP2 = PG8_SP2>
; __device__ __forceinline__ void gemm_phase(LAS unsigned char* lds, const Gemm g, const Sched& S, const Epi& E) {
;     ...
;             PG8_WAIT_V(8); PG8_WAIT_L(0); PG8_BAR; PG8_MMA(1, 0, At, B0); PG8_MMA(1, 1, At, B1); PG8_BAR; PG8_SCHED;
;             PG8_LDB(B0, 1, 0); PG8_LDB(B1, 1, 1); PG8_SCHED; PG8_LDA(At, 1, 0); PG8_STAGE(PG8_SA(0, 1), a2 + hstepA, voffA);
;             PG8_WAIT_V(8); PG8_WAIT_L(0); PG8_BAR; PG8_MMA(0, 0, At, B0); PG8_MMA(0, 1, At, B1); PG8_BAR; PG8_SCHED;
	s_setprio 1
	v_mfma_f32_16x16x32_bf16 v[60:63], v[140:143], v[192:195], v[60:63]
	v_mfma_f32_16x16x32_bf16 v[56:59], v[168:171], v[192:195], v[56:59]
	v_mfma_f32_16x16x32_bf16 v[44:47], v[140:143], v[200:203], v[44:47]
	v_mfma_f32_16x16x32_bf16 v[40:43], v[168:171], v[200:203], v[40:43]
	v_mfma_f32_16x16x32_bf16 v[28:31], v[140:143], v[208:211], v[28:31]
	v_mfma_f32_16x16x32_bf16 v[24:27], v[168:171], v[208:211], v[24:27]
	v_mfma_f32_16x16x32_bf16 v[12:15], v[140:143], v[216:219], v[12:15]
	v_mfma_f32_16x16x32_bf16 v[8:11], v[168:171], v[216:219], v[8:11]
	v_mfma_f32_16x16x32_bf16 v[60:63], v[164:167], v[196:199], v[60:63]
	v_mfma_f32_16x16x32_bf16 v[56:59], v[172:175], v[196:199], v[56:59]
	v_mfma_f32_16x16x32_bf16 v[44:47], v[164:167], v[204:207], v[44:47]
	v_mfma_f32_16x16x32_bf16 v[40:43], v[172:175], v[204:207], v[40:43]
	v_mfma_f32_16x16x32_bf16 v[28:31], v[164:167], v[212:215], v[28:31]
	v_mfma_f32_16x16x32_bf16 v[24:27], v[172:175], v[212:215], v[24:27]
	v_mfma_f32_16x16x32_bf16 v[12:15], v[164:167], v[224:227], v[12:15]
	v_mfma_f32_16x16x32_bf16 v[8:11], v[172:175], v[224:227], v[8:11]
	s_setprio 0
	s_setprio 1
	v_mfma_f32_16x16x32_bf16 v[52:55], v[176:179], v[192:195], v[52:55]
	v_mfma_f32_16x16x32_bf16 v[48:51], v[184:187], v[192:195], v[48:51]
	v_mfma_f32_16x16x32_bf16 v[36:39], v[176:179], v[200:203], v[36:39]
	v_mfma_f32_16x16x32_bf16 v[32:35], v[184:187], v[200:203], v[32:35]
	v_mfma_f32_16x16x32_bf16 v[20:23], v[176:179], v[208:211], v[20:23]
	v_mfma_f32_16x16x32_bf16 v[16:19], v[184:187], v[208:211], v[16:19]
	v_mfma_f32_16x16x32_bf16 v[4:7], v[176:179], v[216:219], v[4:7]
	v_mfma_f32_16x16x32_bf16 v[0:3], v[184:187], v[216:219], v[0:3]
	v_mfma_f32_16x16x32_bf16 v[52:55], v[180:183], v[196:199], v[52:55]
	v_mfma_f32_16x16x32_bf16 v[48:51], v[188:191], v[196:199], v[48:51]
	v_mfma_f32_16x16x32_bf16 v[36:39], v[180:183], v[204:207], v[36:39]
	v_mfma_f32_16x16x32_bf16 v[32:35], v[188:191], v[204:207], v[32:35]
	v_mfma_f32_16x16x32_bf16 v[20:23], v[180:183], v[212:215], v[20:23]
	v_mfma_f32_16x16x32_bf16 v[16:19], v[188:191], v[212:215], v[16:19]
	v_mfma_f32_16x16x32_bf16 v[4:7], v[180:183], v[224:227], v[4:7]
	v_mfma_f32_16x16x32_bf16 v[0:3], v[188:191], v[224:227], v[0:3]
	s_setprio 0
	s_barrier
	v_add_u32_e32 v172, s78, v147
	v_add_u32_e32 v188, s73, v147
	ds_read_b128 v[140:143], v172
	ds_read_b128 v[164:167], v172 offset:1024
	ds_read_b128 v[168:171], v172 offset:2048
	ds_read_b128 v[172:175], v172 offset:3072
	ds_read_b128 v[176:179], v188
	ds_read_b128 v[180:183], v188 offset:1024
	ds_read_b128 v[184:187], v188 offset:2048
	ds_read_b128 v[188:191], v188 offset:3072
	s_mov_b32 m0, s63
	ds_read_b128 v[192:195], v151 offset:32768
	ds_read_b128 v[196:199], v151 offset:33792
	ds_read_b128 v[200:203], v151 offset:34816
	ds_read_b128 v[204:207], v151 offset:35840
	ds_read_b128 v[208:211], v151 offset:36864
	ds_read_b128 v[212:215], v151 offset:37888
	ds_read_b128 v[216:219], v151 offset:38912
	ds_read_b128 v[224:227], v151 offset:39936
	global_load_lds_dwordx4 v128, s[46:47]
	s_mov_b32 m0, s64
	s_nop 0
	global_load_lds_dwordx4 v130, s[46:47]
	s_waitcnt vmcnt(8)
	s_waitcnt lgkmcnt(0)
	s_barrier
	s_setprio 1
	v_mfma_f32_16x16x32_bf16 v[124:127], v[140:143], v[192:195], v[124:127]
	v_mfma_f32_16x16x32_bf16 v[120:123], v[168:171], v[192:195], v[120:123]
	v_mfma_f32_16x16x32_bf16 v[108:111], v[140:143], v[200:203], v[108:111]
	v_mfma_f32_16x16x32_bf16 v[104:107], v[168:171], v[200:203], v[104:107]
	v_mfma_f32_16x16x32_bf16 v[92:95], v[140:143], v[208:211], v[92:95]
	v_mfma_f32_16x16x32_bf16 v[88:91], v[168:171], v[208:211], v[88:91]
	v_mfma_f32_16x16x32_bf16 v[84:87], v[140:143], v[216:219], v[84:87]
	v_mfma_f32_16x16x32_bf16 v[72:75], v[168:171], v[216:219], v[72:75]
	v_mfma_f32_16x16x32_bf16 v[124:127], v[164:167], v[196:199], v[124:127]
	v_mfma_f32_16x16x32_bf16 v[120:123], v[172:175], v[196:199], v[120:123]
	v_mfma_f32_16x16x32_bf16 v[108:111], v[164:167], v[204:207], v[108:111]
	v_mfma_f32_16x16x32_bf16 v[104:107], v[172:175], v[204:207], v[104:107]
	v_mfma_f32_16x16x32_bf16 v[92:95], v[164:167], v[212:215], v[92:95]
	v_mfma_f32_16x16x32_bf16 v[88:91], v[172:175], v[212:215], v[88:91]
	v_mfma_f32_16x16x32_bf16 v[84:87], v[164:167], v[224:227], v[84:87]
	v_mfma_f32_16x16x32_bf16 v[72:75], v[172:175], v[224:227], v[72:75]
	s_setprio 0
	s_setprio 1
	v_mfma_f32_16x16x32_bf16 v[116:119], v[176:179], v[192:195], v[116:119]
	v_mfma_f32_16x16x32_bf16 v[112:115], v[184:187], v[192:195], v[112:115]
	v_mfma_f32_16x16x32_bf16 v[100:103], v[176:179], v[200:203], v[100:103]
	v_mfma_f32_16x16x32_bf16 v[96:99], v[184:187], v[200:203], v[96:99]
	v_mfma_f32_16x16x32_bf16 v[80:83], v[176:179], v[208:211], v[80:83]
	v_mfma_f32_16x16x32_bf16 v[76:79], v[184:187], v[208:211], v[76:79]
	v_mfma_f32_16x16x32_bf16 v[68:71], v[176:179], v[216:219], v[68:71]
	v_mfma_f32_16x16x32_bf16 v[64:67], v[184:187], v[216:219], v[64:67]
	v_mfma_f32_16x16x32_bf16 v[116:119], v[180:183], v[196:199], v[116:119]
	v_mfma_f32_16x16x32_bf16 v[112:115], v[188:191], v[196:199], v[112:115]
	v_mfma_f32_16x16x32_bf16 v[100:103], v[180:183], v[204:207], v[100:103]
	v_mfma_f32_16x16x32_bf16 v[96:99], v[188:191], v[204:207], v[96:99]
	v_mfma_f32_16x16x32_bf16 v[80:83], v[180:183], v[212:215], v[80:83]
	v_mfma_f32_16x16x32_bf16 v[76:79], v[188:191], v[212:215], v[76:79]
	v_mfma_f32_16x16x32_bf16 v[68:71], v[180:183], v[224:227], v[68:71]
	v_mfma_f32_16x16x32_bf16 v[64:67], v[188:191], v[224:227], v[64:67]
	s_setprio 0
	s_barrier
; #define PG8_STAGE(bufoff, gbase, voff) do { _Pragma("unroll") for (int _i = 0; _i < 2; ++_i) \
;         __builtin_amdgcn_global_load_lds((const unsigned*)((const char*)(gbase) + (voff)[_i]), (LAS unsigned*)(lds + (bufoff) + ldsw + _i * 8192), 16, 0, 0); } while (0)
; #define PG8_LDA(dst, b, h) do { _Pragma("unroll") for (int m = 0; m < 4; ++m) _Pragma("unroll") for (int k = 0; k < 2; ++k) dst[m][k] = *(const LAS bf16x8*)(lds + PG8_SA(b, h) + aoff + m * 2048 + k * 1024); } while (0)
; #define PG8_MMA(ai, bj, At, Bt) do { __builtin_amdgcn_s_setprio(1); _Pragma("unroll") for (int m = 0; m < 4; ++m) _Pragma("unroll") for (int n = 0; n < 2; ++n) _Pragma("unroll") for (int k = 0; k < 2; ++k) \
;         acc[ai][bj][m][n] = __builtin_amdgcn_mfma_f32_16x16x32_bf16(Bt[n][k], At[m][k], acc[ai][bj][m][n], 0, 0, 0); __builtin_amdgcn_s_setprio(0); } while (0)
; #define PG8_WAIT_V(n) asm volatile("s_waitcnt vmcnt(" #n ")" ::: "memory")
; #define PG8_WAIT_L(n) asm volatile("s_waitcnt lgkmcnt(" #n ")" ::: "memory")
; #define PG8_BAR __builtin_amdgcn_s_barrier()
; #define PG8_SCHED __builtin_amdgcn_sched_barrier(0)
; template <class Epi, class Sched, bool SP2 = PG8_SP2>
; __device__ __forceinline__ void gemm_phase(LAS unsigned char* lds, const Gemm g, const Sched& S, const Epi& E) {
;     ...
;             PG8_LDA(At, 1, 1); PG8_STAGE(PG8_SB(1, 0), b3, voffB); PG8_STAGE(PG8_SB(1, 1), b3 + hstepB, voffB); PG8_STAGE(PG8_SA(1, 0), a3, voffA);
;             PG8_WAIT_V(8); PG8_WAIT_L(0); PG8_BAR; PG8_MMA(1, 0, At, B0); PG8_MMA(1, 1, At, B1); PG8_BAR; PG8_SCHED;
;     ...
;         if (wr == 0) PG8_BAR;
	s_mov_b32 m0, s72
	ds_read_b128 v[192:195], v151 offset:49152
	ds_read_b128 v[196:199], v151 offset:50176
	ds_read_b128 v[200:203], v151 offset:51200
	ds_read_b128 v[204:207], v151 offset:52224
	ds_read_b128 v[208:211], v151 offset:53248
	ds_read_b128 v[212:215], v151 offset:54272
	ds_read_b128 v[216:219], v151 offset:55296
	ds_read_b128 v[224:227], v151 offset:56320
	global_load_lds_dwordx4 v132, s[98:99]
	s_mov_b32 m0, s3
	s_nop 0
	global_load_lds_dwordx4 v134, s[98:99]
	s_mov_b32 m0, s84
	s_nop 0
	global_load_lds_dwordx4 v132, s[44:45]
	s_mov_b32 m0, s83
	s_nop 0
	global_load_lds_dwordx4 v134, s[44:45]
	s_mov_b32 m0, s66
	s_nop 0
	global_load_lds_dwordx4 v128, s[100:101]
	s_mov_b32 m0, s67
	s_nop 0
	global_load_lds_dwordx4 v130, s[100:101]
	s_waitcnt vmcnt(8)
	s_waitcnt lgkmcnt(0)
	s_barrier
	s_setprio 1
	v_mfma_f32_16x16x32_bf16 v[60:63], v[140:143], v[192:195], v[60:63]
	v_mfma_f32_16x16x32_bf16 v[56:59], v[168:171], v[192:195], v[56:59]
	v_mfma_f32_16x16x32_bf16 v[44:47], v[140:143], v[200:203], v[44:47]
	v_mfma_f32_16x16x32_bf16 v[40:43], v[168:171], v[200:203], v[40:43]
	v_mfma_f32_16x16x32_bf16 v[28:31], v[140:143], v[208:211], v[28:31]
	v_mfma_f32_16x16x32_bf16 v[24:27], v[168:171], v[208:211], v[24:27]
	v_mfma_f32_16x16x32_bf16 v[12:15], v[140:143], v[216:219], v[12:15]
	v_mfma_f32_16x16x32_bf16 v[8:11], v[168:171], v[216:219], v[8:11]
	v_mfma_f32_16x16x32_bf16 v[60:63], v[164:167], v[196:199], v[60:63]
	v_mfma_f32_16x16x32_bf16 v[56:59], v[172:175], v[196:199], v[56:59]
	v_mfma_f32_16x16x32_bf16 v[44:47], v[164:167], v[204:207], v[44:47]
	v_mfma_f32_16x16x32_bf16 v[40:43], v[172:175], v[204:207], v[40:43]
	v_mfma_f32_16x16x32_bf16 v[28:31], v[164:167], v[212:215], v[28:31]
	v_mfma_f32_16x16x32_bf16 v[24:27], v[172:175], v[212:215], v[24:27]
	v_mfma_f32_16x16x32_bf16 v[12:15], v[164:167], v[224:227], v[12:15]
	v_mfma_f32_16x16x32_bf16 v[8:11], v[172:175], v[224:227], v[8:11]
	s_setprio 0
	s_setprio 1
	v_mfma_f32_16x16x32_bf16 v[52:55], v[176:179], v[192:195], v[52:55]
	v_mfma_f32_16x16x32_bf16 v[48:51], v[184:187], v[192:195], v[48:51]
	v_mfma_f32_16x16x32_bf16 v[36:39], v[176:179], v[200:203], v[36:39]
	v_mfma_f32_16x16x32_bf16 v[32:35], v[184:187], v[200:203], v[32:35]
	v_mfma_f32_16x16x32_bf16 v[20:23], v[176:179], v[208:211], v[20:23]
	v_mfma_f32_16x16x32_bf16 v[16:19], v[184:187], v[208:211], v[16:19]
	v_mfma_f32_16x16x32_bf16 v[4:7], v[176:179], v[216:219], v[4:7]
	v_mfma_f32_16x16x32_bf16 v[0:3], v[184:187], v[216:219], v[0:3]
	v_mfma_f32_16x16x32_bf16 v[52:55], v[180:183], v[196:199], v[52:55]
	v_mfma_f32_16x16x32_bf16 v[48:51], v[188:191], v[196:199], v[48:51]
	v_mfma_f32_16x16x32_bf16 v[36:39], v[180:183], v[204:207], v[36:39]
	v_mfma_f32_16x16x32_bf16 v[32:35], v[188:191], v[204:207], v[32:35]
	v_mfma_f32_16x16x32_bf16 v[20:23], v[180:183], v[212:215], v[20:23]
	v_mfma_f32_16x16x32_bf16 v[16:19], v[188:191], v[212:215], v[16:19]
	v_mfma_f32_16x16x32_bf16 v[4:7], v[180:183], v[224:227], v[4:7]
	v_mfma_f32_16x16x32_bf16 v[0:3], v[188:191], v[224:227], v[0:3]
	s_setprio 0
	s_barrier
	s_movk_i32 s3, 0x100
	s_andn2_b64 vcc, exec, s[0:1]
	s_mov_b64 s[44:45], -1
	s_mov_b64 s[0:1], 0
	s_cbranch_vccz .LBB0_359
	s_and_b64 vcc, exec, s[20:21]
	s_cbranch_vccz .LBB0_362
	s_barrier

; #define PG8_STAGE(bufoff, gbase, voff) do { _Pragma("unroll") for (int _i = 0; _i < 2; ++_i) \
;         __builtin_amdgcn_global_load_lds((const unsigned*)((const char*)(gbase) + (voff)[_i]), (LAS unsigned*)(lds + (bufoff) + ldsw + _i * 8192), 16, 0, 0); } while (0)
; #define PG8_LDA(dst, b, h) do { _Pragma("unroll") for (int m = 0; m < 4; ++m) _Pragma("unroll") for (int k = 0; k < 2; ++k) dst[m][k] = *(const LAS bf16x8*)(lds + PG8_SA(b, h) + aoff + m * 2048 + k * 1024); } while (0)
; #define PG8_LDB(dst, b, h) do { _Pragma("unroll") for (int n = 0; n < 2; ++n) _Pragma("unroll") for (int k = 0; k < 2; ++k) dst[n][k] = *(const LAS bf16x8*)(lds + PG8_SB(b, h) + boff + n * 2048 + k * 1024); } while (0)
; #define PG8_MMA(ai, bj, At, Bt) do { __builtin_amdgcn_s_setprio(1); _Pragma("unroll") for (int m = 0; m < 4; ++m) _Pragma("unroll") for (int n = 0; n < 2; ++n) _Pragma("unroll") for (int k = 0; k < 2; ++k) \
;         acc[ai][bj][m][n] = __builtin_amdgcn_mfma_f32_16x16x32_bf16(Bt[n][k], At[m][k], acc[ai][bj][m][n], 0, 0, 0); __builtin_amdgcn_s_setprio(0); } while (0)
; #define PG8_WAIT_V(n) asm volatile("s_waitcnt vmcnt(" #n ")" ::: "memory")
; #define PG8_WAIT_L(n) asm volatile("s_waitcnt lgkmcnt(" #n ")" ::: "memory")
; #define PG8_BAR __builtin_amdgcn_s_barrier()
; template <class Epi, class Sched, bool SP2 = PG8_SP2>
; __device__ __forceinline__ void gemm_phase(LAS unsigned char* lds, const Gemm g, const Sched& S, const Epi& E) {
;     ...
;         for (int t = 0; t < nt; t += 2) {
;             const bool last = (t == nt - 2);
;             const char* a1 = cA + (size_t)(t + 1) * kstep;
;             const char* a2 = last ? nA : cA + (size_t)(t + 2) * kstep; const char* b2 = last ? nB : cB + (size_t)(t + 2) * kstep;
;             const char* a3 = a2 + kstep; const char* b3 = b2 + kstep;
;             if constexpr (SP2) {
;             PG8_LDB(B0, 0, 0); PG8_LDB(B1, 0, 1); PG8_SCHED; PG8_LDA(At, 0, 0); PG8_STAGE(PG8_SA(1, 1), a1 + hstepA, voffA);
;             PG8_WAIT_V(8); PG8_WAIT_L(0); PG8_BAR; PG8_MMA(0, 0, At, B0); PG8_MMA(0, 1, At, B1); PG8_BAR; PG8_SCHED;
;             PG8_LDA(At, 0, 1); PG8_STAGE(PG8_SB(0, 0), b2, voffB); PG8_STAGE(PG8_SB(0, 1), b2 + hstepB, voffB); PG8_STAGE(PG8_SA(0, 0), a2, voffA);
;             PG8_WAIT_V(8); PG8_WAIT_L(0); PG8_BAR; PG8_MMA(1, 0, At, B0); PG8_MMA(1, 1, At, B1); PG8_BAR; PG8_SCHED;
.LBB0_395:
	ds_read_b128 v[152:155], v149
	ds_read_b128 v[156:159], v149 offset:1024
	ds_read_b128 v[160:163], v149 offset:2048
	ds_read_b128 v[164:167], v149 offset:3072
	ds_read_b128 v[168:171], v150
	ds_read_b128 v[172:175], v150 offset:1024
	ds_read_b128 v[176:179], v150 offset:2048
	ds_read_b128 v[180:183], v150 offset:3072
	s_add_u32 s3, s0, 0xfffe0080
	s_addc_u32 s36, s1, -1
	s_cmp_eq_u32 s62, 4
	s_cselect_b32 s39, s2, s36
	s_cselect_b32 s38, s27, s3
	s_cselect_b32 s37, s25, s61
	s_cselect_b32 s36, s59, s60
	s_add_i32 m0, s35, 0xc000
	ds_read_b128 v[184:187], v151
	ds_read_b128 v[188:191], v151 offset:1024
	ds_read_b128 v[192:195], v151 offset:2048
	ds_read_b128 v[196:199], v151 offset:3072
	ds_read_b128 v[200:203], v151 offset:4096
	ds_read_b128 v[204:207], v151 offset:5120
	ds_read_b128 v[208:211], v151 offset:6144
	ds_read_b128 v[212:215], v151 offset:7168
	global_load_lds_dwordx4 v136, s[0:1]
	s_add_i32 m0, s35, 0xe000
	s_nop 0
	global_load_lds_dwordx4 v138, s[0:1]
	s_waitcnt vmcnt(8)
	s_waitcnt lgkmcnt(0)
	s_barrier
	s_setprio 1
	v_mfma_f32_16x16x32_bf16 v[124:127], v[152:155], v[184:187], v[124:127]
	v_mfma_f32_16x16x32_bf16 v[120:123], v[160:163], v[184:187], v[120:123]
	v_mfma_f32_16x16x32_bf16 v[116:119], v[152:155], v[192:195], v[116:119]
	v_mfma_f32_16x16x32_bf16 v[108:111], v[160:163], v[192:195], v[108:111]
	v_mfma_f32_16x16x32_bf16 v[100:103], v[152:155], v[200:203], v[100:103]
	v_mfma_f32_16x16x32_bf16 v[92:95], v[160:163], v[200:203], v[92:95]
	v_mfma_f32_16x16x32_bf16 v[84:87], v[152:155], v[208:211], v[84:87]
	v_mfma_f32_16x16x32_bf16 v[76:79], v[160:163], v[208:211], v[76:79]
	v_mfma_f32_16x16x32_bf16 v[124:127], v[156:159], v[188:191], v[124:127]
	v_mfma_f32_16x16x32_bf16 v[120:123], v[164:167], v[188:191], v[120:123]
	v_mfma_f32_16x16x32_bf16 v[116:119], v[156:159], v[196:199], v[116:119]
	v_mfma_f32_16x16x32_bf16 v[108:111], v[164:167], v[196:199], v[108:111]
	v_mfma_f32_16x16x32_bf16 v[100:103], v[156:159], v[204:207], v[100:103]
	v_mfma_f32_16x16x32_bf16 v[92:95], v[164:167], v[204:207], v[92:95]
	v_mfma_f32_16x16x32_bf16 v[84:87], v[156:159], v[212:215], v[84:87]
	v_mfma_f32_16x16x32_bf16 v[76:79], v[164:167], v[212:215], v[76:79]
	s_setprio 0
	s_setprio 1
	v_mfma_f32_16x16x32_bf16 v[112:115], v[168:171], v[184:187], v[112:115]
	v_mfma_f32_16x16x32_bf16 v[104:107], v[176:179], v[184:187], v[104:107]
	v_mfma_f32_16x16x32_bf16 v[96:99], v[168:171], v[192:195], v[96:99]
	v_mfma_f32_16x16x32_bf16 v[88:91], v[176:179], v[192:195], v[88:91]
	v_mfma_f32_16x16x32_bf16 v[80:83], v[168:171], v[200:203], v[80:83]
	v_mfma_f32_16x16x32_bf16 v[72:75], v[176:179], v[200:203], v[72:75]
	v_mfma_f32_16x16x32_bf16 v[68:71], v[168:171], v[208:211], v[68:71]
	v_mfma_f32_16x16x32_bf16 v[64:67], v[176:179], v[208:211], v[64:67]
	v_mfma_f32_16x16x32_bf16 v[112:115], v[172:175], v[188:191], v[112:115]
	v_mfma_f32_16x16x32_bf16 v[104:107], v[180:183], v[188:191], v[104:107]
	v_mfma_f32_16x16x32_bf16 v[96:99], v[172:175], v[196:199], v[96:99]
	v_mfma_f32_16x16x32_bf16 v[88:91], v[180:183], v[196:199], v[88:91]
	v_mfma_f32_16x16x32_bf16 v[80:83], v[172:175], v[204:207], v[80:83]
	v_mfma_f32_16x16x32_bf16 v[72:75], v[180:183], v[204:207], v[72:75]
	v_mfma_f32_16x16x32_bf16 v[68:71], v[172:175], v[212:215], v[68:71]
	v_mfma_f32_16x16x32_bf16 v[64:67], v[180:183], v[212:215], v[64:67]
	s_setprio 0
	s_barrier
	s_add_i32 s3, s52, s44
	s_add_u32 s98, s36, s12
	s_addc_u32 s99, s37, s13
	s_mov_b32 m0, s3
	ds_read_b128 v[184:187], v151 offset:16384
	ds_read_b128 v[188:191], v151 offset:17408
	ds_read_b128 v[192:195], v151 offset:18432
	ds_read_b128 v[196:199], v151 offset:19456
	ds_read_b128 v[200:203], v151 offset:20480
	ds_read_b128 v[204:207], v151 offset:21504
	ds_read_b128 v[208:211], v151 offset:22528
	ds_read_b128 v[212:215], v151 offset:23552
	global_load_lds_dwordx4 v130, s[36:37]
	s_add_i32 m0, s3, 0x2000
	s_add_u32 s64, s36, 0x20000
	s_addc_u32 s65, s37, 0
	s_add_i32 s3, s53, s44
	global_load_lds_dwordx4 v134, s[36:37]
	s_mov_b32 m0, s3
	s_nop 0
	global_load_lds_dwordx4 v130, s[64:65]
	s_add_i32 m0, s3, 0x2000
	s_nop 0
	global_load_lds_dwordx4 v134, s[64:65]
	s_add_u32 s100, s38, s12
	s_addc_u32 s101, s39, s13
	s_mov_b32 m0, s35
	s_nop 0
	global_load_lds_dwordx4 v128, s[38:39]
	s_mov_b32 m0, s45
	s_nop 0
	global_load_lds_dwordx4 v132, s[38:39]
	s_waitcnt vmcnt(8)
	s_waitcnt lgkmcnt(0)
	s_barrier
	s_setprio 1
	v_mfma_f32_16x16x32_bf16 v[60:63], v[152:155], v[184:187], v[60:63]
	v_mfma_f32_16x16x32_bf16 v[56:59], v[160:163], v[184:187], v[56:59]
	v_mfma_f32_16x16x32_bf16 v[52:55], v[152:155], v[192:195], v[52:55]
	v_mfma_f32_16x16x32_bf16 v[44:47], v[160:163], v[192:195], v[44:47]
	v_mfma_f32_16x16x32_bf16 v[36:39], v[152:155], v[200:203], v[36:39]
	v_mfma_f32_16x16x32_bf16 v[28:31], v[160:163], v[200:203], v[28:31]
	v_mfma_f32_16x16x32_bf16 v[20:23], v[152:155], v[208:211], v[20:23]
	v_mfma_f32_16x16x32_bf16 v[12:15], v[160:163], v[208:211], v[12:15]
	v_mfma_f32_16x16x32_bf16 v[60:63], v[156:159], v[188:191], v[60:63]
	v_mfma_f32_16x16x32_bf16 v[56:59], v[164:167], v[188:191], v[56:59]
	v_mfma_f32_16x16x32_bf16 v[52:55], v[156:159], v[196:199], v[52:55]
	v_mfma_f32_16x16x32_bf16 v[44:47], v[164:167], v[196:199], v[44:47]
	v_mfma_f32_16x16x32_bf16 v[36:39], v[156:159], v[204:207], v[36:39]
	v_mfma_f32_16x16x32_bf16 v[28:31], v[164:167], v[204:207], v[28:31]
	v_mfma_f32_16x16x32_bf16 v[20:23], v[156:159], v[212:215], v[20:23]
	v_mfma_f32_16x16x32_bf16 v[12:15], v[164:167], v[212:215], v[12:15]
	s_setprio 0
	s_setprio 1
	v_mfma_f32_16x16x32_bf16 v[48:51], v[168:171], v[184:187], v[48:51]
	v_mfma_f32_16x16x32_bf16 v[40:43], v[176:179], v[184:187], v[40:43]
	v_mfma_f32_16x16x32_bf16 v[32:35], v[168:171], v[192:195], v[32:35]
	v_mfma_f32_16x16x32_bf16 v[24:27], v[176:179], v[192:195], v[24:27]
	v_mfma_f32_16x16x32_bf16 v[16:19], v[168:171], v[200:203], v[16:19]
	v_mfma_f32_16x16x32_bf16 v[8:11], v[176:179], v[200:203], v[8:11]
	v_mfma_f32_16x16x32_bf16 v[4:7], v[168:171], v[208:211], v[4:7]
	v_mfma_f32_16x16x32_bf16 v[0:3], v[176:179], v[208:211], v[0:3]
	v_mfma_f32_16x16x32_bf16 v[48:51], v[172:175], v[188:191], v[48:51]
	v_mfma_f32_16x16x32_bf16 v[40:43], v[180:183], v[188:191], v[40:43]
	v_mfma_f32_16x16x32_bf16 v[32:35], v[172:175], v[196:199], v[32:35]
	v_mfma_f32_16x16x32_bf16 v[24:27], v[180:183], v[196:199], v[24:27]
	v_mfma_f32_16x16x32_bf16 v[16:19], v[172:175], v[204:207], v[16:19]
	v_mfma_f32_16x16x32_bf16 v[8:11], v[180:183], v[204:207], v[8:11]
	v_mfma_f32_16x16x32_bf16 v[4:7], v[172:175], v[212:215], v[4:7]
	v_mfma_f32_16x16x32_bf16 v[0:3], v[180:183], v[212:215], v[0:3]
	s_setprio 0
	s_barrier
; #define PG8_STAGE(bufoff, gbase, voff) do { _Pragma("unroll") for (int _i = 0; _i < 2; ++_i) \
;         __builtin_amdgcn_global_load_lds((const unsigned*)((const char*)(gbase) + (voff)[_i]), (LAS unsigned*)(lds + (bufoff) + ldsw + _i * 8192), 16, 0, 0); } while (0)
; #define PG8_WAIT_V(n) asm volatile("s_waitcnt vmcnt(" #n ")" ::: "memory")
; template <class Epi, class Sched, bool SP2 = PG8_SP2>
; __device__ __forceinline__ void gemm_phase(LAS unsigned char* lds, const Gemm g, const Sched& S, const Epi& E) {
;     ...
;             PG8_LDB(B0, 1, 0); PG8_LDB(B1, 1, 1); PG8_SCHED; PG8_LDA(At, 1, 0); PG8_STAGE(PG8_SA(0, 1), a2 + hstepA, voffA);
;             PG8_WAIT_V(8); PG8_WAIT_L(0); PG8_BAR; PG8_MMA(0, 0, At, B0); PG8_MMA(0, 1, At, B1); PG8_BAR; PG8_SCHED;
;             PG8_LDA(At, 1, 1); PG8_STAGE(PG8_SB(1, 0), b3, voffB); PG8_STAGE(PG8_SB(1, 1), b3 + hstepB, voffB); PG8_STAGE(PG8_SA(1, 0), a3, voffA);
;             PG8_WAIT_V(8); PG8_WAIT_L(0); PG8_BAR; PG8_MMA(1, 0, At, B0); PG8_MMA(1, 1, At, B1); PG8_BAR; PG8_SCHED;
;             } else {
;             PG8_LDB(B0, 0, 0); PG8_SCHED; PG8_LDA(At, 0, 0); PG8_STAGE(PG8_SA(1, 1), a1 + hstepA, voffA);
;             PG8_WAIT_L(8); PG8_BAR; PG8_WAIT_L(0); PG8_MMA(0, 0, At, B0); PG8_BAR; PG8_SCHED;
;             PG8_LDB(B1, 0, 1); PG8_STAGE(PG8_SB(0, 0), b2, voffB);
;             PG8_BAR; PG8_WAIT_L(0); PG8_MMA(0, 1, At, B1); PG8_BAR;
;             PG8_LDA(At, 0, 1); PG8_STAGE(PG8_SA(0, 0), a2, voffA);
;             PG8_BAR; PG8_WAIT_L(0); PG8_MMA(1, 0, At, B0); PG8_BAR; PG8_SCHED;
;             PG8_STAGE(PG8_SB(0, 1), b2 + hstepB, voffB);
;             PG8_WAIT_V(6); PG8_BAR; PG8_MMA(1, 1, At, B1); PG8_BAR;
;             PG8_LDB(B0, 1, 0); PG8_SCHED; PG8_LDA(At, 1, 0); PG8_STAGE(PG8_SA(0, 1), a2 + hstepA, voffA);
;             PG8_WAIT_L(8); PG8_BAR; PG8_WAIT_L(0); PG8_MMA(0, 0, At, B0); PG8_BAR; PG8_SCHED;
;             PG8_LDB(B1, 1, 1); PG8_STAGE(PG8_SB(1, 0), b3, voffB);
;             PG8_BAR; PG8_WAIT_L(0); PG8_MMA(0, 1, At, B1); PG8_BAR;
;             PG8_LDA(At, 1, 1); PG8_STAGE(PG8_SA(1, 0), a3, voffA);
;             PG8_BAR; PG8_WAIT_L(0); PG8_MMA(1, 0, At, B0); PG8_BAR; PG8_SCHED;
;             PG8_STAGE(PG8_SB(1, 1), b3 + hstepB, voffB);
;             PG8_WAIT_V(6); PG8_BAR; PG8_MMA(1, 1, At, B1); PG8_BAR;
;             }
;         }
;         if (wr == 0) PG8_BAR;
	s_add_i32 s3, 0, 0x18000
	s_add_i32 s63, 0, 0x1c000
	v_add_u32_e32 v164, s3, v147
	v_add_u32_e32 v180, s63, v147
	ds_read_b128 v[152:155], v164
	ds_read_b128 v[156:159], v164 offset:1024
	ds_read_b128 v[160:163], v164 offset:2048
	ds_read_b128 v[164:167], v164 offset:3072
	ds_read_b128 v[168:171], v180
	ds_read_b128 v[172:175], v180 offset:1024
	ds_read_b128 v[176:179], v180 offset:2048
	ds_read_b128 v[180:183], v180 offset:3072
	s_add_u32 s38, s38, 0x20000
	s_addc_u32 s39, s39, 0
	s_mov_b32 m0, s46
	ds_read_b128 v[184:187], v151 offset:32768
	ds_read_b128 v[188:191], v151 offset:33792
	ds_read_b128 v[192:195], v151 offset:34816
	ds_read_b128 v[196:199], v151 offset:35840
	ds_read_b128 v[200:203], v151 offset:36864
	ds_read_b128 v[204:207], v151 offset:37888
	ds_read_b128 v[208:211], v151 offset:38912
	ds_read_b128 v[212:215], v151 offset:39936
	global_load_lds_dwordx4 v128, s[38:39]
	s_mov_b32 m0, s47
	s_nop 0
	global_load_lds_dwordx4 v132, s[38:39]
	s_waitcnt vmcnt(8)
	s_waitcnt lgkmcnt(0)
	s_barrier
	s_setprio 1
	v_mfma_f32_16x16x32_bf16 v[124:127], v[152:155], v[184:187], v[124:127]
	v_mfma_f32_16x16x32_bf16 v[120:123], v[160:163], v[184:187], v[120:123]
	v_mfma_f32_16x16x32_bf16 v[116:119], v[152:155], v[192:195], v[116:119]
	v_mfma_f32_16x16x32_bf16 v[108:111], v[160:163], v[192:195], v[108:111]
	v_mfma_f32_16x16x32_bf16 v[100:103], v[152:155], v[200:203], v[100:103]
	v_mfma_f32_16x16x32_bf16 v[92:95], v[160:163], v[200:203], v[92:95]
	v_mfma_f32_16x16x32_bf16 v[84:87], v[152:155], v[208:211], v[84:87]
	v_mfma_f32_16x16x32_bf16 v[76:79], v[160:163], v[208:211], v[76:79]
	v_mfma_f32_16x16x32_bf16 v[124:127], v[156:159], v[188:191], v[124:127]
	v_mfma_f32_16x16x32_bf16 v[120:123], v[164:167], v[188:191], v[120:123]
	v_mfma_f32_16x16x32_bf16 v[116:119], v[156:159], v[196:199], v[116:119]
	v_mfma_f32_16x16x32_bf16 v[108:111], v[164:167], v[196:199], v[108:111]
	v_mfma_f32_16x16x32_bf16 v[100:103], v[156:159], v[204:207], v[100:103]
	v_mfma_f32_16x16x32_bf16 v[92:95], v[164:167], v[204:207], v[92:95]
	v_mfma_f32_16x16x32_bf16 v[84:87], v[156:159], v[212:215], v[84:87]
	v_mfma_f32_16x16x32_bf16 v[76:79], v[164:167], v[212:215], v[76:79]
	s_setprio 0
	s_setprio 1
	v_mfma_f32_16x16x32_bf16 v[112:115], v[168:171], v[184:187], v[112:115]
	v_mfma_f32_16x16x32_bf16 v[104:107], v[176:179], v[184:187], v[104:107]
	v_mfma_f32_16x16x32_bf16 v[96:99], v[168:171], v[192:195], v[96:99]
	v_mfma_f32_16x16x32_bf16 v[88:91], v[176:179], v[192:195], v[88:91]
	v_mfma_f32_16x16x32_bf16 v[80:83], v[168:171], v[200:203], v[80:83]
	v_mfma_f32_16x16x32_bf16 v[72:75], v[176:179], v[200:203], v[72:75]
	v_mfma_f32_16x16x32_bf16 v[68:71], v[168:171], v[208:211], v[68:71]
	v_mfma_f32_16x16x32_bf16 v[64:67], v[176:179], v[208:211], v[64:67]
	v_mfma_f32_16x16x32_bf16 v[112:115], v[172:175], v[188:191], v[112:115]
	v_mfma_f32_16x16x32_bf16 v[104:107], v[180:183], v[188:191], v[104:107]
	v_mfma_f32_16x16x32_bf16 v[96:99], v[172:175], v[196:199], v[96:99]
	v_mfma_f32_16x16x32_bf16 v[88:91], v[180:183], v[196:199], v[88:91]
	v_mfma_f32_16x16x32_bf16 v[80:83], v[172:175], v[204:207], v[80:83]
	v_mfma_f32_16x16x32_bf16 v[72:75], v[180:183], v[204:207], v[72:75]
	v_mfma_f32_16x16x32_bf16 v[68:71], v[172:175], v[212:215], v[68:71]
	v_mfma_f32_16x16x32_bf16 v[64:67], v[180:183], v[212:215], v[64:67]
	s_setprio 0
	s_barrier
	s_add_i32 s3, s3, s44
	s_mov_b32 m0, s3
	ds_read_b128 v[184:187], v151 offset:49152
	ds_read_b128 v[188:191], v151 offset:50176
	ds_read_b128 v[192:195], v151 offset:51200
	ds_read_b128 v[196:199], v151 offset:52224
	ds_read_b128 v[200:203], v151 offset:53248
	ds_read_b128 v[204:207], v151 offset:54272
	ds_read_b128 v[208:211], v151 offset:55296
	ds_read_b128 v[212:215], v151 offset:56320
	global_load_lds_dwordx4 v130, s[98:99]
	s_add_i32 m0, s3, 0x2000
	s_add_u32 s36, s36, 0x20080
	s_addc_u32 s37, s37, 0
	s_add_i32 s3, s63, s44
	global_load_lds_dwordx4 v134, s[98:99]
	s_mov_b32 m0, s3
	s_nop 0
	global_load_lds_dwordx4 v130, s[36:37]
	s_add_i32 m0, s3, 0x2000
	s_nop 0
	global_load_lds_dwordx4 v134, s[36:37]
	s_mov_b32 m0, s49
	s_nop 0
	global_load_lds_dwordx4 v128, s[100:101]
	s_mov_b32 m0, s50
	s_nop 0
	global_load_lds_dwordx4 v132, s[100:101]
	s_waitcnt vmcnt(8)
	s_waitcnt lgkmcnt(0)
	s_barrier
	s_setprio 1
	v_mfma_f32_16x16x32_bf16 v[60:63], v[152:155], v[184:187], v[60:63]
	v_mfma_f32_16x16x32_bf16 v[56:59], v[160:163], v[184:187], v[56:59]
	v_mfma_f32_16x16x32_bf16 v[52:55], v[152:155], v[192:195], v[52:55]
	v_mfma_f32_16x16x32_bf16 v[44:47], v[160:163], v[192:195], v[44:47]
	v_mfma_f32_16x16x32_bf16 v[36:39], v[152:155], v[200:203], v[36:39]
	v_mfma_f32_16x16x32_bf16 v[28:31], v[160:163], v[200:203], v[28:31]
	v_mfma_f32_16x16x32_bf16 v[20:23], v[152:155], v[208:211], v[20:23]
	v_mfma_f32_16x16x32_bf16 v[12:15], v[160:163], v[208:211], v[12:15]
	v_mfma_f32_16x16x32_bf16 v[60:63], v[156:159], v[188:191], v[60:63]
	v_mfma_f32_16x16x32_bf16 v[56:59], v[164:167], v[188:191], v[56:59]
	v_mfma_f32_16x16x32_bf16 v[52:55], v[156:159], v[196:199], v[52:55]
	v_mfma_f32_16x16x32_bf16 v[44:47], v[164:167], v[196:199], v[44:47]
	v_mfma_f32_16x16x32_bf16 v[36:39], v[156:159], v[204:207], v[36:39]
	v_mfma_f32_16x16x32_bf16 v[28:31], v[164:167], v[204:207], v[28:31]
	v_mfma_f32_16x16x32_bf16 v[20:23], v[156:159], v[212:215], v[20:23]
	v_mfma_f32_16x16x32_bf16 v[12:15], v[164:167], v[212:215], v[12:15]
	s_setprio 0
	s_setprio 1
	v_mfma_f32_16x16x32_bf16 v[48:51], v[168:171], v[184:187], v[48:51]
	v_mfma_f32_16x16x32_bf16 v[40:43], v[176:179], v[184:187], v[40:43]
	v_mfma_f32_16x16x32_bf16 v[32:35], v[168:171], v[192:195], v[32:35]
	v_mfma_f32_16x16x32_bf16 v[24:27], v[176:179], v[192:195], v[24:27]
	v_mfma_f32_16x16x32_bf16 v[16:19], v[168:171], v[200:203], v[16:19]
	v_mfma_f32_16x16x32_bf16 v[8:11], v[176:179], v[200:203], v[8:11]
	v_mfma_f32_16x16x32_bf16 v[4:7], v[168:171], v[208:211], v[4:7]
	v_mfma_f32_16x16x32_bf16 v[0:3], v[176:179], v[208:211], v[0:3]
	v_mfma_f32_16x16x32_bf16 v[48:51], v[172:175], v[188:191], v[48:51]
	v_mfma_f32_16x16x32_bf16 v[40:43], v[180:183], v[188:191], v[40:43]
	v_mfma_f32_16x16x32_bf16 v[32:35], v[172:175], v[196:199], v[32:35]
	v_mfma_f32_16x16x32_bf16 v[24:27], v[180:183], v[196:199], v[24:27]
	v_mfma_f32_16x16x32_bf16 v[16:19], v[172:175], v[204:207], v[16:19]
	v_mfma_f32_16x16x32_bf16 v[8:11], v[180:183], v[204:207], v[8:11]
	v_mfma_f32_16x16x32_bf16 v[4:7], v[172:175], v[212:215], v[4:7]
	v_mfma_f32_16x16x32_bf16 v[0:3], v[180:183], v[212:215], v[0:3]
	s_setprio 0
	s_barrier
	s_add_i32 s62, s62, 2
	s_add_u32 s0, s0, 0x100
	s_addc_u32 s1, s1, 0
	s_add_u32 s60, s60, 0x100
	s_addc_u32 s61, s61, 0
	s_cmp_gt_u32 s62, 5
	s_cbranch_scc0 .LBB0_395
	s_and_b64 vcc, exec, s[14:15]
	s_cbranch_vccz .LBB0_398
	s_barrier

; #define PG8_STAGE(bufoff, gbase, voff) do { _Pragma("unroll") for (int _i = 0; _i < 2; ++_i) \
;         __builtin_amdgcn_global_load_lds((const unsigned*)((const char*)(gbase) + (voff)[_i]), (LAS unsigned*)(lds + (bufoff) + ldsw + _i * 8192), 16, 0, 0); } while (0)
; #define PG8_LDA(dst, b, h) do { _Pragma("unroll") for (int m = 0; m < 4; ++m) _Pragma("unroll") for (int k = 0; k < 2; ++k) dst[m][k] = *(const LAS bf16x8*)(lds + PG8_SA(b, h) + aoff + m * 2048 + k * 1024); } while (0)
; #define PG8_LDB(dst, b, h) do { _Pragma("unroll") for (int n = 0; n < 2; ++n) _Pragma("unroll") for (int k = 0; k < 2; ++k) dst[n][k] = *(const LAS bf16x8*)(lds + PG8_SB(b, h) + boff + n * 2048 + k * 1024); } while (0)
; #define PG8_MMA(ai, bj, At, Bt) do { __builtin_amdgcn_s_setprio(1); _Pragma("unroll") for (int m = 0; m < 4; ++m) _Pragma("unroll") for (int n = 0; n < 2; ++n) _Pragma("unroll") for (int k = 0; k < 2; ++k) \
;         acc[ai][bj][m][n] = __builtin_amdgcn_mfma_f32_16x16x32_bf16(Bt[n][k], At[m][k], acc[ai][bj][m][n], 0, 0, 0); __builtin_amdgcn_s_setprio(0); } while (0)
; #define PG8_WAIT_V(n) asm volatile("s_waitcnt vmcnt(" #n ")" ::: "memory")
; #define PG8_WAIT_L(n) asm volatile("s_waitcnt lgkmcnt(" #n ")" ::: "memory")
; #define PG8_BAR __builtin_amdgcn_s_barrier()
; template <class Epi, class Sched, bool SP2 = PG8_SP2>
; __device__ __forceinline__ void gemm_phase(LAS unsigned char* lds, const Gemm g, const Sched& S, const Epi& E) {
;     ...
;         for (int t = 0; t < nt; t += 2) {
;             const bool last = (t == nt - 2);
;             const char* a1 = cA + (size_t)(t + 1) * kstep;
;             const char* a2 = last ? nA : cA + (size_t)(t + 2) * kstep; const char* b2 = last ? nB : cB + (size_t)(t + 2) * kstep;
;             const char* a3 = a2 + kstep; const char* b3 = b2 + kstep;
;             if constexpr (SP2) {
;             PG8_LDB(B0, 0, 0); PG8_LDB(B1, 0, 1); PG8_SCHED; PG8_LDA(At, 0, 0); PG8_STAGE(PG8_SA(1, 1), a1 + hstepA, voffA);
;             PG8_WAIT_V(8); PG8_WAIT_L(0); PG8_BAR; PG8_MMA(0, 0, At, B0); PG8_MMA(0, 1, At, B1); PG8_BAR; PG8_SCHED;
;             PG8_LDA(At, 0, 1); PG8_STAGE(PG8_SB(0, 0), b2, voffB); PG8_STAGE(PG8_SB(0, 1), b2 + hstepB, voffB); PG8_STAGE(PG8_SA(0, 0), a2, voffA);
;             PG8_WAIT_V(8); PG8_WAIT_L(0); PG8_BAR; PG8_MMA(1, 0, At, B0); PG8_MMA(1, 1, At, B1); PG8_BAR; PG8_SCHED;
.LBB0_845:
	ds_read_b128 v[64:67], v167
	ds_read_b128 v[68:71], v167 offset:1024
	ds_read_b128 v[72:75], v167 offset:2048
	ds_read_b128 v[76:79], v167 offset:3072
	ds_read_b128 v[160:163], v168
	ds_read_b128 v[172:175], v168 offset:1024
	ds_read_b128 v[176:179], v168 offset:2048
	ds_read_b128 v[180:183], v168 offset:3072
	s_add_u32 s3, s0, 0xfff80080
	s_addc_u32 s40, s1, -1
	s_cmp_eq_u32 s60, 28
	s_cselect_b32 s43, s2, s40
	s_cselect_b32 s42, s29, s3
	s_cselect_b32 s41, s27, s59
	s_cselect_b32 s40, s57, s58
	s_add_i32 m0, s37, 0xc000
	ds_read_b128 v[184:187], v169
	ds_read_b128 v[188:191], v169 offset:1024
	ds_read_b128 v[192:195], v169 offset:2048
	ds_read_b128 v[196:199], v169 offset:3072
	ds_read_b128 v[200:203], v169 offset:4096
	ds_read_b128 v[204:207], v169 offset:5120
	ds_read_b128 v[208:211], v169 offset:6144
	ds_read_b128 v[212:215], v169 offset:7168
	global_load_lds_dwordx4 v152, s[0:1]
	s_add_i32 m0, s37, 0xe000
	s_nop 0
	global_load_lds_dwordx4 v154, s[0:1]
	s_waitcnt vmcnt(8)
	s_waitcnt lgkmcnt(0)
	s_barrier
	s_setprio 1
	v_mfma_f32_16x16x32_bf16 v[140:143], v[64:67], v[184:187], v[140:143]
	v_mfma_f32_16x16x32_bf16 v[136:139], v[72:75], v[184:187], v[136:139]
	v_mfma_f32_16x16x32_bf16 v[124:127], v[64:67], v[192:195], v[124:127]
	v_mfma_f32_16x16x32_bf16 v[120:123], v[72:75], v[192:195], v[120:123]
	v_mfma_f32_16x16x32_bf16 v[108:111], v[64:67], v[200:203], v[108:111]
	v_mfma_f32_16x16x32_bf16 v[104:107], v[72:75], v[200:203], v[104:107]
	v_mfma_f32_16x16x32_bf16 v[92:95], v[64:67], v[208:211], v[92:95]
	v_mfma_f32_16x16x32_bf16 v[88:91], v[72:75], v[208:211], v[88:91]
	v_mfma_f32_16x16x32_bf16 v[140:143], v[68:71], v[188:191], v[140:143]
	v_mfma_f32_16x16x32_bf16 v[136:139], v[76:79], v[188:191], v[136:139]
	v_mfma_f32_16x16x32_bf16 v[124:127], v[68:71], v[196:199], v[124:127]
	v_mfma_f32_16x16x32_bf16 v[120:123], v[76:79], v[196:199], v[120:123]
	v_mfma_f32_16x16x32_bf16 v[108:111], v[68:71], v[204:207], v[108:111]
	v_mfma_f32_16x16x32_bf16 v[104:107], v[76:79], v[204:207], v[104:107]
	v_mfma_f32_16x16x32_bf16 v[92:95], v[68:71], v[212:215], v[92:95]
	v_mfma_f32_16x16x32_bf16 v[88:91], v[76:79], v[212:215], v[88:91]
	s_setprio 0
	s_setprio 1
	v_mfma_f32_16x16x32_bf16 v[132:135], v[160:163], v[184:187], v[132:135]
	v_mfma_f32_16x16x32_bf16 v[128:131], v[176:179], v[184:187], v[128:131]
	v_mfma_f32_16x16x32_bf16 v[116:119], v[160:163], v[192:195], v[116:119]
	v_mfma_f32_16x16x32_bf16 v[112:115], v[176:179], v[192:195], v[112:115]
	v_mfma_f32_16x16x32_bf16 v[100:103], v[160:163], v[200:203], v[100:103]
	v_mfma_f32_16x16x32_bf16 v[96:99], v[176:179], v[200:203], v[96:99]
	v_mfma_f32_16x16x32_bf16 v[84:87], v[160:163], v[208:211], v[84:87]
	v_mfma_f32_16x16x32_bf16 v[80:83], v[176:179], v[208:211], v[80:83]
	v_mfma_f32_16x16x32_bf16 v[132:135], v[172:175], v[188:191], v[132:135]
	v_mfma_f32_16x16x32_bf16 v[128:131], v[180:183], v[188:191], v[128:131]
	v_mfma_f32_16x16x32_bf16 v[116:119], v[172:175], v[196:199], v[116:119]
	v_mfma_f32_16x16x32_bf16 v[112:115], v[180:183], v[196:199], v[112:115]
	v_mfma_f32_16x16x32_bf16 v[100:103], v[172:175], v[204:207], v[100:103]
	v_mfma_f32_16x16x32_bf16 v[96:99], v[180:183], v[204:207], v[96:99]
	v_mfma_f32_16x16x32_bf16 v[84:87], v[172:175], v[212:215], v[84:87]
	v_mfma_f32_16x16x32_bf16 v[80:83], v[180:183], v[212:215], v[80:83]
	s_setprio 0
	s_barrier
	s_add_i32 s3, s55, s47
	s_add_u32 s98, s40, s22
	s_addc_u32 s99, s41, s23
	s_mov_b32 m0, s3
	ds_read_b128 v[184:187], v169 offset:16384
	ds_read_b128 v[188:191], v169 offset:17408
	ds_read_b128 v[192:195], v169 offset:18432
	ds_read_b128 v[196:199], v169 offset:19456
	ds_read_b128 v[200:203], v169 offset:20480
	ds_read_b128 v[204:207], v169 offset:21504
	ds_read_b128 v[208:211], v169 offset:22528
	ds_read_b128 v[212:215], v169 offset:23552
	global_load_lds_dwordx4 v146, s[40:41]
	s_add_i32 m0, s3, 0x2000
	s_add_u32 s62, s40, 0x80000
	s_addc_u32 s63, s41, 0
	s_add_i32 s3, s56, s47
	global_load_lds_dwordx4 v150, s[40:41]
	s_mov_b32 m0, s3
	s_nop 0
	global_load_lds_dwordx4 v146, s[62:63]
	s_add_i32 m0, s3, 0x2000
	s_nop 0
	global_load_lds_dwordx4 v150, s[62:63]
	s_add_u32 s100, s42, s22
	s_addc_u32 s101, s43, s23
	s_mov_b32 m0, s37
	s_nop 0
	global_load_lds_dwordx4 v144, s[42:43]
	s_mov_b32 m0, s39
	s_nop 0
	global_load_lds_dwordx4 v148, s[42:43]
	s_waitcnt vmcnt(8)
	s_waitcnt lgkmcnt(0)
	s_barrier
	s_setprio 1
	v_mfma_f32_16x16x32_bf16 v[60:63], v[64:67], v[184:187], v[60:63]
	v_mfma_f32_16x16x32_bf16 v[56:59], v[72:75], v[184:187], v[56:59]
	v_mfma_f32_16x16x32_bf16 v[44:47], v[64:67], v[192:195], v[44:47]
	v_mfma_f32_16x16x32_bf16 v[40:43], v[72:75], v[192:195], v[40:43]
	v_mfma_f32_16x16x32_bf16 v[28:31], v[64:67], v[200:203], v[28:31]
	v_mfma_f32_16x16x32_bf16 v[24:27], v[72:75], v[200:203], v[24:27]
	v_mfma_f32_16x16x32_bf16 v[12:15], v[64:67], v[208:211], v[12:15]
	v_mfma_f32_16x16x32_bf16 v[8:11], v[72:75], v[208:211], v[8:11]
	v_mfma_f32_16x16x32_bf16 v[60:63], v[68:71], v[188:191], v[60:63]
	v_mfma_f32_16x16x32_bf16 v[56:59], v[76:79], v[188:191], v[56:59]
	v_mfma_f32_16x16x32_bf16 v[44:47], v[68:71], v[196:199], v[44:47]
	v_mfma_f32_16x16x32_bf16 v[40:43], v[76:79], v[196:199], v[40:43]
	v_mfma_f32_16x16x32_bf16 v[28:31], v[68:71], v[204:207], v[28:31]
	v_mfma_f32_16x16x32_bf16 v[24:27], v[76:79], v[204:207], v[24:27]
	v_mfma_f32_16x16x32_bf16 v[12:15], v[68:71], v[212:215], v[12:15]
	v_mfma_f32_16x16x32_bf16 v[8:11], v[76:79], v[212:215], v[8:11]
	s_setprio 0
	s_setprio 1
	v_mfma_f32_16x16x32_bf16 v[52:55], v[160:163], v[184:187], v[52:55]
	v_mfma_f32_16x16x32_bf16 v[48:51], v[176:179], v[184:187], v[48:51]
	v_mfma_f32_16x16x32_bf16 v[36:39], v[160:163], v[192:195], v[36:39]
	v_mfma_f32_16x16x32_bf16 v[32:35], v[176:179], v[192:195], v[32:35]
	v_mfma_f32_16x16x32_bf16 v[20:23], v[160:163], v[200:203], v[20:23]
	v_mfma_f32_16x16x32_bf16 v[16:19], v[176:179], v[200:203], v[16:19]
	v_mfma_f32_16x16x32_bf16 v[4:7], v[160:163], v[208:211], v[4:7]
	v_mfma_f32_16x16x32_bf16 v[0:3], v[176:179], v[208:211], v[0:3]
	v_mfma_f32_16x16x32_bf16 v[52:55], v[172:175], v[188:191], v[52:55]
	v_mfma_f32_16x16x32_bf16 v[48:51], v[180:183], v[188:191], v[48:51]
	v_mfma_f32_16x16x32_bf16 v[36:39], v[172:175], v[196:199], v[36:39]
	v_mfma_f32_16x16x32_bf16 v[32:35], v[180:183], v[196:199], v[32:35]
	v_mfma_f32_16x16x32_bf16 v[20:23], v[172:175], v[204:207], v[20:23]
	v_mfma_f32_16x16x32_bf16 v[16:19], v[180:183], v[204:207], v[16:19]
	v_mfma_f32_16x16x32_bf16 v[4:7], v[172:175], v[212:215], v[4:7]
	v_mfma_f32_16x16x32_bf16 v[0:3], v[180:183], v[212:215], v[0:3]
	s_setprio 0
	s_barrier
; #define PG8_STAGE(bufoff, gbase, voff) do { _Pragma("unroll") for (int _i = 0; _i < 2; ++_i) \
;         __builtin_amdgcn_global_load_lds((const unsigned*)((const char*)(gbase) + (voff)[_i]), (LAS unsigned*)(lds + (bufoff) + ldsw + _i * 8192), 16, 0, 0); } while (0)
; #define PG8_WAIT_V(n) asm volatile("s_waitcnt vmcnt(" #n ")" ::: "memory")
; template <class Epi, class Sched, bool SP2 = PG8_SP2>
; __device__ __forceinline__ void gemm_phase(LAS unsigned char* lds, const Gemm g, const Sched& S, const Epi& E) {
;     ...
;             PG8_LDB(B0, 1, 0); PG8_LDB(B1, 1, 1); PG8_SCHED; PG8_LDA(At, 1, 0); PG8_STAGE(PG8_SA(0, 1), a2 + hstepA, voffA);
;             PG8_WAIT_V(8); PG8_WAIT_L(0); PG8_BAR; PG8_MMA(0, 0, At, B0); PG8_MMA(0, 1, At, B1); PG8_BAR; PG8_SCHED;
;             PG8_LDA(At, 1, 1); PG8_STAGE(PG8_SB(1, 0), b3, voffB); PG8_STAGE(PG8_SB(1, 1), b3 + hstepB, voffB); PG8_STAGE(PG8_SA(1, 0), a3, voffA);
;             PG8_WAIT_V(8); PG8_WAIT_L(0); PG8_BAR; PG8_MMA(1, 0, At, B0); PG8_MMA(1, 1, At, B1); PG8_BAR; PG8_SCHED;
;             } else {
;             PG8_LDB(B0, 0, 0); PG8_SCHED; PG8_LDA(At, 0, 0); PG8_STAGE(PG8_SA(1, 1), a1 + hstepA, voffA);
;             PG8_WAIT_L(8); PG8_BAR; PG8_WAIT_L(0); PG8_MMA(0, 0, At, B0); PG8_BAR; PG8_SCHED;
;             PG8_LDB(B1, 0, 1); PG8_STAGE(PG8_SB(0, 0), b2, voffB);
;             PG8_BAR; PG8_WAIT_L(0); PG8_MMA(0, 1, At, B1); PG8_BAR;
;             PG8_LDA(At, 0, 1); PG8_STAGE(PG8_SA(0, 0), a2, voffA);
;             PG8_BAR; PG8_WAIT_L(0); PG8_MMA(1, 0, At, B0); PG8_BAR; PG8_SCHED;
;             PG8_STAGE(PG8_SB(0, 1), b2 + hstepB, voffB);
;             PG8_WAIT_V(6); PG8_BAR; PG8_MMA(1, 1, At, B1); PG8_BAR;
;             PG8_LDB(B0, 1, 0); PG8_SCHED; PG8_LDA(At, 1, 0); PG8_STAGE(PG8_SA(0, 1), a2 + hstepA, voffA);
;             PG8_WAIT_L(8); PG8_BAR; PG8_WAIT_L(0); PG8_MMA(0, 0, At, B0); PG8_BAR; PG8_SCHED;
;             PG8_LDB(B1, 1, 1); PG8_STAGE(PG8_SB(1, 0), b3, voffB);
;             PG8_BAR; PG8_WAIT_L(0); PG8_MMA(0, 1, At, B1); PG8_BAR;
;             PG8_LDA(At, 1, 1); PG8_STAGE(PG8_SA(1, 0), a3, voffA);
;             PG8_BAR; PG8_WAIT_L(0); PG8_MMA(1, 0, At, B0); PG8_BAR; PG8_SCHED;
;             PG8_STAGE(PG8_SB(1, 1), b3 + hstepB, voffB);
;             PG8_WAIT_V(6); PG8_BAR; PG8_MMA(1, 1, At, B1); PG8_BAR;
;             }
;         }
;         if (wr == 0) PG8_BAR;
	s_add_i32 s3, 0, 0x18000
	s_add_i32 s61, 0, 0x1c000
	v_add_u32_e32 v76, s3, v165
	v_add_u32_e32 v171, s61, v165
	ds_read_b128 v[64:67], v76
	ds_read_b128 v[68:71], v76 offset:1024
	ds_read_b128 v[72:75], v76 offset:2048
	ds_read_b128 v[76:79], v76 offset:3072
	ds_read_b128 v[160:163], v171
	ds_read_b128 v[172:175], v171 offset:1024
	ds_read_b128 v[176:179], v171 offset:2048
	ds_read_b128 v[180:183], v171 offset:3072
	s_add_u32 s42, s42, 0x80000
	s_addc_u32 s43, s43, 0
	s_mov_b32 m0, s48
	ds_read_b128 v[184:187], v169 offset:32768
	ds_read_b128 v[188:191], v169 offset:33792
	ds_read_b128 v[192:195], v169 offset:34816
	ds_read_b128 v[196:199], v169 offset:35840
	ds_read_b128 v[200:203], v169 offset:36864
	ds_read_b128 v[204:207], v169 offset:37888
	ds_read_b128 v[208:211], v169 offset:38912
	ds_read_b128 v[212:215], v169 offset:39936
	global_load_lds_dwordx4 v144, s[42:43]
	s_mov_b32 m0, s49
	s_nop 0
	global_load_lds_dwordx4 v148, s[42:43]
	s_waitcnt vmcnt(8)
	s_waitcnt lgkmcnt(0)
	s_barrier
	s_setprio 1
	v_mfma_f32_16x16x32_bf16 v[140:143], v[64:67], v[184:187], v[140:143]
	v_mfma_f32_16x16x32_bf16 v[136:139], v[72:75], v[184:187], v[136:139]
	v_mfma_f32_16x16x32_bf16 v[124:127], v[64:67], v[192:195], v[124:127]
	v_mfma_f32_16x16x32_bf16 v[120:123], v[72:75], v[192:195], v[120:123]
	v_mfma_f32_16x16x32_bf16 v[108:111], v[64:67], v[200:203], v[108:111]
	v_mfma_f32_16x16x32_bf16 v[104:107], v[72:75], v[200:203], v[104:107]
	v_mfma_f32_16x16x32_bf16 v[92:95], v[64:67], v[208:211], v[92:95]
	v_mfma_f32_16x16x32_bf16 v[88:91], v[72:75], v[208:211], v[88:91]
	v_mfma_f32_16x16x32_bf16 v[140:143], v[68:71], v[188:191], v[140:143]
	v_mfma_f32_16x16x32_bf16 v[136:139], v[76:79], v[188:191], v[136:139]
	v_mfma_f32_16x16x32_bf16 v[124:127], v[68:71], v[196:199], v[124:127]
	v_mfma_f32_16x16x32_bf16 v[120:123], v[76:79], v[196:199], v[120:123]
	v_mfma_f32_16x16x32_bf16 v[108:111], v[68:71], v[204:207], v[108:111]
	v_mfma_f32_16x16x32_bf16 v[104:107], v[76:79], v[204:207], v[104:107]
	v_mfma_f32_16x16x32_bf16 v[92:95], v[68:71], v[212:215], v[92:95]
	v_mfma_f32_16x16x32_bf16 v[88:91], v[76:79], v[212:215], v[88:91]
	s_setprio 0
	s_setprio 1
	v_mfma_f32_16x16x32_bf16 v[132:135], v[160:163], v[184:187], v[132:135]
	v_mfma_f32_16x16x32_bf16 v[128:131], v[176:179], v[184:187], v[128:131]
	v_mfma_f32_16x16x32_bf16 v[116:119], v[160:163], v[192:195], v[116:119]
	v_mfma_f32_16x16x32_bf16 v[112:115], v[176:179], v[192:195], v[112:115]
	v_mfma_f32_16x16x32_bf16 v[100:103], v[160:163], v[200:203], v[100:103]
	v_mfma_f32_16x16x32_bf16 v[96:99], v[176:179], v[200:203], v[96:99]
	v_mfma_f32_16x16x32_bf16 v[84:87], v[160:163], v[208:211], v[84:87]
	v_mfma_f32_16x16x32_bf16 v[80:83], v[176:179], v[208:211], v[80:83]
	v_mfma_f32_16x16x32_bf16 v[132:135], v[172:175], v[188:191], v[132:135]
	v_mfma_f32_16x16x32_bf16 v[128:131], v[180:183], v[188:191], v[128:131]
	v_mfma_f32_16x16x32_bf16 v[116:119], v[172:175], v[196:199], v[116:119]
	v_mfma_f32_16x16x32_bf16 v[112:115], v[180:183], v[196:199], v[112:115]
	v_mfma_f32_16x16x32_bf16 v[100:103], v[172:175], v[204:207], v[100:103]
	v_mfma_f32_16x16x32_bf16 v[96:99], v[180:183], v[204:207], v[96:99]
	v_mfma_f32_16x16x32_bf16 v[84:87], v[172:175], v[212:215], v[84:87]
	v_mfma_f32_16x16x32_bf16 v[80:83], v[180:183], v[212:215], v[80:83]
	s_setprio 0
	s_barrier
	s_add_i32 s3, s3, s47
	s_mov_b32 m0, s3
	ds_read_b128 v[184:187], v169 offset:49152
	ds_read_b128 v[188:191], v169 offset:50176
	ds_read_b128 v[192:195], v169 offset:51200
	ds_read_b128 v[196:199], v169 offset:52224
	ds_read_b128 v[200:203], v169 offset:53248
	ds_read_b128 v[204:207], v169 offset:54272
	ds_read_b128 v[208:211], v169 offset:55296
	ds_read_b128 v[212:215], v169 offset:56320
	global_load_lds_dwordx4 v146, s[98:99]
	s_add_i32 m0, s3, 0x2000
	s_add_u32 s40, s40, 0x80080
	s_addc_u32 s41, s41, 0
	s_add_i32 s3, s61, s47
	global_load_lds_dwordx4 v150, s[98:99]
	s_mov_b32 m0, s3
	s_nop 0
	global_load_lds_dwordx4 v146, s[40:41]
	s_add_i32 m0, s3, 0x2000
	s_nop 0
	global_load_lds_dwordx4 v150, s[40:41]
	s_mov_b32 m0, s51
	s_nop 0
	global_load_lds_dwordx4 v144, s[100:101]
	s_mov_b32 m0, s52
	s_nop 0
	global_load_lds_dwordx4 v148, s[100:101]
	s_waitcnt vmcnt(8)
	s_waitcnt lgkmcnt(0)
	s_barrier
	s_setprio 1
	v_mfma_f32_16x16x32_bf16 v[60:63], v[64:67], v[184:187], v[60:63]
	v_mfma_f32_16x16x32_bf16 v[56:59], v[72:75], v[184:187], v[56:59]
	v_mfma_f32_16x16x32_bf16 v[44:47], v[64:67], v[192:195], v[44:47]
	v_mfma_f32_16x16x32_bf16 v[40:43], v[72:75], v[192:195], v[40:43]
	v_mfma_f32_16x16x32_bf16 v[28:31], v[64:67], v[200:203], v[28:31]
	v_mfma_f32_16x16x32_bf16 v[24:27], v[72:75], v[200:203], v[24:27]
	v_mfma_f32_16x16x32_bf16 v[12:15], v[64:67], v[208:211], v[12:15]
	v_mfma_f32_16x16x32_bf16 v[8:11], v[72:75], v[208:211], v[8:11]
	v_mfma_f32_16x16x32_bf16 v[60:63], v[68:71], v[188:191], v[60:63]
	v_mfma_f32_16x16x32_bf16 v[56:59], v[76:79], v[188:191], v[56:59]
	v_mfma_f32_16x16x32_bf16 v[44:47], v[68:71], v[196:199], v[44:47]
	v_mfma_f32_16x16x32_bf16 v[40:43], v[76:79], v[196:199], v[40:43]
	v_mfma_f32_16x16x32_bf16 v[28:31], v[68:71], v[204:207], v[28:31]
	v_mfma_f32_16x16x32_bf16 v[24:27], v[76:79], v[204:207], v[24:27]
	v_mfma_f32_16x16x32_bf16 v[12:15], v[68:71], v[212:215], v[12:15]
	v_mfma_f32_16x16x32_bf16 v[8:11], v[76:79], v[212:215], v[8:11]
	s_setprio 0
	s_setprio 1
	v_mfma_f32_16x16x32_bf16 v[52:55], v[160:163], v[184:187], v[52:55]
	v_mfma_f32_16x16x32_bf16 v[48:51], v[176:179], v[184:187], v[48:51]
	v_mfma_f32_16x16x32_bf16 v[36:39], v[160:163], v[192:195], v[36:39]
	v_mfma_f32_16x16x32_bf16 v[32:35], v[176:179], v[192:195], v[32:35]
	v_mfma_f32_16x16x32_bf16 v[20:23], v[160:163], v[200:203], v[20:23]
	v_mfma_f32_16x16x32_bf16 v[16:19], v[176:179], v[200:203], v[16:19]
	v_mfma_f32_16x16x32_bf16 v[4:7], v[160:163], v[208:211], v[4:7]
	v_mfma_f32_16x16x32_bf16 v[0:3], v[176:179], v[208:211], v[0:3]
	v_mfma_f32_16x16x32_bf16 v[52:55], v[172:175], v[188:191], v[52:55]
	v_mfma_f32_16x16x32_bf16 v[48:51], v[180:183], v[188:191], v[48:51]
	v_mfma_f32_16x16x32_bf16 v[36:39], v[172:175], v[196:199], v[36:39]
	v_mfma_f32_16x16x32_bf16 v[32:35], v[180:183], v[196:199], v[32:35]
	v_mfma_f32_16x16x32_bf16 v[20:23], v[172:175], v[204:207], v[20:23]
	v_mfma_f32_16x16x32_bf16 v[16:19], v[180:183], v[204:207], v[16:19]
	v_mfma_f32_16x16x32_bf16 v[4:7], v[172:175], v[212:215], v[4:7]
	v_mfma_f32_16x16x32_bf16 v[0:3], v[180:183], v[212:215], v[0:3]
	s_setprio 0
	s_barrier
	s_add_i32 s60, s60, 2
	s_add_u32 s0, s0, 0x100
	s_addc_u32 s1, s1, 0
	s_add_u32 s58, s58, 0x100
	s_addc_u32 s59, s59, 0
	s_cmp_gt_u32 s60, 29
	s_cbranch_scc0 .LBB0_845
	s_and_b64 vcc, exec, s[24:25]
	s_cbranch_vccz .LBB0_848
	s_barrier

; #define PG8_STAGE(bufoff, gbase, voff) do { _Pragma("unroll") for (int _i = 0; _i < 2; ++_i) \
;         __builtin_amdgcn_global_load_lds((const unsigned*)((const char*)(gbase) + (voff)[_i]), (LAS unsigned*)(lds + (bufoff) + ldsw + _i * 8192), 16, 0, 0); } while (0)
; #define PG8_LDA(dst, b, h) do { _Pragma("unroll") for (int m = 0; m < 4; ++m) _Pragma("unroll") for (int k = 0; k < 2; ++k) dst[m][k] = *(const LAS bf16x8*)(lds + PG8_SA(b, h) + aoff + m * 2048 + k * 1024); } while (0)
; #define PG8_LDB(dst, b, h) do { _Pragma("unroll") for (int n = 0; n < 2; ++n) _Pragma("unroll") for (int k = 0; k < 2; ++k) dst[n][k] = *(const LAS bf16x8*)(lds + PG8_SB(b, h) + boff + n * 2048 + k * 1024); } while (0)
; #define PG8_MMA(ai, bj, At, Bt) do { __builtin_amdgcn_s_setprio(1); _Pragma("unroll") for (int m = 0; m < 4; ++m) _Pragma("unroll") for (int n = 0; n < 2; ++n) _Pragma("unroll") for (int k = 0; k < 2; ++k) \
;         acc[ai][bj][m][n] = __builtin_amdgcn_mfma_f32_16x16x32_bf16(Bt[n][k], At[m][k], acc[ai][bj][m][n], 0, 0, 0); __builtin_amdgcn_s_setprio(0); } while (0)
; #define PG8_WAIT_V(n) asm volatile("s_waitcnt vmcnt(" #n ")" ::: "memory")
; #define PG8_WAIT_L(n) asm volatile("s_waitcnt lgkmcnt(" #n ")" ::: "memory")
; #define PG8_BAR __builtin_amdgcn_s_barrier()
; template <class Epi, class Sched, bool SP2 = PG8_SP2>
; __device__ __forceinline__ void gemm_phase(LAS unsigned char* lds, const Gemm g, const Sched& S, const Epi& E) {
;     ...
;         for (int t = 0; t < nt; t += 2) {
;             const bool last = (t == nt - 2);
;             const char* a1 = cA + (size_t)(t + 1) * kstep;
;             const char* a2 = last ? nA : cA + (size_t)(t + 2) * kstep; const char* b2 = last ? nB : cB + (size_t)(t + 2) * kstep;
;             const char* a3 = a2 + kstep; const char* b3 = b2 + kstep;
;             if constexpr (SP2) {
;             PG8_LDB(B0, 0, 0); PG8_LDB(B1, 0, 1); PG8_SCHED; PG8_LDA(At, 0, 0); PG8_STAGE(PG8_SA(1, 1), a1 + hstepA, voffA);
;             PG8_WAIT_V(8); PG8_WAIT_L(0); PG8_BAR; PG8_MMA(0, 0, At, B0); PG8_MMA(0, 1, At, B1); PG8_BAR; PG8_SCHED;
;             PG8_LDA(At, 0, 1); PG8_STAGE(PG8_SB(0, 0), b2, voffB); PG8_STAGE(PG8_SB(0, 1), b2 + hstepB, voffB); PG8_STAGE(PG8_SA(0, 0), a2, voffA);
;             PG8_WAIT_V(8); PG8_WAIT_L(0); PG8_BAR; PG8_MMA(1, 0, At, B0); PG8_MMA(1, 1, At, B1); PG8_BAR; PG8_SCHED;
.LBB0_932:
	ds_read_b128 v[144:147], v155
	ds_read_b128 v[148:151], v155 offset:1024
	ds_read_b128 v[160:163], v155 offset:2048
	ds_read_b128 v[164:167], v155 offset:3072
	ds_read_b128 v[168:171], v156
	ds_read_b128 v[172:175], v156 offset:1024
	ds_read_b128 v[176:179], v156 offset:2048
	ds_read_b128 v[180:183], v156 offset:3072
	s_add_u32 s3, s0, 0xfff80080
	s_addc_u32 s28, s1, -1
	s_cmp_eq_u32 s54, 28
	s_cselect_b32 s31, s2, s28
	s_cselect_b32 s30, s21, s3
	s_cselect_b32 s29, s19, s53
	s_cselect_b32 s28, s51, s52
	s_add_i32 m0, s27, 0xc000
	ds_read_b128 v[184:187], v157
	ds_read_b128 v[188:191], v157 offset:1024
	ds_read_b128 v[192:195], v157 offset:2048
	ds_read_b128 v[196:199], v157 offset:3072
	ds_read_b128 v[200:203], v157 offset:4096
	ds_read_b128 v[204:207], v157 offset:5120
	ds_read_b128 v[208:211], v157 offset:6144
	ds_read_b128 v[212:215], v157 offset:7168
	global_load_lds_dwordx4 v136, s[0:1]
	s_add_i32 m0, s27, 0xe000
	s_nop 0
	global_load_lds_dwordx4 v138, s[0:1]
	s_waitcnt vmcnt(8)
	s_waitcnt lgkmcnt(0)
	s_barrier
	s_setprio 1
	v_mfma_f32_16x16x32_bf16 v[124:127], v[144:147], v[184:187], v[124:127]
	v_mfma_f32_16x16x32_bf16 v[120:123], v[160:163], v[184:187], v[120:123]
	v_mfma_f32_16x16x32_bf16 v[108:111], v[144:147], v[192:195], v[108:111]
	v_mfma_f32_16x16x32_bf16 v[104:107], v[160:163], v[192:195], v[104:107]
	v_mfma_f32_16x16x32_bf16 v[92:95], v[144:147], v[200:203], v[92:95]
	v_mfma_f32_16x16x32_bf16 v[88:91], v[160:163], v[200:203], v[88:91]
	v_mfma_f32_16x16x32_bf16 v[84:87], v[144:147], v[208:211], v[84:87]
	v_mfma_f32_16x16x32_bf16 v[76:79], v[160:163], v[208:211], v[76:79]
	v_mfma_f32_16x16x32_bf16 v[124:127], v[148:151], v[188:191], v[124:127]
	v_mfma_f32_16x16x32_bf16 v[120:123], v[164:167], v[188:191], v[120:123]
	v_mfma_f32_16x16x32_bf16 v[108:111], v[148:151], v[196:199], v[108:111]
	v_mfma_f32_16x16x32_bf16 v[104:107], v[164:167], v[196:199], v[104:107]
	v_mfma_f32_16x16x32_bf16 v[92:95], v[148:151], v[204:207], v[92:95]
	v_mfma_f32_16x16x32_bf16 v[88:91], v[164:167], v[204:207], v[88:91]
	v_mfma_f32_16x16x32_bf16 v[84:87], v[148:151], v[212:215], v[84:87]
	v_mfma_f32_16x16x32_bf16 v[76:79], v[164:167], v[212:215], v[76:79]
	s_setprio 0
	s_setprio 1
	v_mfma_f32_16x16x32_bf16 v[116:119], v[168:171], v[184:187], v[116:119]
	v_mfma_f32_16x16x32_bf16 v[112:115], v[176:179], v[184:187], v[112:115]
	v_mfma_f32_16x16x32_bf16 v[100:103], v[168:171], v[192:195], v[100:103]
	v_mfma_f32_16x16x32_bf16 v[96:99], v[176:179], v[192:195], v[96:99]
	v_mfma_f32_16x16x32_bf16 v[80:83], v[168:171], v[200:203], v[80:83]
	v_mfma_f32_16x16x32_bf16 v[72:75], v[176:179], v[200:203], v[72:75]
	v_mfma_f32_16x16x32_bf16 v[68:71], v[168:171], v[208:211], v[68:71]
	v_mfma_f32_16x16x32_bf16 v[64:67], v[176:179], v[208:211], v[64:67]
	v_mfma_f32_16x16x32_bf16 v[116:119], v[172:175], v[188:191], v[116:119]
	v_mfma_f32_16x16x32_bf16 v[112:115], v[180:183], v[188:191], v[112:115]
	v_mfma_f32_16x16x32_bf16 v[100:103], v[172:175], v[196:199], v[100:103]
	v_mfma_f32_16x16x32_bf16 v[96:99], v[180:183], v[196:199], v[96:99]
	v_mfma_f32_16x16x32_bf16 v[80:83], v[172:175], v[204:207], v[80:83]
	v_mfma_f32_16x16x32_bf16 v[72:75], v[180:183], v[204:207], v[72:75]
	v_mfma_f32_16x16x32_bf16 v[68:71], v[172:175], v[212:215], v[68:71]
	v_mfma_f32_16x16x32_bf16 v[64:67], v[180:183], v[212:215], v[64:67]
	s_setprio 0
	s_barrier
	s_add_i32 s3, s47, s37
	s_add_u32 s98, s28, s14
	s_addc_u32 s99, s29, s15
	s_mov_b32 m0, s3
	ds_read_b128 v[184:187], v157 offset:16384
	ds_read_b128 v[188:191], v157 offset:17408
	ds_read_b128 v[192:195], v157 offset:18432
	ds_read_b128 v[196:199], v157 offset:19456
	ds_read_b128 v[200:203], v157 offset:20480
	ds_read_b128 v[204:207], v157 offset:21504
	ds_read_b128 v[208:211], v157 offset:22528
	ds_read_b128 v[212:215], v157 offset:23552
	global_load_lds_dwordx4 v132, s[28:29]
	s_add_i32 m0, s3, 0x2000
	s_add_u32 s56, s28, 0x80000
	s_addc_u32 s57, s29, 0
	s_add_i32 s3, s48, s37
	global_load_lds_dwordx4 v128, s[28:29]
	s_mov_b32 m0, s3
	s_nop 0
	global_load_lds_dwordx4 v132, s[56:57]
	s_add_i32 m0, s3, 0x2000
	s_nop 0
	global_load_lds_dwordx4 v128, s[56:57]
	s_add_u32 s100, s30, s14
	s_addc_u32 s101, s31, s15
	s_mov_b32 m0, s27
	s_nop 0
	global_load_lds_dwordx4 v134, s[30:31]
	s_mov_b32 m0, s40
	s_nop 0
	global_load_lds_dwordx4 v130, s[30:31]
	s_waitcnt vmcnt(8)
	s_waitcnt lgkmcnt(0)
	s_barrier
	s_setprio 1
	v_mfma_f32_16x16x32_bf16 v[60:63], v[144:147], v[184:187], v[60:63]
	v_mfma_f32_16x16x32_bf16 v[56:59], v[160:163], v[184:187], v[56:59]
	v_mfma_f32_16x16x32_bf16 v[44:47], v[144:147], v[192:195], v[44:47]
	v_mfma_f32_16x16x32_bf16 v[40:43], v[160:163], v[192:195], v[40:43]
	v_mfma_f32_16x16x32_bf16 v[28:31], v[144:147], v[200:203], v[28:31]
	v_mfma_f32_16x16x32_bf16 v[24:27], v[160:163], v[200:203], v[24:27]
	v_mfma_f32_16x16x32_bf16 v[12:15], v[144:147], v[208:211], v[12:15]
	v_mfma_f32_16x16x32_bf16 v[8:11], v[160:163], v[208:211], v[8:11]
	v_mfma_f32_16x16x32_bf16 v[60:63], v[148:151], v[188:191], v[60:63]
	v_mfma_f32_16x16x32_bf16 v[56:59], v[164:167], v[188:191], v[56:59]
	v_mfma_f32_16x16x32_bf16 v[44:47], v[148:151], v[196:199], v[44:47]
	v_mfma_f32_16x16x32_bf16 v[40:43], v[164:167], v[196:199], v[40:43]
	v_mfma_f32_16x16x32_bf16 v[28:31], v[148:151], v[204:207], v[28:31]
	v_mfma_f32_16x16x32_bf16 v[24:27], v[164:167], v[204:207], v[24:27]
	v_mfma_f32_16x16x32_bf16 v[12:15], v[148:151], v[212:215], v[12:15]
	v_mfma_f32_16x16x32_bf16 v[8:11], v[164:167], v[212:215], v[8:11]
	s_setprio 0
	s_setprio 1
	v_mfma_f32_16x16x32_bf16 v[52:55], v[168:171], v[184:187], v[52:55]
	v_mfma_f32_16x16x32_bf16 v[48:51], v[176:179], v[184:187], v[48:51]
	v_mfma_f32_16x16x32_bf16 v[36:39], v[168:171], v[192:195], v[36:39]
	v_mfma_f32_16x16x32_bf16 v[32:35], v[176:179], v[192:195], v[32:35]
	v_mfma_f32_16x16x32_bf16 v[20:23], v[168:171], v[200:203], v[20:23]
	v_mfma_f32_16x16x32_bf16 v[16:19], v[176:179], v[200:203], v[16:19]
	v_mfma_f32_16x16x32_bf16 v[4:7], v[168:171], v[208:211], v[4:7]
	v_mfma_f32_16x16x32_bf16 v[0:3], v[176:179], v[208:211], v[0:3]
	v_mfma_f32_16x16x32_bf16 v[52:55], v[172:175], v[188:191], v[52:55]
	v_mfma_f32_16x16x32_bf16 v[48:51], v[180:183], v[188:191], v[48:51]
	v_mfma_f32_16x16x32_bf16 v[36:39], v[172:175], v[196:199], v[36:39]
	v_mfma_f32_16x16x32_bf16 v[32:35], v[180:183], v[196:199], v[32:35]
	v_mfma_f32_16x16x32_bf16 v[20:23], v[172:175], v[204:207], v[20:23]
	v_mfma_f32_16x16x32_bf16 v[16:19], v[180:183], v[204:207], v[16:19]
	v_mfma_f32_16x16x32_bf16 v[4:7], v[172:175], v[212:215], v[4:7]
	v_mfma_f32_16x16x32_bf16 v[0:3], v[180:183], v[212:215], v[0:3]
	s_setprio 0
	s_barrier
; #define PG8_STAGE(bufoff, gbase, voff) do { _Pragma("unroll") for (int _i = 0; _i < 2; ++_i) \
;         __builtin_amdgcn_global_load_lds((const unsigned*)((const char*)(gbase) + (voff)[_i]), (LAS unsigned*)(lds + (bufoff) + ldsw + _i * 8192), 16, 0, 0); } while (0)
; #define PG8_WAIT_V(n) asm volatile("s_waitcnt vmcnt(" #n ")" ::: "memory")
; template <class Epi, class Sched, bool SP2 = PG8_SP2>
; __device__ __forceinline__ void gemm_phase(LAS unsigned char* lds, const Gemm g, const Sched& S, const Epi& E) {
;     ...
;             PG8_LDB(B0, 1, 0); PG8_LDB(B1, 1, 1); PG8_SCHED; PG8_LDA(At, 1, 0); PG8_STAGE(PG8_SA(0, 1), a2 + hstepA, voffA);
;             PG8_WAIT_V(8); PG8_WAIT_L(0); PG8_BAR; PG8_MMA(0, 0, At, B0); PG8_MMA(0, 1, At, B1); PG8_BAR; PG8_SCHED;
;             PG8_LDA(At, 1, 1); PG8_STAGE(PG8_SB(1, 0), b3, voffB); PG8_STAGE(PG8_SB(1, 1), b3 + hstepB, voffB); PG8_STAGE(PG8_SA(1, 0), a3, voffA);
;             PG8_WAIT_V(8); PG8_WAIT_L(0); PG8_BAR; PG8_MMA(1, 0, At, B0); PG8_MMA(1, 1, At, B1); PG8_BAR; PG8_SCHED;
;             } else {
;             PG8_LDB(B0, 0, 0); PG8_SCHED; PG8_LDA(At, 0, 0); PG8_STAGE(PG8_SA(1, 1), a1 + hstepA, voffA);
;             PG8_WAIT_L(8); PG8_BAR; PG8_WAIT_L(0); PG8_MMA(0, 0, At, B0); PG8_BAR; PG8_SCHED;
;             PG8_LDB(B1, 0, 1); PG8_STAGE(PG8_SB(0, 0), b2, voffB);
;             PG8_BAR; PG8_WAIT_L(0); PG8_MMA(0, 1, At, B1); PG8_BAR;
;             PG8_LDA(At, 0, 1); PG8_STAGE(PG8_SA(0, 0), a2, voffA);
;             PG8_BAR; PG8_WAIT_L(0); PG8_MMA(1, 0, At, B0); PG8_BAR; PG8_SCHED;
;             PG8_STAGE(PG8_SB(0, 1), b2 + hstepB, voffB);
;             PG8_WAIT_V(6); PG8_BAR; PG8_MMA(1, 1, At, B1); PG8_BAR;
;             PG8_LDB(B0, 1, 0); PG8_SCHED; PG8_LDA(At, 1, 0); PG8_STAGE(PG8_SA(0, 1), a2 + hstepA, voffA);
;             PG8_WAIT_L(8); PG8_BAR; PG8_WAIT_L(0); PG8_MMA(0, 0, At, B0); PG8_BAR; PG8_SCHED;
;             PG8_LDB(B1, 1, 1); PG8_STAGE(PG8_SB(1, 0), b3, voffB);
;             PG8_BAR; PG8_WAIT_L(0); PG8_MMA(0, 1, At, B1); PG8_BAR;
;             PG8_LDA(At, 1, 1); PG8_STAGE(PG8_SA(1, 0), a3, voffA);
;             PG8_BAR; PG8_WAIT_L(0); PG8_MMA(1, 0, At, B0); PG8_BAR; PG8_SCHED;
;             PG8_STAGE(PG8_SB(1, 1), b3 + hstepB, voffB);
;             PG8_WAIT_V(6); PG8_BAR; PG8_MMA(1, 1, At, B1); PG8_BAR;
;             }
;         }
;         if (wr == 0) PG8_BAR;
	s_add_i32 s3, 0, 0x18000
	v_add_u32_e32 v159, s3, v153
	s_add_i32 s55, 0, 0x1c000
	ds_read_b128 v[144:147], v159
	ds_read_b128 v[148:151], v159 offset:1024
	ds_read_b128 v[160:163], v159 offset:2048
	ds_read_b128 v[164:167], v159 offset:3072
	v_add_u32_e32 v159, s55, v153
	ds_read_b128 v[168:171], v159
	ds_read_b128 v[172:175], v159 offset:1024
	ds_read_b128 v[176:179], v159 offset:2048
	ds_read_b128 v[180:183], v159 offset:3072
	s_add_u32 s30, s30, 0x80000
	s_addc_u32 s31, s31, 0
	s_mov_b32 m0, s41
	ds_read_b128 v[184:187], v157 offset:32768
	ds_read_b128 v[188:191], v157 offset:33792
	ds_read_b128 v[192:195], v157 offset:34816
	ds_read_b128 v[196:199], v157 offset:35840
	ds_read_b128 v[200:203], v157 offset:36864
	ds_read_b128 v[204:207], v157 offset:37888
	ds_read_b128 v[208:211], v157 offset:38912
	ds_read_b128 v[212:215], v157 offset:39936
	global_load_lds_dwordx4 v134, s[30:31]
	s_mov_b32 m0, s42
	s_nop 0
	global_load_lds_dwordx4 v130, s[30:31]
	s_waitcnt vmcnt(8)
	s_waitcnt lgkmcnt(0)
	s_barrier
	s_setprio 1
	v_mfma_f32_16x16x32_bf16 v[124:127], v[144:147], v[184:187], v[124:127]
	v_mfma_f32_16x16x32_bf16 v[120:123], v[160:163], v[184:187], v[120:123]
	v_mfma_f32_16x16x32_bf16 v[108:111], v[144:147], v[192:195], v[108:111]
	v_mfma_f32_16x16x32_bf16 v[104:107], v[160:163], v[192:195], v[104:107]
	v_mfma_f32_16x16x32_bf16 v[92:95], v[144:147], v[200:203], v[92:95]
	v_mfma_f32_16x16x32_bf16 v[88:91], v[160:163], v[200:203], v[88:91]
	v_mfma_f32_16x16x32_bf16 v[84:87], v[144:147], v[208:211], v[84:87]
	v_mfma_f32_16x16x32_bf16 v[76:79], v[160:163], v[208:211], v[76:79]
	v_mfma_f32_16x16x32_bf16 v[124:127], v[148:151], v[188:191], v[124:127]
	v_mfma_f32_16x16x32_bf16 v[120:123], v[164:167], v[188:191], v[120:123]
	v_mfma_f32_16x16x32_bf16 v[108:111], v[148:151], v[196:199], v[108:111]
	v_mfma_f32_16x16x32_bf16 v[104:107], v[164:167], v[196:199], v[104:107]
	v_mfma_f32_16x16x32_bf16 v[92:95], v[148:151], v[204:207], v[92:95]
	v_mfma_f32_16x16x32_bf16 v[88:91], v[164:167], v[204:207], v[88:91]
	v_mfma_f32_16x16x32_bf16 v[84:87], v[148:151], v[212:215], v[84:87]
	v_mfma_f32_16x16x32_bf16 v[76:79], v[164:167], v[212:215], v[76:79]
	s_setprio 0
	s_setprio 1
	v_mfma_f32_16x16x32_bf16 v[116:119], v[168:171], v[184:187], v[116:119]
	v_mfma_f32_16x16x32_bf16 v[112:115], v[176:179], v[184:187], v[112:115]
	v_mfma_f32_16x16x32_bf16 v[100:103], v[168:171], v[192:195], v[100:103]
	v_mfma_f32_16x16x32_bf16 v[96:99], v[176:179], v[192:195], v[96:99]
	v_mfma_f32_16x16x32_bf16 v[80:83], v[168:171], v[200:203], v[80:83]
	v_mfma_f32_16x16x32_bf16 v[72:75], v[176:179], v[200:203], v[72:75]
	v_mfma_f32_16x16x32_bf16 v[68:71], v[168:171], v[208:211], v[68:71]
	v_mfma_f32_16x16x32_bf16 v[64:67], v[176:179], v[208:211], v[64:67]
	v_mfma_f32_16x16x32_bf16 v[116:119], v[172:175], v[188:191], v[116:119]
	v_mfma_f32_16x16x32_bf16 v[112:115], v[180:183], v[188:191], v[112:115]
	v_mfma_f32_16x16x32_bf16 v[100:103], v[172:175], v[196:199], v[100:103]
	v_mfma_f32_16x16x32_bf16 v[96:99], v[180:183], v[196:199], v[96:99]
	v_mfma_f32_16x16x32_bf16 v[80:83], v[172:175], v[204:207], v[80:83]
	v_mfma_f32_16x16x32_bf16 v[72:75], v[180:183], v[204:207], v[72:75]
	v_mfma_f32_16x16x32_bf16 v[68:71], v[172:175], v[212:215], v[68:71]
	v_mfma_f32_16x16x32_bf16 v[64:67], v[180:183], v[212:215], v[64:67]
	s_setprio 0
	s_barrier
	s_add_i32 s3, s3, s37
	s_mov_b32 m0, s3
	ds_read_b128 v[184:187], v157 offset:49152
	ds_read_b128 v[188:191], v157 offset:50176
	ds_read_b128 v[192:195], v157 offset:51200
	ds_read_b128 v[196:199], v157 offset:52224
	ds_read_b128 v[200:203], v157 offset:53248
	ds_read_b128 v[204:207], v157 offset:54272
	ds_read_b128 v[208:211], v157 offset:55296
	ds_read_b128 v[212:215], v157 offset:56320
	global_load_lds_dwordx4 v132, s[98:99]
	s_add_i32 m0, s3, 0x2000
	s_add_u32 s28, s28, 0x80080
	s_addc_u32 s29, s29, 0
	s_add_i32 s3, s55, s37
	global_load_lds_dwordx4 v128, s[98:99]
	s_mov_b32 m0, s3
	s_nop 0
	global_load_lds_dwordx4 v132, s[28:29]
	s_add_i32 m0, s3, 0x2000
	s_nop 0
	global_load_lds_dwordx4 v128, s[28:29]
	s_mov_b32 m0, s44
	s_nop 0
	global_load_lds_dwordx4 v134, s[100:101]
	s_mov_b32 m0, s45
	s_nop 0
	global_load_lds_dwordx4 v130, s[100:101]
	s_waitcnt vmcnt(8)
	s_waitcnt lgkmcnt(0)
	s_barrier
	s_setprio 1
	v_mfma_f32_16x16x32_bf16 v[60:63], v[144:147], v[184:187], v[60:63]
	v_mfma_f32_16x16x32_bf16 v[56:59], v[160:163], v[184:187], v[56:59]
	v_mfma_f32_16x16x32_bf16 v[44:47], v[144:147], v[192:195], v[44:47]
	v_mfma_f32_16x16x32_bf16 v[40:43], v[160:163], v[192:195], v[40:43]
	v_mfma_f32_16x16x32_bf16 v[28:31], v[144:147], v[200:203], v[28:31]
	v_mfma_f32_16x16x32_bf16 v[24:27], v[160:163], v[200:203], v[24:27]
	v_mfma_f32_16x16x32_bf16 v[12:15], v[144:147], v[208:211], v[12:15]
	v_mfma_f32_16x16x32_bf16 v[8:11], v[160:163], v[208:211], v[8:11]
	v_mfma_f32_16x16x32_bf16 v[60:63], v[148:151], v[188:191], v[60:63]
	v_mfma_f32_16x16x32_bf16 v[56:59], v[164:167], v[188:191], v[56:59]
	v_mfma_f32_16x16x32_bf16 v[44:47], v[148:151], v[196:199], v[44:47]
	v_mfma_f32_16x16x32_bf16 v[40:43], v[164:167], v[196:199], v[40:43]
	v_mfma_f32_16x16x32_bf16 v[28:31], v[148:151], v[204:207], v[28:31]
	v_mfma_f32_16x16x32_bf16 v[24:27], v[164:167], v[204:207], v[24:27]
	v_mfma_f32_16x16x32_bf16 v[12:15], v[148:151], v[212:215], v[12:15]
	v_mfma_f32_16x16x32_bf16 v[8:11], v[164:167], v[212:215], v[8:11]
	s_setprio 0
	s_setprio 1
	v_mfma_f32_16x16x32_bf16 v[52:55], v[168:171], v[184:187], v[52:55]
	v_mfma_f32_16x16x32_bf16 v[48:51], v[176:179], v[184:187], v[48:51]
	v_mfma_f32_16x16x32_bf16 v[36:39], v[168:171], v[192:195], v[36:39]
	v_mfma_f32_16x16x32_bf16 v[32:35], v[176:179], v[192:195], v[32:35]
	v_mfma_f32_16x16x32_bf16 v[20:23], v[168:171], v[200:203], v[20:23]
	v_mfma_f32_16x16x32_bf16 v[16:19], v[176:179], v[200:203], v[16:19]
	v_mfma_f32_16x16x32_bf16 v[4:7], v[168:171], v[208:211], v[4:7]
	v_mfma_f32_16x16x32_bf16 v[0:3], v[176:179], v[208:211], v[0:3]
	v_mfma_f32_16x16x32_bf16 v[52:55], v[172:175], v[188:191], v[52:55]
	v_mfma_f32_16x16x32_bf16 v[48:51], v[180:183], v[188:191], v[48:51]
	v_mfma_f32_16x16x32_bf16 v[36:39], v[172:175], v[196:199], v[36:39]
	v_mfma_f32_16x16x32_bf16 v[32:35], v[180:183], v[196:199], v[32:35]
	v_mfma_f32_16x16x32_bf16 v[20:23], v[172:175], v[204:207], v[20:23]
	v_mfma_f32_16x16x32_bf16 v[16:19], v[180:183], v[204:207], v[16:19]
	v_mfma_f32_16x16x32_bf16 v[4:7], v[172:175], v[212:215], v[4:7]
	v_mfma_f32_16x16x32_bf16 v[0:3], v[180:183], v[212:215], v[0:3]
	s_setprio 0
	s_barrier
	s_add_i32 s54, s54, 2
	s_add_u32 s0, s0, 0x100
	s_addc_u32 s1, s1, 0
	s_add_u32 s52, s52, 0x100
	s_addc_u32 s53, s53, 0
	s_cmp_gt_u32 s54, 29
	s_cbranch_scc0 .LBB0_932
	s_and_b64 vcc, exec, s[16:17]
	s_cbranch_vccz .LBB0_935
	s_barrier

; #define PG8_STAGE(bufoff, gbase, voff) do { _Pragma("unroll") for (int _i = 0; _i < 2; ++_i) \
;         __builtin_amdgcn_global_load_lds((const unsigned*)((const char*)(gbase) + (voff)[_i]), (LAS unsigned*)(lds + (bufoff) + ldsw + _i * 8192), 16, 0, 0); } while (0)
; #define PG8_LDA(dst, b, h) do { _Pragma("unroll") for (int m = 0; m < 4; ++m) _Pragma("unroll") for (int k = 0; k < 2; ++k) dst[m][k] = *(const LAS bf16x8*)(lds + PG8_SA(b, h) + aoff + m * 2048 + k * 1024); } while (0)
; #define PG8_LDB(dst, b, h) do { _Pragma("unroll") for (int n = 0; n < 2; ++n) _Pragma("unroll") for (int k = 0; k < 2; ++k) dst[n][k] = *(const LAS bf16x8*)(lds + PG8_SB(b, h) + boff + n * 2048 + k * 1024); } while (0)
; #define PG8_MMA(ai, bj, At, Bt) do { __builtin_amdgcn_s_setprio(1); _Pragma("unroll") for (int m = 0; m < 4; ++m) _Pragma("unroll") for (int n = 0; n < 2; ++n) _Pragma("unroll") for (int k = 0; k < 2; ++k) \
;         acc[ai][bj][m][n] = __builtin_amdgcn_mfma_f32_16x16x32_bf16(Bt[n][k], At[m][k], acc[ai][bj][m][n], 0, 0, 0); __builtin_amdgcn_s_setprio(0); } while (0)
; #define PG8_WAIT_V(n) asm volatile("s_waitcnt vmcnt(" #n ")" ::: "memory")
; #define PG8_WAIT_L(n) asm volatile("s_waitcnt lgkmcnt(" #n ")" ::: "memory")
; #define PG8_BAR __builtin_amdgcn_s_barrier()
; template <class Epi, class Sched, bool SP2 = PG8_SP2>
; __device__ __forceinline__ void gemm_phase(LAS unsigned char* lds, const Gemm g, const Sched& S, const Epi& E) {
;     ...
;         for (int t = 0; t < nt; t += 2) {
;             const bool last = (t == nt - 2);
;             const char* a1 = cA + (size_t)(t + 1) * kstep;
;             const char* a2 = last ? nA : cA + (size_t)(t + 2) * kstep; const char* b2 = last ? nB : cB + (size_t)(t + 2) * kstep;
;             const char* a3 = a2 + kstep; const char* b3 = b2 + kstep;
;             if constexpr (SP2) {
;             PG8_LDB(B0, 0, 0); PG8_LDB(B1, 0, 1); PG8_SCHED; PG8_LDA(At, 0, 0); PG8_STAGE(PG8_SA(1, 1), a1 + hstepA, voffA);
;             PG8_WAIT_V(8); PG8_WAIT_L(0); PG8_BAR; PG8_MMA(0, 0, At, B0); PG8_MMA(0, 1, At, B1); PG8_BAR; PG8_SCHED;
;             PG8_LDA(At, 0, 1); PG8_STAGE(PG8_SB(0, 0), b2, voffB); PG8_STAGE(PG8_SB(0, 1), b2 + hstepB, voffB); PG8_STAGE(PG8_SA(0, 0), a2, voffA);
;             PG8_WAIT_V(8); PG8_WAIT_L(0); PG8_BAR; PG8_MMA(1, 0, At, B0); PG8_MMA(1, 1, At, B1); PG8_BAR; PG8_SCHED;
.LBB0_1003:
	ds_read_b128 v[96:99], v226
	ds_read_b128 v[100:103], v226 offset:1024
	ds_read_b128 v[104:107], v226 offset:2048
	ds_read_b128 v[108:111], v226 offset:3072
	ds_read_b128 v[112:115], v227
	ds_read_b128 v[116:119], v227 offset:1024
	ds_read_b128 v[154:157], v227 offset:2048
	ds_read_b128 v[158:161], v227 offset:3072
	s_add_u32 s3, s0, 0xfff80080
	s_addc_u32 s8, s1, -1
	s_cmp_eq_u32 s66, 28
	s_cselect_b32 s37, s2, s8
	s_cselect_b32 s36, s39, s3
	s_cselect_b32 s9, s35, s65
	s_cselect_b32 s8, s63, s64
	s_add_i32 m0, s50, 0xc000
	ds_read_b128 v[162:165], v228
	ds_read_b128 v[166:169], v228 offset:1024
	ds_read_b128 v[170:173], v228 offset:2048
	ds_read_b128 v[174:177], v228 offset:3072
	ds_read_b128 v[178:181], v228 offset:4096
	ds_read_b128 v[182:185], v228 offset:5120
	ds_read_b128 v[202:205], v228 offset:6144
	ds_read_b128 v[206:209], v228 offset:7168
	global_load_lds_dwordx4 v194, s[0:1]
	s_add_i32 m0, s50, 0xe000
	s_nop 0
	global_load_lds_dwordx4 v196, s[0:1]
	s_waitcnt vmcnt(8)
	s_waitcnt lgkmcnt(0)
	s_barrier
	s_setprio 1
	v_mfma_f32_16x16x32_bf16 v[150:153], v[96:99], v[162:165], v[150:153]
	v_mfma_f32_16x16x32_bf16 v[146:149], v[104:107], v[162:165], v[146:149]
	v_mfma_f32_16x16x32_bf16 v[142:145], v[96:99], v[170:173], v[142:145]
	v_mfma_f32_16x16x32_bf16 v[138:141], v[104:107], v[170:173], v[138:141]
	v_mfma_f32_16x16x32_bf16 v[134:137], v[96:99], v[178:181], v[134:137]
	v_mfma_f32_16x16x32_bf16 v[130:133], v[104:107], v[178:181], v[130:133]
	v_mfma_f32_16x16x32_bf16 v[126:129], v[96:99], v[202:205], v[126:129]
	v_mfma_f32_16x16x32_bf16 v[120:123], v[104:107], v[202:205], v[122:125]
	v_mfma_f32_16x16x32_bf16 v[150:153], v[100:103], v[166:169], v[150:153]
	v_mfma_f32_16x16x32_bf16 v[146:149], v[108:111], v[166:169], v[146:149]
	v_mfma_f32_16x16x32_bf16 v[142:145], v[100:103], v[174:177], v[142:145]
	v_mfma_f32_16x16x32_bf16 v[138:141], v[108:111], v[174:177], v[138:141]
	v_mfma_f32_16x16x32_bf16 v[134:137], v[100:103], v[182:185], v[134:137]
	v_mfma_f32_16x16x32_bf16 v[130:133], v[108:111], v[182:185], v[130:133]
	v_mfma_f32_16x16x32_bf16 v[126:129], v[100:103], v[206:209], v[126:129]
	v_mfma_f32_16x16x32_bf16 v[120:123], v[108:111], v[206:209], v[120:123]
	s_setprio 0
	s_setprio 1
	v_mfma_f32_16x16x32_bf16 v[60:63], v[112:115], v[162:165], v[60:63]
	v_mfma_f32_16x16x32_bf16 v[56:59], v[154:157], v[162:165], v[56:59]
	v_mfma_f32_16x16x32_bf16 v[52:55], v[112:115], v[170:173], v[52:55]
	v_mfma_f32_16x16x32_bf16 v[48:51], v[154:157], v[170:173], v[48:51]
	v_mfma_f32_16x16x32_bf16 v[44:47], v[112:115], v[178:181], v[44:47]
	v_mfma_f32_16x16x32_bf16 v[40:43], v[154:157], v[178:181], v[40:43]
	v_mfma_f32_16x16x32_bf16 v[36:39], v[112:115], v[202:205], v[36:39]
	v_mfma_f32_16x16x32_bf16 v[32:35], v[154:157], v[202:205], v[32:35]
	v_mfma_f32_16x16x32_bf16 v[60:63], v[116:119], v[166:169], v[60:63]
	v_mfma_f32_16x16x32_bf16 v[56:59], v[158:161], v[166:169], v[56:59]
	v_mfma_f32_16x16x32_bf16 v[52:55], v[116:119], v[174:177], v[52:55]
	v_mfma_f32_16x16x32_bf16 v[48:51], v[158:161], v[174:177], v[48:51]
	v_mfma_f32_16x16x32_bf16 v[44:47], v[116:119], v[182:185], v[44:47]
	v_mfma_f32_16x16x32_bf16 v[40:43], v[158:161], v[182:185], v[40:43]
	v_mfma_f32_16x16x32_bf16 v[36:39], v[116:119], v[206:209], v[36:39]
	v_mfma_f32_16x16x32_bf16 v[32:35], v[158:161], v[206:209], v[32:35]
	s_setprio 0
	s_barrier
	s_add_i32 s3, s58, s47
	s_add_u32 s98, s8, s24
	s_addc_u32 s99, s9, s25
	s_mov_b32 m0, s3
	ds_read_b128 v[162:165], v228 offset:16384
	ds_read_b128 v[166:169], v228 offset:17408
	ds_read_b128 v[170:173], v228 offset:18432
	ds_read_b128 v[174:177], v228 offset:19456
	ds_read_b128 v[178:181], v228 offset:20480
	ds_read_b128 v[182:185], v228 offset:21504
	ds_read_b128 v[202:205], v228 offset:22528
	ds_read_b128 v[206:209], v228 offset:23552
	global_load_lds_dwordx4 v190, s[8:9]
	s_add_i32 m0, s3, 0x2000
	s_add_u32 s68, s8, 0x80000
	s_addc_u32 s69, s9, 0
	s_add_i32 s3, s59, s47
	global_load_lds_dwordx4 v186, s[8:9]
	s_mov_b32 m0, s3
	s_add_u32 s100, s36, s24
	s_addc_u32 s101, s37, s25
	global_load_lds_dwordx4 v190, s[68:69]
	s_add_i32 m0, s3, 0x2000
	s_nop 0
	global_load_lds_dwordx4 v186, s[68:69]
	s_mov_b32 m0, s50
	s_nop 0
	global_load_lds_dwordx4 v192, s[36:37]
	s_mov_b32 m0, s51
	s_nop 0
	global_load_lds_dwordx4 v188, s[36:37]
	s_waitcnt vmcnt(8)
	s_waitcnt lgkmcnt(0)
	s_barrier
	s_setprio 1
	v_mfma_f32_16x16x32_bf16 v[92:95], v[96:99], v[162:165], v[92:95]
	v_mfma_f32_16x16x32_bf16 v[88:91], v[104:107], v[162:165], v[88:91]
	v_mfma_f32_16x16x32_bf16 v[84:87], v[96:99], v[170:173], v[84:87]
	v_mfma_f32_16x16x32_bf16 v[80:83], v[104:107], v[170:173], v[80:83]
	v_mfma_f32_16x16x32_bf16 v[76:79], v[96:99], v[178:181], v[76:79]
	v_mfma_f32_16x16x32_bf16 v[72:75], v[104:107], v[178:181], v[72:75]
	v_mfma_f32_16x16x32_bf16 v[68:71], v[96:99], v[202:205], v[68:71]
	v_mfma_f32_16x16x32_bf16 v[64:67], v[104:107], v[202:205], v[64:67]
	v_mfma_f32_16x16x32_bf16 v[92:95], v[100:103], v[166:169], v[92:95]
	v_mfma_f32_16x16x32_bf16 v[88:91], v[108:111], v[166:169], v[88:91]
	v_mfma_f32_16x16x32_bf16 v[84:87], v[100:103], v[174:177], v[84:87]
	v_mfma_f32_16x16x32_bf16 v[80:83], v[108:111], v[174:177], v[80:83]
	v_mfma_f32_16x16x32_bf16 v[76:79], v[100:103], v[182:185], v[76:79]
	v_mfma_f32_16x16x32_bf16 v[72:75], v[108:111], v[182:185], v[72:75]
	v_mfma_f32_16x16x32_bf16 v[68:71], v[100:103], v[206:209], v[68:71]
	v_mfma_f32_16x16x32_bf16 v[64:67], v[108:111], v[206:209], v[64:67]
	s_setprio 0
	s_setprio 1
	v_mfma_f32_16x16x32_bf16 v[28:31], v[112:115], v[162:165], v[28:31]
	v_mfma_f32_16x16x32_bf16 v[24:27], v[154:157], v[162:165], v[24:27]
	v_mfma_f32_16x16x32_bf16 v[20:23], v[112:115], v[170:173], v[20:23]
	v_mfma_f32_16x16x32_bf16 v[16:19], v[154:157], v[170:173], v[16:19]
	v_mfma_f32_16x16x32_bf16 v[12:15], v[112:115], v[178:181], v[12:15]
	v_mfma_f32_16x16x32_bf16 v[8:11], v[154:157], v[178:181], v[8:11]
	v_mfma_f32_16x16x32_bf16 v[4:7], v[112:115], v[202:205], v[4:7]
	v_mfma_f32_16x16x32_bf16 v[0:3], v[154:157], v[202:205], v[0:3]
	v_mfma_f32_16x16x32_bf16 v[28:31], v[116:119], v[166:169], v[28:31]
	v_mfma_f32_16x16x32_bf16 v[24:27], v[158:161], v[166:169], v[24:27]
	v_mfma_f32_16x16x32_bf16 v[20:23], v[116:119], v[174:177], v[20:23]
	v_mfma_f32_16x16x32_bf16 v[16:19], v[158:161], v[174:177], v[16:19]
	v_mfma_f32_16x16x32_bf16 v[12:15], v[116:119], v[182:185], v[12:15]
	v_mfma_f32_16x16x32_bf16 v[8:11], v[158:161], v[182:185], v[8:11]
	v_mfma_f32_16x16x32_bf16 v[4:7], v[116:119], v[206:209], v[4:7]
	v_mfma_f32_16x16x32_bf16 v[0:3], v[158:161], v[206:209], v[0:3]
	s_setprio 0
	s_barrier
; #define PG8_STAGE(bufoff, gbase, voff) do { _Pragma("unroll") for (int _i = 0; _i < 2; ++_i) \
;         __builtin_amdgcn_global_load_lds((const unsigned*)((const char*)(gbase) + (voff)[_i]), (LAS unsigned*)(lds + (bufoff) + ldsw + _i * 8192), 16, 0, 0); } while (0)
; #define PG8_WAIT_V(n) asm volatile("s_waitcnt vmcnt(" #n ")" ::: "memory")
; template <class Epi, class Sched, bool SP2 = PG8_SP2>
; __device__ __forceinline__ void gemm_phase(LAS unsigned char* lds, const Gemm g, const Sched& S, const Epi& E) {
;     ...
;             PG8_LDB(B0, 1, 0); PG8_LDB(B1, 1, 1); PG8_SCHED; PG8_LDA(At, 1, 0); PG8_STAGE(PG8_SA(0, 1), a2 + hstepA, voffA);
;             PG8_WAIT_V(8); PG8_WAIT_L(0); PG8_BAR; PG8_MMA(0, 0, At, B0); PG8_MMA(0, 1, At, B1); PG8_BAR; PG8_SCHED;
;             PG8_LDA(At, 1, 1); PG8_STAGE(PG8_SB(1, 0), b3, voffB); PG8_STAGE(PG8_SB(1, 1), b3 + hstepB, voffB); PG8_STAGE(PG8_SA(1, 0), a3, voffA);
;             PG8_WAIT_V(8); PG8_WAIT_L(0); PG8_BAR; PG8_MMA(1, 0, At, B0); PG8_MMA(1, 1, At, B1); PG8_BAR; PG8_SCHED;
;             } else {
;             PG8_LDB(B0, 0, 0); PG8_SCHED; PG8_LDA(At, 0, 0); PG8_STAGE(PG8_SA(1, 1), a1 + hstepA, voffA);
;             PG8_WAIT_L(8); PG8_BAR; PG8_WAIT_L(0); PG8_MMA(0, 0, At, B0); PG8_BAR; PG8_SCHED;
;             PG8_LDB(B1, 0, 1); PG8_STAGE(PG8_SB(0, 0), b2, voffB);
;             PG8_BAR; PG8_WAIT_L(0); PG8_MMA(0, 1, At, B1); PG8_BAR;
;             PG8_LDA(At, 0, 1); PG8_STAGE(PG8_SA(0, 0), a2, voffA);
;             PG8_BAR; PG8_WAIT_L(0); PG8_MMA(1, 0, At, B0); PG8_BAR; PG8_SCHED;
;             PG8_STAGE(PG8_SB(0, 1), b2 + hstepB, voffB);
;             PG8_WAIT_V(6); PG8_BAR; PG8_MMA(1, 1, At, B1); PG8_BAR;
;             PG8_LDB(B0, 1, 0); PG8_SCHED; PG8_LDA(At, 1, 0); PG8_STAGE(PG8_SA(0, 1), a2 + hstepA, voffA);
;             PG8_WAIT_L(8); PG8_BAR; PG8_WAIT_L(0); PG8_MMA(0, 0, At, B0); PG8_BAR; PG8_SCHED;
;             PG8_LDB(B1, 1, 1); PG8_STAGE(PG8_SB(1, 0), b3, voffB);
;             PG8_BAR; PG8_WAIT_L(0); PG8_MMA(0, 1, At, B1); PG8_BAR;
;             PG8_LDA(At, 1, 1); PG8_STAGE(PG8_SA(1, 0), a3, voffA);
;             PG8_BAR; PG8_WAIT_L(0); PG8_MMA(1, 0, At, B0); PG8_BAR; PG8_SCHED;
;             PG8_STAGE(PG8_SB(1, 1), b3 + hstepB, voffB);
;             PG8_WAIT_V(6); PG8_BAR; PG8_MMA(1, 1, At, B1); PG8_BAR;
;             }
;         }
;         if (wr == 0) PG8_BAR;
	s_add_i32 s3, 0, 0x18000
	s_add_i32 s67, 0, 0x1c000
	v_add_u32_e32 v108, s3, v224
	v_add_u32_e32 v124, s67, v224
	ds_read_b128 v[96:99], v108
	ds_read_b128 v[100:103], v108 offset:1024
	ds_read_b128 v[104:107], v108 offset:2048
	ds_read_b128 v[108:111], v108 offset:3072
	ds_read_b128 v[112:115], v124
	ds_read_b128 v[116:119], v124 offset:1024
	ds_read_b128 v[154:157], v124 offset:2048
	ds_read_b128 v[158:161], v124 offset:3072
	s_add_u32 s36, s36, 0x80000
	s_addc_u32 s37, s37, 0
	s_mov_b32 m0, s52
	ds_read_b128 v[162:165], v228 offset:32768
	ds_read_b128 v[166:169], v228 offset:33792
	ds_read_b128 v[170:173], v228 offset:34816
	ds_read_b128 v[174:177], v228 offset:35840
	ds_read_b128 v[178:181], v228 offset:36864
	ds_read_b128 v[182:185], v228 offset:37888
	ds_read_b128 v[202:205], v228 offset:38912
	ds_read_b128 v[206:209], v228 offset:39936
	global_load_lds_dwordx4 v192, s[36:37]
	s_mov_b32 m0, s53
	s_nop 0
	global_load_lds_dwordx4 v188, s[36:37]
	s_waitcnt vmcnt(8)
	s_waitcnt lgkmcnt(0)
	s_barrier
	s_setprio 1
	v_mfma_f32_16x16x32_bf16 v[150:153], v[96:99], v[162:165], v[150:153]
	v_mfma_f32_16x16x32_bf16 v[146:149], v[104:107], v[162:165], v[146:149]
	v_mfma_f32_16x16x32_bf16 v[142:145], v[96:99], v[170:173], v[142:145]
	v_mfma_f32_16x16x32_bf16 v[138:141], v[104:107], v[170:173], v[138:141]
	v_mfma_f32_16x16x32_bf16 v[134:137], v[96:99], v[178:181], v[134:137]
	v_mfma_f32_16x16x32_bf16 v[130:133], v[104:107], v[178:181], v[130:133]
	v_mfma_f32_16x16x32_bf16 v[124:127], v[96:99], v[202:205], v[126:129]
	v_mfma_f32_16x16x32_bf16 v[120:123], v[104:107], v[202:205], v[120:123]
	v_mfma_f32_16x16x32_bf16 v[150:153], v[100:103], v[166:169], v[150:153]
	v_mfma_f32_16x16x32_bf16 v[146:149], v[108:111], v[166:169], v[146:149]
	v_mfma_f32_16x16x32_bf16 v[142:145], v[100:103], v[174:177], v[142:145]
	v_mfma_f32_16x16x32_bf16 v[138:141], v[108:111], v[174:177], v[138:141]
	v_mfma_f32_16x16x32_bf16 v[134:137], v[100:103], v[182:185], v[134:137]
	v_mfma_f32_16x16x32_bf16 v[130:133], v[108:111], v[182:185], v[130:133]
	v_mfma_f32_16x16x32_bf16 v[126:129], v[100:103], v[206:209], v[124:127]
	v_mfma_f32_16x16x32_bf16 v[122:125], v[108:111], v[206:209], v[120:123]
	s_setprio 0
	s_setprio 1
	v_mfma_f32_16x16x32_bf16 v[60:63], v[112:115], v[162:165], v[60:63]
	v_mfma_f32_16x16x32_bf16 v[56:59], v[154:157], v[162:165], v[56:59]
	v_mfma_f32_16x16x32_bf16 v[52:55], v[112:115], v[170:173], v[52:55]
	v_mfma_f32_16x16x32_bf16 v[48:51], v[154:157], v[170:173], v[48:51]
	v_mfma_f32_16x16x32_bf16 v[44:47], v[112:115], v[178:181], v[44:47]
	v_mfma_f32_16x16x32_bf16 v[40:43], v[154:157], v[178:181], v[40:43]
	v_mfma_f32_16x16x32_bf16 v[36:39], v[112:115], v[202:205], v[36:39]
	v_mfma_f32_16x16x32_bf16 v[32:35], v[154:157], v[202:205], v[32:35]
	v_mfma_f32_16x16x32_bf16 v[60:63], v[116:119], v[166:169], v[60:63]
	v_mfma_f32_16x16x32_bf16 v[56:59], v[158:161], v[166:169], v[56:59]
	v_mfma_f32_16x16x32_bf16 v[52:55], v[116:119], v[174:177], v[52:55]
	v_mfma_f32_16x16x32_bf16 v[48:51], v[158:161], v[174:177], v[48:51]
	v_mfma_f32_16x16x32_bf16 v[44:47], v[116:119], v[182:185], v[44:47]
	v_mfma_f32_16x16x32_bf16 v[40:43], v[158:161], v[182:185], v[40:43]
	v_mfma_f32_16x16x32_bf16 v[36:39], v[116:119], v[206:209], v[36:39]
	v_mfma_f32_16x16x32_bf16 v[32:35], v[158:161], v[206:209], v[32:35]
	s_setprio 0
	s_barrier
	s_add_i32 s3, s3, s47
	s_mov_b32 m0, s3
	ds_read_b128 v[162:165], v228 offset:49152
	ds_read_b128 v[166:169], v228 offset:50176
	ds_read_b128 v[170:173], v228 offset:51200
	ds_read_b128 v[174:177], v228 offset:52224
	ds_read_b128 v[178:181], v228 offset:53248
	ds_read_b128 v[182:185], v228 offset:54272
	ds_read_b128 v[202:205], v228 offset:55296
	ds_read_b128 v[206:209], v228 offset:56320
	global_load_lds_dwordx4 v190, s[98:99]
	s_add_i32 m0, s3, 0x2000
	s_add_u32 s8, s8, 0x80080
	s_addc_u32 s9, s9, 0
	s_add_i32 s3, s67, s47
	global_load_lds_dwordx4 v186, s[98:99]
	s_mov_b32 m0, s3
	s_nop 0
	global_load_lds_dwordx4 v190, s[8:9]
	s_add_i32 m0, s3, 0x2000
	s_nop 0
	global_load_lds_dwordx4 v186, s[8:9]
	s_mov_b32 m0, s55
	s_nop 0
	global_load_lds_dwordx4 v192, s[100:101]
	s_mov_b32 m0, s56
	s_nop 0
	global_load_lds_dwordx4 v188, s[100:101]
	s_waitcnt vmcnt(8)
	s_waitcnt lgkmcnt(0)
	s_barrier
	s_setprio 1
	v_mfma_f32_16x16x32_bf16 v[92:95], v[96:99], v[162:165], v[92:95]
	v_mfma_f32_16x16x32_bf16 v[88:91], v[104:107], v[162:165], v[88:91]
	v_mfma_f32_16x16x32_bf16 v[84:87], v[96:99], v[170:173], v[84:87]
	v_mfma_f32_16x16x32_bf16 v[80:83], v[104:107], v[170:173], v[80:83]
	v_mfma_f32_16x16x32_bf16 v[76:79], v[96:99], v[178:181], v[76:79]
	v_mfma_f32_16x16x32_bf16 v[72:75], v[104:107], v[178:181], v[72:75]
	v_mfma_f32_16x16x32_bf16 v[68:71], v[96:99], v[202:205], v[68:71]
	v_mfma_f32_16x16x32_bf16 v[64:67], v[104:107], v[202:205], v[64:67]
	v_mfma_f32_16x16x32_bf16 v[92:95], v[100:103], v[166:169], v[92:95]
	v_mfma_f32_16x16x32_bf16 v[88:91], v[108:111], v[166:169], v[88:91]
	v_mfma_f32_16x16x32_bf16 v[84:87], v[100:103], v[174:177], v[84:87]
	v_mfma_f32_16x16x32_bf16 v[80:83], v[108:111], v[174:177], v[80:83]
	v_mfma_f32_16x16x32_bf16 v[76:79], v[100:103], v[182:185], v[76:79]
	v_mfma_f32_16x16x32_bf16 v[72:75], v[108:111], v[182:185], v[72:75]
	v_mfma_f32_16x16x32_bf16 v[68:71], v[100:103], v[206:209], v[68:71]
	v_mfma_f32_16x16x32_bf16 v[64:67], v[108:111], v[206:209], v[64:67]
	s_setprio 0
	s_setprio 1
	v_mfma_f32_16x16x32_bf16 v[28:31], v[112:115], v[162:165], v[28:31]
	v_mfma_f32_16x16x32_bf16 v[24:27], v[154:157], v[162:165], v[24:27]
	v_mfma_f32_16x16x32_bf16 v[20:23], v[112:115], v[170:173], v[20:23]
	v_mfma_f32_16x16x32_bf16 v[16:19], v[154:157], v[170:173], v[16:19]
	v_mfma_f32_16x16x32_bf16 v[12:15], v[112:115], v[178:181], v[12:15]
	v_mfma_f32_16x16x32_bf16 v[8:11], v[154:157], v[178:181], v[8:11]
	v_mfma_f32_16x16x32_bf16 v[4:7], v[112:115], v[202:205], v[4:7]
	v_mfma_f32_16x16x32_bf16 v[0:3], v[154:157], v[202:205], v[0:3]
	v_mfma_f32_16x16x32_bf16 v[28:31], v[116:119], v[166:169], v[28:31]
	v_mfma_f32_16x16x32_bf16 v[24:27], v[158:161], v[166:169], v[24:27]
	v_mfma_f32_16x16x32_bf16 v[20:23], v[116:119], v[174:177], v[20:23]
	v_mfma_f32_16x16x32_bf16 v[16:19], v[158:161], v[174:177], v[16:19]
	v_mfma_f32_16x16x32_bf16 v[12:15], v[116:119], v[182:185], v[12:15]
	v_mfma_f32_16x16x32_bf16 v[8:11], v[158:161], v[182:185], v[8:11]
	v_mfma_f32_16x16x32_bf16 v[4:7], v[116:119], v[206:209], v[4:7]
	v_mfma_f32_16x16x32_bf16 v[0:3], v[158:161], v[206:209], v[0:3]
	s_setprio 0
	s_barrier
	s_add_i32 s66, s66, 2
	s_add_u32 s0, s0, 0x100
	s_addc_u32 s1, s1, 0
	s_add_u32 s64, s64, 0x100
	s_addc_u32 s65, s65, 0
	s_cmp_gt_u32 s66, 29
	s_cbranch_scc0 .LBB0_1003
	s_and_b64 vcc, exec, s[26:27]
	s_cbranch_vccz .LBB0_1006
	s_barrier

; #define PG8_STAGE(bufoff, gbase, voff) do { _Pragma("unroll") for (int _i = 0; _i < 2; ++_i) \
;         __builtin_amdgcn_global_load_lds((const unsigned*)((const char*)(gbase) + (voff)[_i]), (LAS unsigned*)(lds + (bufoff) + ldsw + _i * 8192), 16, 0, 0); } while (0)
; #define PG8_LDA(dst, b, h) do { _Pragma("unroll") for (int m = 0; m < 4; ++m) _Pragma("unroll") for (int k = 0; k < 2; ++k) dst[m][k] = *(const LAS bf16x8*)(lds + PG8_SA(b, h) + aoff + m * 2048 + k * 1024); } while (0)
; #define PG8_LDB(dst, b, h) do { _Pragma("unroll") for (int n = 0; n < 2; ++n) _Pragma("unroll") for (int k = 0; k < 2; ++k) dst[n][k] = *(const LAS bf16x8*)(lds + PG8_SB(b, h) + boff + n * 2048 + k * 1024); } while (0)
; #define PG8_MMA(ai, bj, At, Bt) do { __builtin_amdgcn_s_setprio(1); _Pragma("unroll") for (int m = 0; m < 4; ++m) _Pragma("unroll") for (int n = 0; n < 2; ++n) _Pragma("unroll") for (int k = 0; k < 2; ++k) \
;         acc[ai][bj][m][n] = __builtin_amdgcn_mfma_f32_16x16x32_bf16(Bt[n][k], At[m][k], acc[ai][bj][m][n], 0, 0, 0); __builtin_amdgcn_s_setprio(0); } while (0)
; #define PG8_WAIT_V(n) asm volatile("s_waitcnt vmcnt(" #n ")" ::: "memory")
; #define PG8_WAIT_L(n) asm volatile("s_waitcnt lgkmcnt(" #n ")" ::: "memory")
; #define PG8_BAR __builtin_amdgcn_s_barrier()
; template <class Epi, class Sched, bool SP2 = PG8_SP2>
; __device__ __forceinline__ void gemm_phase(LAS unsigned char* lds, const Gemm g, const Sched& S, const Epi& E) {
;     ...
;         for (int t = 0; t < nt; t += 2) {
;             const bool last = (t == nt - 2);
;             const char* a1 = cA + (size_t)(t + 1) * kstep;
;             const char* a2 = last ? nA : cA + (size_t)(t + 2) * kstep; const char* b2 = last ? nB : cB + (size_t)(t + 2) * kstep;
;             const char* a3 = a2 + kstep; const char* b3 = b2 + kstep;
;             if constexpr (SP2) {
;             PG8_LDB(B0, 0, 0); PG8_LDB(B1, 0, 1); PG8_SCHED; PG8_LDA(At, 0, 0); PG8_STAGE(PG8_SA(1, 1), a1 + hstepA, voffA);
;             PG8_WAIT_V(8); PG8_WAIT_L(0); PG8_BAR; PG8_MMA(0, 0, At, B0); PG8_MMA(0, 1, At, B1); PG8_BAR; PG8_SCHED;
;             PG8_LDA(At, 0, 1); PG8_STAGE(PG8_SB(0, 0), b2, voffB); PG8_STAGE(PG8_SB(0, 1), b2 + hstepB, voffB); PG8_STAGE(PG8_SA(0, 0), a2, voffA);
;             PG8_WAIT_V(8); PG8_WAIT_L(0); PG8_BAR; PG8_MMA(1, 0, At, B0); PG8_MMA(1, 1, At, B1); PG8_BAR; PG8_SCHED;
.LBB0_1090:
	ds_read_b128 v[148:151], v145
	ds_read_b128 v[152:155], v145 offset:1024
	ds_read_b128 v[156:159], v145 offset:2048
	ds_read_b128 v[160:163], v145 offset:3072
	ds_read_b128 v[164:167], v146
	ds_read_b128 v[168:171], v146 offset:1024
	ds_read_b128 v[172:175], v146 offset:2048
	ds_read_b128 v[176:179], v146 offset:3072
	s_add_u32 s3, s24, 0xffea0080
	s_addc_u32 s26, s25, -1
	s_cmpk_eq_i32 s56, 0x54
	s_cselect_b32 s29, s5, s26
	s_cselect_b32 s28, s4, s3
	s_cselect_b32 s27, s23, s55
	s_cselect_b32 s26, s22, s2
	s_add_i32 m0, s37, 0xc000
	ds_read_b128 v[180:183], v147
	ds_read_b128 v[184:187], v147 offset:1024
	ds_read_b128 v[188:191], v147 offset:2048
	ds_read_b128 v[192:195], v147 offset:3072
	ds_read_b128 v[196:199], v147 offset:4096
	ds_read_b128 v[200:203], v147 offset:5120
	ds_read_b128 v[204:207], v147 offset:6144
	ds_read_b128 v[208:211], v147 offset:7168
	global_load_lds_dwordx4 v132, s[24:25]
	s_add_i32 m0, s37, 0xe000
	s_nop 0
	global_load_lds_dwordx4 v134, s[24:25]
	s_waitcnt vmcnt(8)
	s_waitcnt lgkmcnt(0)
	s_barrier
	s_setprio 1
	v_mfma_f32_16x16x32_bf16 v[124:127], v[148:151], v[180:183], v[124:127]
	v_mfma_f32_16x16x32_bf16 v[120:123], v[156:159], v[180:183], v[120:123]
	v_mfma_f32_16x16x32_bf16 v[116:119], v[148:151], v[188:191], v[116:119]
	v_mfma_f32_16x16x32_bf16 v[112:115], v[156:159], v[188:191], v[112:115]
	v_mfma_f32_16x16x32_bf16 v[92:95], v[148:151], v[196:199], v[92:95]
	v_mfma_f32_16x16x32_bf16 v[88:91], v[156:159], v[196:199], v[88:91]
	v_mfma_f32_16x16x32_bf16 v[84:87], v[148:151], v[204:207], v[84:87]
	v_mfma_f32_16x16x32_bf16 v[80:83], v[156:159], v[204:207], v[80:83]
	v_mfma_f32_16x16x32_bf16 v[124:127], v[152:155], v[184:187], v[124:127]
	v_mfma_f32_16x16x32_bf16 v[120:123], v[160:163], v[184:187], v[120:123]
	v_mfma_f32_16x16x32_bf16 v[116:119], v[152:155], v[192:195], v[116:119]
	v_mfma_f32_16x16x32_bf16 v[112:115], v[160:163], v[192:195], v[112:115]
	v_mfma_f32_16x16x32_bf16 v[92:95], v[152:155], v[200:203], v[92:95]
	v_mfma_f32_16x16x32_bf16 v[88:91], v[160:163], v[200:203], v[88:91]
	v_mfma_f32_16x16x32_bf16 v[84:87], v[152:155], v[208:211], v[84:87]
	v_mfma_f32_16x16x32_bf16 v[80:83], v[160:163], v[208:211], v[80:83]
	s_setprio 0
	s_setprio 1
	v_mfma_f32_16x16x32_bf16 v[108:111], v[164:167], v[180:183], v[108:111]
	v_mfma_f32_16x16x32_bf16 v[104:107], v[172:175], v[180:183], v[104:107]
	v_mfma_f32_16x16x32_bf16 v[100:103], v[164:167], v[188:191], v[100:103]
	v_mfma_f32_16x16x32_bf16 v[96:99], v[172:175], v[188:191], v[96:99]
	v_mfma_f32_16x16x32_bf16 v[76:79], v[164:167], v[196:199], v[76:79]
	v_mfma_f32_16x16x32_bf16 v[72:75], v[172:175], v[196:199], v[72:75]
	v_mfma_f32_16x16x32_bf16 v[68:71], v[164:167], v[204:207], v[68:71]
	v_mfma_f32_16x16x32_bf16 v[64:67], v[172:175], v[204:207], v[64:67]
	v_mfma_f32_16x16x32_bf16 v[108:111], v[168:171], v[184:187], v[108:111]
	v_mfma_f32_16x16x32_bf16 v[104:107], v[176:179], v[184:187], v[104:107]
	v_mfma_f32_16x16x32_bf16 v[100:103], v[168:171], v[192:195], v[100:103]
	v_mfma_f32_16x16x32_bf16 v[96:99], v[176:179], v[192:195], v[96:99]
	v_mfma_f32_16x16x32_bf16 v[76:79], v[168:171], v[200:203], v[76:79]
	v_mfma_f32_16x16x32_bf16 v[72:75], v[176:179], v[200:203], v[72:75]
	v_mfma_f32_16x16x32_bf16 v[68:71], v[168:171], v[208:211], v[68:71]
	v_mfma_f32_16x16x32_bf16 v[64:67], v[176:179], v[208:211], v[64:67]
	s_setprio 0
	s_barrier
	s_add_i32 s3, s45, s36
	s_add_u32 s98, s26, s12
	s_addc_u32 s99, s27, s13
	s_mov_b32 m0, s3
	ds_read_b128 v[180:183], v147 offset:16384
	ds_read_b128 v[184:187], v147 offset:17408
	ds_read_b128 v[188:191], v147 offset:18432
	ds_read_b128 v[192:195], v147 offset:19456
	ds_read_b128 v[196:199], v147 offset:20480
	ds_read_b128 v[200:203], v147 offset:21504
	ds_read_b128 v[204:207], v147 offset:22528
	ds_read_b128 v[208:211], v147 offset:23552
	global_load_lds_dwordx4 v128, s[26:27]
	s_add_i32 m0, s3, 0x2000
	s_add_u32 s58, s26, 0x160000
	s_addc_u32 s59, s27, 0
	s_add_i32 s3, s46, s36
	global_load_lds_dwordx4 v130, s[26:27]
	s_mov_b32 m0, s3
	s_nop 0
	global_load_lds_dwordx4 v128, s[58:59]
	s_add_i32 m0, s3, 0x2000
	s_nop 0
	global_load_lds_dwordx4 v130, s[58:59]
	s_add_u32 s100, s28, s12
	s_addc_u32 s101, s29, s13
	s_mov_b32 m0, s37
	s_nop 0
	global_load_lds_dwordx4 v128, s[28:29]
	s_mov_b32 m0, s38
	s_nop 0
	global_load_lds_dwordx4 v130, s[28:29]
	s_waitcnt vmcnt(8)
	s_waitcnt lgkmcnt(0)
	s_barrier
	s_setprio 1
	v_mfma_f32_16x16x32_bf16 v[60:63], v[148:151], v[180:183], v[60:63]
	v_mfma_f32_16x16x32_bf16 v[56:59], v[156:159], v[180:183], v[56:59]
	v_mfma_f32_16x16x32_bf16 v[52:55], v[148:151], v[188:191], v[52:55]
	v_mfma_f32_16x16x32_bf16 v[48:51], v[156:159], v[188:191], v[48:51]
	v_mfma_f32_16x16x32_bf16 v[28:31], v[148:151], v[196:199], v[28:31]
	v_mfma_f32_16x16x32_bf16 v[24:27], v[156:159], v[196:199], v[24:27]
	v_mfma_f32_16x16x32_bf16 v[20:23], v[148:151], v[204:207], v[20:23]
	v_mfma_f32_16x16x32_bf16 v[16:19], v[156:159], v[204:207], v[16:19]
	v_mfma_f32_16x16x32_bf16 v[60:63], v[152:155], v[184:187], v[60:63]
	v_mfma_f32_16x16x32_bf16 v[56:59], v[160:163], v[184:187], v[56:59]
	v_mfma_f32_16x16x32_bf16 v[52:55], v[152:155], v[192:195], v[52:55]
	v_mfma_f32_16x16x32_bf16 v[48:51], v[160:163], v[192:195], v[48:51]
	v_mfma_f32_16x16x32_bf16 v[28:31], v[152:155], v[200:203], v[28:31]
	v_mfma_f32_16x16x32_bf16 v[24:27], v[160:163], v[200:203], v[24:27]
	v_mfma_f32_16x16x32_bf16 v[20:23], v[152:155], v[208:211], v[20:23]
	v_mfma_f32_16x16x32_bf16 v[16:19], v[160:163], v[208:211], v[16:19]
	s_setprio 0
	s_setprio 1
	v_mfma_f32_16x16x32_bf16 v[44:47], v[164:167], v[180:183], v[44:47]
	v_mfma_f32_16x16x32_bf16 v[40:43], v[172:175], v[180:183], v[40:43]
	v_mfma_f32_16x16x32_bf16 v[36:39], v[164:167], v[188:191], v[36:39]
	v_mfma_f32_16x16x32_bf16 v[32:35], v[172:175], v[188:191], v[32:35]
	v_mfma_f32_16x16x32_bf16 v[12:15], v[164:167], v[196:199], v[12:15]
	v_mfma_f32_16x16x32_bf16 v[8:11], v[172:175], v[196:199], v[8:11]
	v_mfma_f32_16x16x32_bf16 v[4:7], v[164:167], v[204:207], v[4:7]
	v_mfma_f32_16x16x32_bf16 v[0:3], v[172:175], v[204:207], v[0:3]
	v_mfma_f32_16x16x32_bf16 v[44:47], v[168:171], v[184:187], v[44:47]
	v_mfma_f32_16x16x32_bf16 v[40:43], v[176:179], v[184:187], v[40:43]
	v_mfma_f32_16x16x32_bf16 v[36:39], v[168:171], v[192:195], v[36:39]
	v_mfma_f32_16x16x32_bf16 v[32:35], v[176:179], v[192:195], v[32:35]
	v_mfma_f32_16x16x32_bf16 v[12:15], v[168:171], v[200:203], v[12:15]
	v_mfma_f32_16x16x32_bf16 v[8:11], v[176:179], v[200:203], v[8:11]
	v_mfma_f32_16x16x32_bf16 v[4:7], v[168:171], v[208:211], v[4:7]
	v_mfma_f32_16x16x32_bf16 v[0:3], v[176:179], v[208:211], v[0:3]
	s_setprio 0
	s_barrier
; #define PG8_STAGE(bufoff, gbase, voff) do { _Pragma("unroll") for (int _i = 0; _i < 2; ++_i) \
;         __builtin_amdgcn_global_load_lds((const unsigned*)((const char*)(gbase) + (voff)[_i]), (LAS unsigned*)(lds + (bufoff) + ldsw + _i * 8192), 16, 0, 0); } while (0)
; #define PG8_WAIT_V(n) asm volatile("s_waitcnt vmcnt(" #n ")" ::: "memory")
; template <class Epi, class Sched, bool SP2 = PG8_SP2>
; __device__ __forceinline__ void gemm_phase(LAS unsigned char* lds, const Gemm g, const Sched& S, const Epi& E) {
;     ...
;             PG8_LDB(B0, 1, 0); PG8_LDB(B1, 1, 1); PG8_SCHED; PG8_LDA(At, 1, 0); PG8_STAGE(PG8_SA(0, 1), a2 + hstepA, voffA);
;             PG8_WAIT_V(8); PG8_WAIT_L(0); PG8_BAR; PG8_MMA(0, 0, At, B0); PG8_MMA(0, 1, At, B1); PG8_BAR; PG8_SCHED;
;             PG8_LDA(At, 1, 1); PG8_STAGE(PG8_SB(1, 0), b3, voffB); PG8_STAGE(PG8_SB(1, 1), b3 + hstepB, voffB); PG8_STAGE(PG8_SA(1, 0), a3, voffA);
;             PG8_WAIT_V(8); PG8_WAIT_L(0); PG8_BAR; PG8_MMA(1, 0, At, B0); PG8_MMA(1, 1, At, B1); PG8_BAR; PG8_SCHED;
;             } else {
;             PG8_LDB(B0, 0, 0); PG8_SCHED; PG8_LDA(At, 0, 0); PG8_STAGE(PG8_SA(1, 1), a1 + hstepA, voffA);
;             PG8_WAIT_L(8); PG8_BAR; PG8_WAIT_L(0); PG8_MMA(0, 0, At, B0); PG8_BAR; PG8_SCHED;
;             PG8_LDB(B1, 0, 1); PG8_STAGE(PG8_SB(0, 0), b2, voffB);
;             PG8_BAR; PG8_WAIT_L(0); PG8_MMA(0, 1, At, B1); PG8_BAR;
;             PG8_LDA(At, 0, 1); PG8_STAGE(PG8_SA(0, 0), a2, voffA);
;             PG8_BAR; PG8_WAIT_L(0); PG8_MMA(1, 0, At, B0); PG8_BAR; PG8_SCHED;
;             PG8_STAGE(PG8_SB(0, 1), b2 + hstepB, voffB);
;             PG8_WAIT_V(6); PG8_BAR; PG8_MMA(1, 1, At, B1); PG8_BAR;
;             PG8_LDB(B0, 1, 0); PG8_SCHED; PG8_LDA(At, 1, 0); PG8_STAGE(PG8_SA(0, 1), a2 + hstepA, voffA);
;             PG8_WAIT_L(8); PG8_BAR; PG8_WAIT_L(0); PG8_MMA(0, 0, At, B0); PG8_BAR; PG8_SCHED;
;             PG8_LDB(B1, 1, 1); PG8_STAGE(PG8_SB(1, 0), b3, voffB);
;             PG8_BAR; PG8_WAIT_L(0); PG8_MMA(0, 1, At, B1); PG8_BAR;
;             PG8_LDA(At, 1, 1); PG8_STAGE(PG8_SA(1, 0), a3, voffA);
;             PG8_BAR; PG8_WAIT_L(0); PG8_MMA(1, 0, At, B0); PG8_BAR; PG8_SCHED;
;             PG8_STAGE(PG8_SB(1, 1), b3 + hstepB, voffB);
;             PG8_WAIT_V(6); PG8_BAR; PG8_MMA(1, 1, At, B1); PG8_BAR;
;             }
;         }
;         if (wr == 0) PG8_BAR;
	s_add_i32 s3, 0, 0x18000
	s_add_i32 s57, 0, 0x1c000
	v_add_u32_e32 v160, s3, v143
	v_add_u32_e32 v176, s57, v143
	ds_read_b128 v[148:151], v160
	ds_read_b128 v[152:155], v160 offset:1024
	ds_read_b128 v[156:159], v160 offset:2048
	ds_read_b128 v[160:163], v160 offset:3072
	ds_read_b128 v[164:167], v176
	ds_read_b128 v[168:171], v176 offset:1024
	ds_read_b128 v[172:175], v176 offset:2048
	ds_read_b128 v[176:179], v176 offset:3072
	s_add_u32 s28, s28, 0x160000
	s_addc_u32 s29, s29, 0
	s_mov_b32 m0, s39
	ds_read_b128 v[180:183], v147 offset:32768
	ds_read_b128 v[184:187], v147 offset:33792
	ds_read_b128 v[188:191], v147 offset:34816
	ds_read_b128 v[192:195], v147 offset:35840
	ds_read_b128 v[196:199], v147 offset:36864
	ds_read_b128 v[200:203], v147 offset:37888
	ds_read_b128 v[204:207], v147 offset:38912
	ds_read_b128 v[208:211], v147 offset:39936
	global_load_lds_dwordx4 v128, s[28:29]
	s_mov_b32 m0, s40
	s_nop 0
	global_load_lds_dwordx4 v130, s[28:29]
	s_waitcnt vmcnt(8)
	s_waitcnt lgkmcnt(0)
	s_barrier
	s_setprio 1
	v_mfma_f32_16x16x32_bf16 v[124:127], v[148:151], v[180:183], v[124:127]
	v_mfma_f32_16x16x32_bf16 v[120:123], v[156:159], v[180:183], v[120:123]
	v_mfma_f32_16x16x32_bf16 v[116:119], v[148:151], v[188:191], v[116:119]
	v_mfma_f32_16x16x32_bf16 v[112:115], v[156:159], v[188:191], v[112:115]
	v_mfma_f32_16x16x32_bf16 v[92:95], v[148:151], v[196:199], v[92:95]
	v_mfma_f32_16x16x32_bf16 v[88:91], v[156:159], v[196:199], v[88:91]
	v_mfma_f32_16x16x32_bf16 v[84:87], v[148:151], v[204:207], v[84:87]
	v_mfma_f32_16x16x32_bf16 v[80:83], v[156:159], v[204:207], v[80:83]
	v_mfma_f32_16x16x32_bf16 v[124:127], v[152:155], v[184:187], v[124:127]
	v_mfma_f32_16x16x32_bf16 v[120:123], v[160:163], v[184:187], v[120:123]
	v_mfma_f32_16x16x32_bf16 v[116:119], v[152:155], v[192:195], v[116:119]
	v_mfma_f32_16x16x32_bf16 v[112:115], v[160:163], v[192:195], v[112:115]
	v_mfma_f32_16x16x32_bf16 v[92:95], v[152:155], v[200:203], v[92:95]
	v_mfma_f32_16x16x32_bf16 v[88:91], v[160:163], v[200:203], v[88:91]
	v_mfma_f32_16x16x32_bf16 v[84:87], v[152:155], v[208:211], v[84:87]
	v_mfma_f32_16x16x32_bf16 v[80:83], v[160:163], v[208:211], v[80:83]
	s_setprio 0
	s_setprio 1
	v_mfma_f32_16x16x32_bf16 v[108:111], v[164:167], v[180:183], v[108:111]
	v_mfma_f32_16x16x32_bf16 v[104:107], v[172:175], v[180:183], v[104:107]
	v_mfma_f32_16x16x32_bf16 v[100:103], v[164:167], v[188:191], v[100:103]
	v_mfma_f32_16x16x32_bf16 v[96:99], v[172:175], v[188:191], v[96:99]
	v_mfma_f32_16x16x32_bf16 v[76:79], v[164:167], v[196:199], v[76:79]
	v_mfma_f32_16x16x32_bf16 v[72:75], v[172:175], v[196:199], v[72:75]
	v_mfma_f32_16x16x32_bf16 v[68:71], v[164:167], v[204:207], v[68:71]
	v_mfma_f32_16x16x32_bf16 v[64:67], v[172:175], v[204:207], v[64:67]
	v_mfma_f32_16x16x32_bf16 v[108:111], v[168:171], v[184:187], v[108:111]
	v_mfma_f32_16x16x32_bf16 v[104:107], v[176:179], v[184:187], v[104:107]
	v_mfma_f32_16x16x32_bf16 v[100:103], v[168:171], v[192:195], v[100:103]
	v_mfma_f32_16x16x32_bf16 v[96:99], v[176:179], v[192:195], v[96:99]
	v_mfma_f32_16x16x32_bf16 v[76:79], v[168:171], v[200:203], v[76:79]
	v_mfma_f32_16x16x32_bf16 v[72:75], v[176:179], v[200:203], v[72:75]
	v_mfma_f32_16x16x32_bf16 v[68:71], v[168:171], v[208:211], v[68:71]
	v_mfma_f32_16x16x32_bf16 v[64:67], v[176:179], v[208:211], v[64:67]
	s_setprio 0
	s_barrier
	s_add_i32 s3, s3, s36
	s_mov_b32 m0, s3
	ds_read_b128 v[180:183], v147 offset:49152
	ds_read_b128 v[184:187], v147 offset:50176
	ds_read_b128 v[188:191], v147 offset:51200
	ds_read_b128 v[192:195], v147 offset:52224
	ds_read_b128 v[196:199], v147 offset:53248
	ds_read_b128 v[200:203], v147 offset:54272
	ds_read_b128 v[204:207], v147 offset:55296
	ds_read_b128 v[208:211], v147 offset:56320
	global_load_lds_dwordx4 v128, s[98:99]
	s_add_i32 m0, s3, 0x2000
	s_add_u32 s26, s26, 0x160080
	s_addc_u32 s27, s27, 0
	s_add_i32 s3, s57, s36
	global_load_lds_dwordx4 v130, s[98:99]
	s_mov_b32 m0, s3
	s_nop 0
	global_load_lds_dwordx4 v128, s[26:27]
	s_add_i32 m0, s3, 0x2000
	s_nop 0
	global_load_lds_dwordx4 v130, s[26:27]
	s_mov_b32 m0, s42
	s_nop 0
	global_load_lds_dwordx4 v128, s[100:101]
	s_mov_b32 m0, s43
	s_nop 0
	global_load_lds_dwordx4 v130, s[100:101]
	s_waitcnt vmcnt(8)
	s_waitcnt lgkmcnt(0)
	s_barrier
	s_setprio 1
	v_mfma_f32_16x16x32_bf16 v[60:63], v[148:151], v[180:183], v[60:63]
	v_mfma_f32_16x16x32_bf16 v[56:59], v[156:159], v[180:183], v[56:59]
	v_mfma_f32_16x16x32_bf16 v[52:55], v[148:151], v[188:191], v[52:55]
	v_mfma_f32_16x16x32_bf16 v[48:51], v[156:159], v[188:191], v[48:51]
	v_mfma_f32_16x16x32_bf16 v[28:31], v[148:151], v[196:199], v[28:31]
	v_mfma_f32_16x16x32_bf16 v[24:27], v[156:159], v[196:199], v[24:27]
	v_mfma_f32_16x16x32_bf16 v[20:23], v[148:151], v[204:207], v[20:23]
	v_mfma_f32_16x16x32_bf16 v[16:19], v[156:159], v[204:207], v[16:19]
	v_mfma_f32_16x16x32_bf16 v[60:63], v[152:155], v[184:187], v[60:63]
	v_mfma_f32_16x16x32_bf16 v[56:59], v[160:163], v[184:187], v[56:59]
	v_mfma_f32_16x16x32_bf16 v[52:55], v[152:155], v[192:195], v[52:55]
	v_mfma_f32_16x16x32_bf16 v[48:51], v[160:163], v[192:195], v[48:51]
	v_mfma_f32_16x16x32_bf16 v[28:31], v[152:155], v[200:203], v[28:31]
	v_mfma_f32_16x16x32_bf16 v[24:27], v[160:163], v[200:203], v[24:27]
	v_mfma_f32_16x16x32_bf16 v[20:23], v[152:155], v[208:211], v[20:23]
	v_mfma_f32_16x16x32_bf16 v[16:19], v[160:163], v[208:211], v[16:19]
	s_setprio 0
	s_setprio 1
	v_mfma_f32_16x16x32_bf16 v[44:47], v[164:167], v[180:183], v[44:47]
	v_mfma_f32_16x16x32_bf16 v[40:43], v[172:175], v[180:183], v[40:43]
	v_mfma_f32_16x16x32_bf16 v[36:39], v[164:167], v[188:191], v[36:39]
	v_mfma_f32_16x16x32_bf16 v[32:35], v[172:175], v[188:191], v[32:35]
	v_mfma_f32_16x16x32_bf16 v[12:15], v[164:167], v[196:199], v[12:15]
	v_mfma_f32_16x16x32_bf16 v[8:11], v[172:175], v[196:199], v[8:11]
	v_mfma_f32_16x16x32_bf16 v[4:7], v[164:167], v[204:207], v[4:7]
	v_mfma_f32_16x16x32_bf16 v[0:3], v[172:175], v[204:207], v[0:3]
	v_mfma_f32_16x16x32_bf16 v[44:47], v[168:171], v[184:187], v[44:47]
	v_mfma_f32_16x16x32_bf16 v[40:43], v[176:179], v[184:187], v[40:43]
	v_mfma_f32_16x16x32_bf16 v[36:39], v[168:171], v[192:195], v[36:39]
	v_mfma_f32_16x16x32_bf16 v[32:35], v[176:179], v[192:195], v[32:35]
	v_mfma_f32_16x16x32_bf16 v[12:15], v[168:171], v[200:203], v[12:15]
	v_mfma_f32_16x16x32_bf16 v[8:11], v[176:179], v[200:203], v[8:11]
	v_mfma_f32_16x16x32_bf16 v[4:7], v[168:171], v[208:211], v[4:7]
	v_mfma_f32_16x16x32_bf16 v[0:3], v[176:179], v[208:211], v[0:3]
	s_setprio 0
	s_barrier
	s_add_i32 s56, s56, 2
	s_add_u32 s24, s24, 0x100
	s_addc_u32 s25, s25, 0
	s_add_u32 s2, s2, 0x100
	s_addc_u32 s55, s55, 0
	s_cmpk_gt_u32 s56, 0x55
	s_cbranch_scc0 .LBB0_1090
	s_and_b64 vcc, exec, s[14:15]
	s_cbranch_vccz .LBB0_1093
	s_barrier
